# v47 + code placement: the nine GEMM K-loop headers aligned to 64 bytes (.p2align 6)
# speedup vs baseline: 1.0052x; 1.0052x over previous
; #define PG8_STAGE(bufoff, gbase, voff) do { _Pragma("unroll") for (int _i = 0; _i < 2; ++_i) glds16_s((gbase), (voff)[_i], ldsb + (unsigned)((bufoff) + _i * 8192)); } while (0)
; #define PG8_LDA(dst, b, h) do { _Pragma("unroll") for (int m = 0; m < 4; ++m) _Pragma("unroll") for (int k = 0; k < 2; ++k) dst[m][k] = *(const LAS h16x8*)(lds + PG8_SA(b, h) + aoff + m * 2048 + k * 1024); } while (0)
; #define PG8_LDB(dst, b, h) do { _Pragma("unroll") for (int n = 0; n < 2; ++n) _Pragma("unroll") for (int k = 0; k < 2; ++k) dst[n][k] = *(const LAS h16x8*)(lds + PG8_SB(b, h) + boff + n * 2048 + k * 1024); } while (0)
; #define PG8_MMA(ai, bj, At, Bt) do { __builtin_amdgcn_s_setprio(1); _Pragma("unroll") for (int m = 0; m < 4; ++m) _Pragma("unroll") for (int n = 0; n < 2; ++n) _Pragma("unroll") for (int k = 0; k < 2; ++k) \
;         acc[ai][bj][m][n] = mma_step<I8>(Bt[n][k], At[m][k], acc[ai][bj][m][n]); __builtin_amdgcn_s_setprio(0); } while (0)
; #define PG8_WAIT_V(n) asm volatile("s_waitcnt vmcnt(" #n ")" ::: "memory")
; #define PG8_WAIT_L(n) asm volatile("s_waitcnt lgkmcnt(" #n ")" ::: "memory")
; #define PG8_BAR __builtin_amdgcn_s_barrier()
; #define PG8_SCHED __builtin_amdgcn_sched_barrier(0)
; template <class Prob, class Epi, bool I8 = false, bool ALIGN_EPI = true, bool SP2 = true>
; __device__ __forceinline__ void gemm_phase(LAS unsigned char* lds, int wave, const Prob& P, const Epi& E) {
;     ...
;             PG8_LDB(B0, 0, 0); PG8_LDB(B1, 0, 1); PG8_SCHED; PG8_LDA(At, 0, 0); PG8_STAGE(PG8_SA(1, 1), a1 + hstepA, voffA);
;             PG8_WAIT_V(8); PG8_WAIT_L(0); PG8_BAR; PG8_MMA(0, 0, At, B0); PG8_MMA(0, 1, At, B1); PG8_BAR; PG8_SCHED;
;             PG8_LDA(At, 0, 1); PG8_STAGE(PG8_SB(0, 0), b2, voffB); PG8_STAGE(PG8_SB(0, 1), b2 + hstepB, voffB); PG8_STAGE(PG8_SA(0, 0), a2, voffA);
;             PG8_WAIT_V(8); PG8_WAIT_L(0); PG8_BAR; PG8_MMA(1, 0, At, B0); PG8_MMA(1, 1, At, B1); PG8_BAR; PG8_SCHED;
.Lpeel_225:
	ds_read_b128 v[138:141], v132
	ds_read_b128 v[142:145], v132 offset:1024
	ds_read_b128 v[146:149], v132 offset:2048
	ds_read_b128 v[150:153], v132 offset:3072
	ds_read_b128 v[154:157], v133
	ds_read_b128 v[158:161], v133 offset:1024
	ds_read_b128 v[162:165], v133 offset:2048
	ds_read_b128 v[166:169], v133 offset:3072
	s_add_u32 s44, s42, 0x100
	s_addc_u32 s45, s43, 0
	s_cmp_eq_u32 s29, 4
	s_cselect_b32 s50, s87, s44
	s_cselect_b32 s51, s23, s45
	s_cselect_b32 s48, s1, s4
	s_cselect_b32 s49, s0, s5
	s_add_u32 s46, s50, 0x80
	s_addc_u32 s47, s51, 0
	ds_read_b128 v[170:173], v134
	ds_read_b128 v[174:177], v134 offset:1024
	ds_read_b128 v[178:181], v134 offset:2048
	ds_read_b128 v[182:185], v134 offset:3072
	ds_read_b128 v[186:189], v134 offset:4096
	ds_read_b128 v[190:193], v134 offset:5120
	ds_read_b128 v[194:197], v134 offset:6144
	ds_read_b128 v[198:201], v134 offset:7168
	s_add_u32 s42, s42, 0x20080
	s_addc_u32 s43, s43, 0
	s_mov_b32 s6, m0
	s_mov_b32 m0, s80
	s_nop 0
	global_load_lds_dwordx4 v128, s[42:43]
	s_mov_b32 m0, s6
	s_nop 0
	s_mov_b32 s6, m0
	s_mov_b32 m0, s81
	s_nop 0
	global_load_lds_dwordx4 v130, s[42:43]
	s_mov_b32 m0, s6
	s_waitcnt vmcnt(8)
	s_waitcnt lgkmcnt(0)
	s_barrier
	s_waitcnt lgkmcnt(7)
	v_mfma_f32_16x16x32_f16 v[124:127], v[138:141], v[170:173], 0
	v_mfma_f32_16x16x32_f16 v[120:123], v[146:149], v[170:173], 0
	s_waitcnt lgkmcnt(5)
	v_mfma_f32_16x16x32_f16 v[116:119], v[138:141], v[178:181], 0
	v_mfma_f32_16x16x32_f16 v[112:115], v[146:149], v[178:181], 0
	s_waitcnt lgkmcnt(3)
	v_mfma_f32_16x16x32_f16 v[100:103], v[138:141], v[186:189], 0
	v_mfma_f32_16x16x32_f16 v[96:99], v[146:149], v[186:189], 0
	s_waitcnt lgkmcnt(1)
	v_mfma_f32_16x16x32_f16 v[84:87], v[138:141], v[194:197], 0
	v_mfma_f32_16x16x32_f16 v[80:83], v[146:149], v[194:197], 0
	v_mfma_f32_16x16x32_f16 v[124:127], v[142:145], v[174:177], v[124:127]
	v_mfma_f32_16x16x32_f16 v[120:123], v[150:153], v[174:177], v[120:123]
	v_mfma_f32_16x16x32_f16 v[116:119], v[142:145], v[182:185], v[116:119]
	v_mfma_f32_16x16x32_f16 v[112:115], v[150:153], v[182:185], v[112:115]
	v_mfma_f32_16x16x32_f16 v[100:103], v[142:145], v[190:193], v[100:103]
	v_mfma_f32_16x16x32_f16 v[96:99], v[150:153], v[190:193], v[96:99]
	s_waitcnt lgkmcnt(0)
	v_mfma_f32_16x16x32_f16 v[84:87], v[142:145], v[198:201], v[84:87]
	v_mfma_f32_16x16x32_f16 v[80:83], v[150:153], v[198:201], v[80:83]
	v_mfma_f32_16x16x32_f16 v[108:111], v[154:157], v[170:173], 0
	v_mfma_f32_16x16x32_f16 v[104:107], v[162:165], v[170:173], 0
	v_mfma_f32_16x16x32_f16 v[92:95], v[154:157], v[178:181], 0
	v_mfma_f32_16x16x32_f16 v[88:91], v[162:165], v[178:181], 0
	v_mfma_f32_16x16x32_f16 v[76:79], v[154:157], v[186:189], 0
	v_mfma_f32_16x16x32_f16 v[72:75], v[162:165], v[186:189], 0
	v_mfma_f32_16x16x32_f16 v[68:71], v[154:157], v[194:197], 0
	v_mfma_f32_16x16x32_f16 v[64:67], v[162:165], v[194:197], 0
	v_mfma_f32_16x16x32_f16 v[108:111], v[158:161], v[174:177], v[108:111]
	v_mfma_f32_16x16x32_f16 v[104:107], v[166:169], v[174:177], v[104:107]
	v_mfma_f32_16x16x32_f16 v[92:95], v[158:161], v[182:185], v[92:95]
	v_mfma_f32_16x16x32_f16 v[88:91], v[166:169], v[182:185], v[88:91]
	v_mfma_f32_16x16x32_f16 v[76:79], v[158:161], v[190:193], v[76:79]
	v_mfma_f32_16x16x32_f16 v[72:75], v[166:169], v[190:193], v[72:75]
	v_mfma_f32_16x16x32_f16 v[68:71], v[158:161], v[198:201], v[68:71]
	v_mfma_f32_16x16x32_f16 v[64:67], v[166:169], v[198:201], v[64:67]
	s_barrier
	ds_read_b128 v[170:173], v134 offset:16384
	ds_read_b128 v[174:177], v134 offset:17408
	ds_read_b128 v[178:181], v134 offset:18432
	ds_read_b128 v[182:185], v134 offset:19456
	ds_read_b128 v[186:189], v134 offset:20480
	ds_read_b128 v[190:193], v134 offset:21504
	ds_read_b128 v[194:197], v134 offset:22528
	ds_read_b128 v[198:201], v134 offset:23552
	s_mov_b32 s6, m0
	s_mov_b32 m0, s57
	s_nop 0
	global_load_lds_dwordx4 v129, s[48:49]
	s_mov_b32 m0, s6
	s_add_u32 s42, s48, 0x80000
	s_mov_b32 s6, m0
	s_mov_b32 m0, s60
	s_nop 0
	global_load_lds_dwordx4 v131, s[48:49]
	s_mov_b32 m0, s6
	s_addc_u32 s43, s49, 0
	s_mov_b32 s6, m0
	s_mov_b32 m0, s61
	s_nop 0
	global_load_lds_dwordx4 v129, s[42:43]
	s_mov_b32 m0, s6
	s_nop 0
	s_mov_b32 s6, m0
	s_mov_b32 m0, s62
	s_nop 0
	global_load_lds_dwordx4 v131, s[42:43]
	s_mov_b32 m0, s6
	s_nop 0
	s_mov_b32 s6, m0
	s_mov_b32 m0, s56
	s_nop 0
	global_load_lds_dwordx4 v128, s[50:51]
	s_mov_b32 m0, s6
	s_nop 0
	s_mov_b32 s6, m0
	s_mov_b32 m0, s63
	s_nop 0
	global_load_lds_dwordx4 v130, s[50:51]
	s_mov_b32 m0, s6
	s_waitcnt vmcnt(8)
	s_waitcnt lgkmcnt(0)
	s_barrier
; #define PG8_STAGE(bufoff, gbase, voff) do { _Pragma("unroll") for (int _i = 0; _i < 2; ++_i) glds16_s((gbase), (voff)[_i], ldsb + (unsigned)((bufoff) + _i * 8192)); } while (0)
; #define PG8_LDA(dst, b, h) do { _Pragma("unroll") for (int m = 0; m < 4; ++m) _Pragma("unroll") for (int k = 0; k < 2; ++k) dst[m][k] = *(const LAS h16x8*)(lds + PG8_SA(b, h) + aoff + m * 2048 + k * 1024); } while (0)
; #define PG8_LDB(dst, b, h) do { _Pragma("unroll") for (int n = 0; n < 2; ++n) _Pragma("unroll") for (int k = 0; k < 2; ++k) dst[n][k] = *(const LAS h16x8*)(lds + PG8_SB(b, h) + boff + n * 2048 + k * 1024); } while (0)
; #define PG8_MMA(ai, bj, At, Bt) do { __builtin_amdgcn_s_setprio(1); _Pragma("unroll") for (int m = 0; m < 4; ++m) _Pragma("unroll") for (int n = 0; n < 2; ++n) _Pragma("unroll") for (int k = 0; k < 2; ++k) \
;         acc[ai][bj][m][n] = mma_step<I8>(Bt[n][k], At[m][k], acc[ai][bj][m][n]); __builtin_amdgcn_s_setprio(0); } while (0)
; #define PG8_WAIT_V(n) asm volatile("s_waitcnt vmcnt(" #n ")" ::: "memory")
; #define PG8_WAIT_L(n) asm volatile("s_waitcnt lgkmcnt(" #n ")" ::: "memory")
; #define PG8_BAR __builtin_amdgcn_s_barrier()
; template <class Prob, class Epi, bool I8 = false, bool ALIGN_EPI = true, bool SP2 = true>
; __device__ __forceinline__ void gemm_phase(LAS unsigned char* lds, int wave, const Prob& P, const Epi& E) {
;     ...
;             PG8_LDB(B0, 0, 0); PG8_LDB(B1, 0, 1); PG8_SCHED; PG8_LDA(At, 0, 0); PG8_STAGE(PG8_SA(1, 1), a1 + hstepA, voffA);
;             PG8_WAIT_V(8); PG8_WAIT_L(0); PG8_BAR; PG8_MMA(0, 0, At, B0); PG8_MMA(0, 1, At, B1); PG8_BAR; PG8_SCHED;
;             PG8_LDA(At, 0, 1); PG8_STAGE(PG8_SB(0, 0), b2, voffB); PG8_STAGE(PG8_SB(0, 1), b2 + hstepB, voffB); PG8_STAGE(PG8_SA(0, 0), a2, voffA);
;             PG8_WAIT_V(8); PG8_WAIT_L(0); PG8_BAR; PG8_MMA(1, 0, At, B0); PG8_MMA(1, 1, At, B1); PG8_BAR; PG8_SCHED;
;             PG8_LDB(B0, 1, 0); PG8_LDB(B1, 1, 1); PG8_SCHED; PG8_LDA(At, 1, 0); PG8_STAGE(PG8_SA(0, 1), a2 + hstepA, voffA);
;             PG8_WAIT_V(8); PG8_WAIT_L(0); PG8_BAR; PG8_MMA(0, 0, At, B0); PG8_MMA(0, 1, At, B1); PG8_BAR; PG8_SCHED;
;             PG8_LDA(At, 1, 1); PG8_STAGE(PG8_SB(1, 0), b3, voffB); PG8_STAGE(PG8_SB(1, 1), b3 + hstepB, voffB); PG8_STAGE(PG8_SA(1, 0), a3, voffA);
;             PG8_WAIT_V(8); PG8_WAIT_L(0); PG8_BAR; PG8_MMA(1, 0, At, B0); PG8_MMA(1, 1, At, B1); PG8_BAR; PG8_SCHED;
	s_waitcnt lgkmcnt(7)
	v_mfma_f32_16x16x32_f16 v[60:63], v[138:141], v[170:173], 0
	v_mfma_f32_16x16x32_f16 v[56:59], v[146:149], v[170:173], 0
	s_waitcnt lgkmcnt(5)
	v_mfma_f32_16x16x32_f16 v[52:55], v[138:141], v[178:181], 0
	v_mfma_f32_16x16x32_f16 v[48:51], v[146:149], v[178:181], 0
	s_waitcnt lgkmcnt(3)
	v_mfma_f32_16x16x32_f16 v[36:39], v[138:141], v[186:189], 0
	v_mfma_f32_16x16x32_f16 v[32:35], v[146:149], v[186:189], 0
	s_waitcnt lgkmcnt(1)
	v_mfma_f32_16x16x32_f16 v[20:23], v[138:141], v[194:197], 0
	v_mfma_f32_16x16x32_f16 v[16:19], v[146:149], v[194:197], 0
	v_mfma_f32_16x16x32_f16 v[60:63], v[142:145], v[174:177], v[60:63]
	v_mfma_f32_16x16x32_f16 v[56:59], v[150:153], v[174:177], v[56:59]
	v_mfma_f32_16x16x32_f16 v[52:55], v[142:145], v[182:185], v[52:55]
	v_mfma_f32_16x16x32_f16 v[48:51], v[150:153], v[182:185], v[48:51]
	v_mfma_f32_16x16x32_f16 v[36:39], v[142:145], v[190:193], v[36:39]
	v_mfma_f32_16x16x32_f16 v[32:35], v[150:153], v[190:193], v[32:35]
	s_waitcnt lgkmcnt(0)
	v_mfma_f32_16x16x32_f16 v[20:23], v[142:145], v[198:201], v[20:23]
	v_mfma_f32_16x16x32_f16 v[16:19], v[150:153], v[198:201], v[16:19]
	v_mfma_f32_16x16x32_f16 v[44:47], v[154:157], v[170:173], 0
	v_mfma_f32_16x16x32_f16 v[40:43], v[162:165], v[170:173], 0
	v_mfma_f32_16x16x32_f16 v[28:31], v[154:157], v[178:181], 0
	v_mfma_f32_16x16x32_f16 v[24:27], v[162:165], v[178:181], 0
	v_mfma_f32_16x16x32_f16 v[12:15], v[154:157], v[186:189], 0
	v_mfma_f32_16x16x32_f16 v[8:11], v[162:165], v[186:189], 0
	v_mfma_f32_16x16x32_f16 v[4:7], v[154:157], v[194:197], 0
	v_mfma_f32_16x16x32_f16 v[0:3], v[162:165], v[194:197], 0
	v_mfma_f32_16x16x32_f16 v[44:47], v[158:161], v[174:177], v[44:47]
	v_mfma_f32_16x16x32_f16 v[40:43], v[166:169], v[174:177], v[40:43]
	v_mfma_f32_16x16x32_f16 v[28:31], v[158:161], v[182:185], v[28:31]
	v_mfma_f32_16x16x32_f16 v[24:27], v[166:169], v[182:185], v[24:27]
	v_mfma_f32_16x16x32_f16 v[12:15], v[158:161], v[190:193], v[12:15]
	v_mfma_f32_16x16x32_f16 v[8:11], v[166:169], v[190:193], v[8:11]
	v_mfma_f32_16x16x32_f16 v[4:7], v[158:161], v[198:201], v[4:7]
	v_mfma_f32_16x16x32_f16 v[0:3], v[166:169], v[198:201], v[0:3]
	s_barrier
	ds_read_b128 v[138:141], v135
	ds_read_b128 v[142:145], v135 offset:1024
	ds_read_b128 v[146:149], v135 offset:2048
	ds_read_b128 v[150:153], v135 offset:3072
	ds_read_b128 v[154:157], v136
	ds_read_b128 v[158:161], v136 offset:1024
	ds_read_b128 v[162:165], v136 offset:2048
	ds_read_b128 v[166:169], v136 offset:3072
	ds_read_b128 v[170:173], v134 offset:32768
	ds_read_b128 v[174:177], v134 offset:33792
	ds_read_b128 v[178:181], v134 offset:34816
	ds_read_b128 v[182:185], v134 offset:35840
	ds_read_b128 v[186:189], v134 offset:36864
	ds_read_b128 v[190:193], v134 offset:37888
	ds_read_b128 v[194:197], v134 offset:38912
	ds_read_b128 v[198:201], v134 offset:39936
	s_add_u32 s42, s50, 0x20000
	s_addc_u32 s43, s51, 0
	s_mov_b32 s6, m0
	s_mov_b32 m0, s64
	s_nop 0
	global_load_lds_dwordx4 v128, s[42:43]
	s_mov_b32 m0, s6
	s_nop 0
	s_mov_b32 s6, m0
	s_mov_b32 m0, s68
	s_nop 0
	global_load_lds_dwordx4 v130, s[42:43]
	s_mov_b32 m0, s6
	s_waitcnt vmcnt(8)
	s_waitcnt lgkmcnt(0)
	s_barrier
	s_waitcnt lgkmcnt(7)
	v_mfma_f32_16x16x32_f16 v[124:127], v[138:141], v[170:173], v[124:127]
	v_mfma_f32_16x16x32_f16 v[120:123], v[146:149], v[170:173], v[120:123]
	s_waitcnt lgkmcnt(5)
	v_mfma_f32_16x16x32_f16 v[116:119], v[138:141], v[178:181], v[116:119]
	v_mfma_f32_16x16x32_f16 v[112:115], v[146:149], v[178:181], v[112:115]
	s_waitcnt lgkmcnt(3)
	v_mfma_f32_16x16x32_f16 v[100:103], v[138:141], v[186:189], v[100:103]
	v_mfma_f32_16x16x32_f16 v[96:99], v[146:149], v[186:189], v[96:99]
	s_waitcnt lgkmcnt(1)
	v_mfma_f32_16x16x32_f16 v[84:87], v[138:141], v[194:197], v[84:87]
	v_mfma_f32_16x16x32_f16 v[80:83], v[146:149], v[194:197], v[80:83]
	v_mfma_f32_16x16x32_f16 v[124:127], v[142:145], v[174:177], v[124:127]
	v_mfma_f32_16x16x32_f16 v[120:123], v[150:153], v[174:177], v[120:123]
	v_mfma_f32_16x16x32_f16 v[116:119], v[142:145], v[182:185], v[116:119]
	v_mfma_f32_16x16x32_f16 v[112:115], v[150:153], v[182:185], v[112:115]
	v_mfma_f32_16x16x32_f16 v[100:103], v[142:145], v[190:193], v[100:103]
	v_mfma_f32_16x16x32_f16 v[96:99], v[150:153], v[190:193], v[96:99]
	s_waitcnt lgkmcnt(0)
	v_mfma_f32_16x16x32_f16 v[84:87], v[142:145], v[198:201], v[84:87]
	v_mfma_f32_16x16x32_f16 v[80:83], v[150:153], v[198:201], v[80:83]
	v_mfma_f32_16x16x32_f16 v[108:111], v[154:157], v[170:173], v[108:111]
	v_mfma_f32_16x16x32_f16 v[104:107], v[162:165], v[170:173], v[104:107]
	v_mfma_f32_16x16x32_f16 v[92:95], v[154:157], v[178:181], v[92:95]
	v_mfma_f32_16x16x32_f16 v[88:91], v[162:165], v[178:181], v[88:91]
	v_mfma_f32_16x16x32_f16 v[76:79], v[154:157], v[186:189], v[76:79]
	v_mfma_f32_16x16x32_f16 v[72:75], v[162:165], v[186:189], v[72:75]
	v_mfma_f32_16x16x32_f16 v[68:71], v[154:157], v[194:197], v[68:71]
	v_mfma_f32_16x16x32_f16 v[64:67], v[162:165], v[194:197], v[64:67]
	v_mfma_f32_16x16x32_f16 v[108:111], v[158:161], v[174:177], v[108:111]
	v_mfma_f32_16x16x32_f16 v[104:107], v[166:169], v[174:177], v[104:107]
	v_mfma_f32_16x16x32_f16 v[92:95], v[158:161], v[182:185], v[92:95]
	v_mfma_f32_16x16x32_f16 v[88:91], v[166:169], v[182:185], v[88:91]
	v_mfma_f32_16x16x32_f16 v[76:79], v[158:161], v[190:193], v[76:79]
	v_mfma_f32_16x16x32_f16 v[72:75], v[166:169], v[190:193], v[72:75]
	v_mfma_f32_16x16x32_f16 v[68:71], v[158:161], v[198:201], v[68:71]
	v_mfma_f32_16x16x32_f16 v[64:67], v[166:169], v[198:201], v[64:67]
	s_barrier
; #define PG8_STAGE(bufoff, gbase, voff) do { _Pragma("unroll") for (int _i = 0; _i < 2; ++_i) glds16_s((gbase), (voff)[_i], ldsb + (unsigned)((bufoff) + _i * 8192)); } while (0)
; #define PG8_LDA(dst, b, h) do { _Pragma("unroll") for (int m = 0; m < 4; ++m) _Pragma("unroll") for (int k = 0; k < 2; ++k) dst[m][k] = *(const LAS h16x8*)(lds + PG8_SA(b, h) + aoff + m * 2048 + k * 1024); } while (0)
; #define PG8_MMA(ai, bj, At, Bt) do { __builtin_amdgcn_s_setprio(1); _Pragma("unroll") for (int m = 0; m < 4; ++m) _Pragma("unroll") for (int n = 0; n < 2; ++n) _Pragma("unroll") for (int k = 0; k < 2; ++k) \
;         acc[ai][bj][m][n] = mma_step<I8>(Bt[n][k], At[m][k], acc[ai][bj][m][n]); __builtin_amdgcn_s_setprio(0); } while (0)
; #define PG8_WAIT_V(n) asm volatile("s_waitcnt vmcnt(" #n ")" ::: "memory")
; #define PG8_WAIT_L(n) asm volatile("s_waitcnt lgkmcnt(" #n ")" ::: "memory")
; #define PG8_BAR __builtin_amdgcn_s_barrier()
; #define PG8_SCHED __builtin_amdgcn_sched_barrier(0)
; template <class Prob, class Epi, bool I8 = false, bool ALIGN_EPI = true, bool SP2 = true>
; __device__ __forceinline__ void gemm_phase(LAS unsigned char* lds, int wave, const Prob& P, const Epi& E) {
;     ...
;         for (int t = 0; t < nt; t += 2) {
;             const bool last = (t == nt - 2);
;             const char* a1 = cA + (size_t)(t + 1) * kstep;
;             const char* a2 = last ? nA : cA + (size_t)(t + 2) * kstep; const char* b2 = last ? nB : cB + (size_t)(t + 2) * kstep;
;             const char* a3 = a2 + kstep; const char* b3 = b2 + kstep;
;     ...
;             PG8_LDA(At, 1, 1); PG8_STAGE(PG8_SB(1, 0), b3, voffB); PG8_STAGE(PG8_SB(1, 1), b3 + hstepB, voffB); PG8_STAGE(PG8_SA(1, 0), a3, voffA);
;             PG8_WAIT_V(8); PG8_WAIT_L(0); PG8_BAR; PG8_MMA(1, 0, At, B0); PG8_MMA(1, 1, At, B1); PG8_BAR; PG8_SCHED;
	ds_read_b128 v[170:173], v134 offset:49152
	ds_read_b128 v[174:177], v134 offset:50176
	ds_read_b128 v[178:181], v134 offset:51200
	ds_read_b128 v[182:185], v134 offset:52224
	ds_read_b128 v[186:189], v134 offset:53248
	ds_read_b128 v[190:193], v134 offset:54272
	ds_read_b128 v[194:197], v134 offset:55296
	ds_read_b128 v[198:201], v134 offset:56320
	s_add_u32 s42, s48, 0x80
	s_addc_u32 s43, s49, 0
	s_mov_b32 s6, m0
	s_mov_b32 m0, s73
	s_nop 0
	global_load_lds_dwordx4 v129, s[42:43]
	s_mov_b32 m0, s6
	s_nop 0
	s_mov_b32 s6, m0
	s_mov_b32 m0, s74
	s_nop 0
	global_load_lds_dwordx4 v131, s[42:43]
	s_mov_b32 m0, s6
	s_add_u32 s42, s48, 0x80080
	s_addc_u32 s43, s49, 0
	s_mov_b32 s6, m0
	s_mov_b32 m0, s77
	s_nop 0
	global_load_lds_dwordx4 v129, s[42:43]
	s_mov_b32 m0, s6
	s_nop 0
	s_mov_b32 s6, m0
	s_mov_b32 m0, s79
	s_nop 0
	global_load_lds_dwordx4 v131, s[42:43]
	s_mov_b32 m0, s6
	s_nop 0
	s_mov_b32 s6, m0
	s_mov_b32 m0, s75
	s_nop 0
	global_load_lds_dwordx4 v128, s[46:47]
	s_mov_b32 m0, s6
	s_nop 0
	s_mov_b32 s6, m0
	s_mov_b32 m0, s76
	s_nop 0
	global_load_lds_dwordx4 v130, s[46:47]
	s_mov_b32 m0, s6
	s_waitcnt vmcnt(8)
	s_waitcnt lgkmcnt(0)
	s_barrier
	s_waitcnt lgkmcnt(7)
	v_mfma_f32_16x16x32_f16 v[60:63], v[138:141], v[170:173], v[60:63]
	v_mfma_f32_16x16x32_f16 v[56:59], v[146:149], v[170:173], v[56:59]
	s_waitcnt lgkmcnt(5)
	v_mfma_f32_16x16x32_f16 v[52:55], v[138:141], v[178:181], v[52:55]
	v_mfma_f32_16x16x32_f16 v[48:51], v[146:149], v[178:181], v[48:51]
	s_waitcnt lgkmcnt(3)
	v_mfma_f32_16x16x32_f16 v[36:39], v[138:141], v[186:189], v[36:39]
	v_mfma_f32_16x16x32_f16 v[32:35], v[146:149], v[186:189], v[32:35]
	s_waitcnt lgkmcnt(1)
	v_mfma_f32_16x16x32_f16 v[20:23], v[138:141], v[194:197], v[20:23]
	v_mfma_f32_16x16x32_f16 v[16:19], v[146:149], v[194:197], v[16:19]
	v_mfma_f32_16x16x32_f16 v[60:63], v[142:145], v[174:177], v[60:63]
	v_mfma_f32_16x16x32_f16 v[56:59], v[150:153], v[174:177], v[56:59]
	v_mfma_f32_16x16x32_f16 v[52:55], v[142:145], v[182:185], v[52:55]
	v_mfma_f32_16x16x32_f16 v[48:51], v[150:153], v[182:185], v[48:51]
	v_mfma_f32_16x16x32_f16 v[36:39], v[142:145], v[190:193], v[36:39]
	v_mfma_f32_16x16x32_f16 v[32:35], v[150:153], v[190:193], v[32:35]
	s_waitcnt lgkmcnt(0)
	v_mfma_f32_16x16x32_f16 v[20:23], v[142:145], v[198:201], v[20:23]
	v_mfma_f32_16x16x32_f16 v[16:19], v[150:153], v[198:201], v[16:19]
	v_mfma_f32_16x16x32_f16 v[44:47], v[154:157], v[170:173], v[44:47]
	v_mfma_f32_16x16x32_f16 v[40:43], v[162:165], v[170:173], v[40:43]
	v_mfma_f32_16x16x32_f16 v[28:31], v[154:157], v[178:181], v[28:31]
	v_mfma_f32_16x16x32_f16 v[24:27], v[162:165], v[178:181], v[24:27]
	v_mfma_f32_16x16x32_f16 v[12:15], v[154:157], v[186:189], v[12:15]
	v_mfma_f32_16x16x32_f16 v[8:11], v[162:165], v[186:189], v[8:11]
	v_mfma_f32_16x16x32_f16 v[4:7], v[154:157], v[194:197], v[4:7]
	v_mfma_f32_16x16x32_f16 v[0:3], v[162:165], v[194:197], v[0:3]
	v_mfma_f32_16x16x32_f16 v[44:47], v[158:161], v[174:177], v[44:47]
	v_mfma_f32_16x16x32_f16 v[40:43], v[166:169], v[174:177], v[40:43]
	v_mfma_f32_16x16x32_f16 v[28:31], v[158:161], v[182:185], v[28:31]
	v_mfma_f32_16x16x32_f16 v[24:27], v[166:169], v[182:185], v[24:27]
	v_mfma_f32_16x16x32_f16 v[12:15], v[158:161], v[190:193], v[12:15]
	v_mfma_f32_16x16x32_f16 v[8:11], v[166:169], v[190:193], v[8:11]
	v_mfma_f32_16x16x32_f16 v[4:7], v[158:161], v[198:201], v[4:7]
	v_mfma_f32_16x16x32_f16 v[0:3], v[166:169], v[198:201], v[0:3]
	s_barrier
	s_add_i32 s29, s29, 2
	s_add_u32 s4, s4, 0x100
	s_addc_u32 s5, s5, 0
	s_cmp_gt_u32 s29, 5
	s_mov_b64 s[42:43], s[44:45]
	.p2align 6

;     __device__ bool next(int i, Unit& u) const { return S.next(i, u); }
;     __device__ bool next(int i, Unit& u) const { const int L = i * G + c; if (L >= 3 * 44) return false; u.pm = L % 3; u.pn = L / 3; u.g = 0; u.part = 0; u.keep = 0; return true; }
; template <class Prob, class Epi, bool I8 = false, bool ALIGN_EPI = true, bool SP2 = true>
; __device__ __forceinline__ void gemm_phase(LAS unsigned char* lds, int wave, const Prob& P, const Epi& E) {
;     ...
;         const bool has_next = P.next(ui + 1, nxt);
;         const char* nA = has_next ? P.a_tile(nxt) : cA; const char* nB = has_next ? P.b_tile(nxt) : cB;
;         for (int t = 0; t < nt; t += 2) {
;             const bool last = (t == nt - 2);
;             const char* a1 = cA + (size_t)(t + 1) * kstep;
;             const char* a2 = last ? nA : cA + (size_t)(t + 2) * kstep; const char* b2 = last ? nB : cB + (size_t)(t + 2) * kstep;
;             const char* a3 = a2 + kstep; const char* b3 = b2 + kstep;
.LBB0_296:
	s_ashr_i32 s23, s22, 31
	s_lshl_b64 s[0:1], s[22:23], 21
	s_add_u32 s0, s46, s0
	s_addc_u32 s1, s47, s1
	s_add_u32 s50, s0, s44
	s_addc_u32 s51, s1, s45
	s_and_b64 s[0:1], s[40:41], exec
	s_cselect_b32 s0, s51, s15
	s_cselect_b32 s1, s50, s14
	s_add_u32 s17, s38, 0x100
	s_addc_u32 s4, s39, 0
	s_mov_b32 s5, -2
	.p2align 6

; #define PG8_STAGE(bufoff, gbase, voff) do { _Pragma("unroll") for (int _i = 0; _i < 2; ++_i) glds16_s((gbase), (voff)[_i], ldsb + (unsigned)((bufoff) + _i * 8192)); } while (0)
; #define PG8_LDA(dst, b, h) do { _Pragma("unroll") for (int m = 0; m < 4; ++m) _Pragma("unroll") for (int k = 0; k < 2; ++k) dst[m][k] = *(const LAS h16x8*)(lds + PG8_SA(b, h) + aoff + m * 2048 + k * 1024); } while (0)
; #define PG8_LDB(dst, b, h) do { _Pragma("unroll") for (int n = 0; n < 2; ++n) _Pragma("unroll") for (int k = 0; k < 2; ++k) dst[n][k] = *(const LAS h16x8*)(lds + PG8_SB(b, h) + boff + n * 2048 + k * 1024); } while (0)
; #define PG8_MMA(ai, bj, At, Bt) do { __builtin_amdgcn_s_setprio(1); _Pragma("unroll") for (int m = 0; m < 4; ++m) _Pragma("unroll") for (int n = 0; n < 2; ++n) _Pragma("unroll") for (int k = 0; k < 2; ++k) \
;         acc[ai][bj][m][n] = mma_step<I8>(Bt[n][k], At[m][k], acc[ai][bj][m][n]); __builtin_amdgcn_s_setprio(0); } while (0)
; #define PG8_WAIT_V(n) asm volatile("s_waitcnt vmcnt(" #n ")" ::: "memory")
; #define PG8_WAIT_L(n) asm volatile("s_waitcnt lgkmcnt(" #n ")" ::: "memory")
; #define PG8_BAR __builtin_amdgcn_s_barrier()
; #define PG8_SCHED __builtin_amdgcn_sched_barrier(0)
; template <class Prob, class Epi, bool I8 = false, bool ALIGN_EPI = true, bool SP2 = true>
; __device__ __forceinline__ void gemm_phase(LAS unsigned char* lds, int wave, const Prob& P, const Epi& E) {
;     ...
;             PG8_LDB(B0, 0, 0); PG8_LDB(B1, 0, 1); PG8_SCHED; PG8_LDA(At, 0, 0); PG8_STAGE(PG8_SA(1, 1), a1 + hstepA, voffA);
;             PG8_WAIT_V(8); PG8_WAIT_L(0); PG8_BAR; PG8_MMA(0, 0, At, B0); PG8_MMA(0, 1, At, B1); PG8_BAR; PG8_SCHED;
;             PG8_LDA(At, 0, 1); PG8_STAGE(PG8_SB(0, 0), b2, voffB); PG8_STAGE(PG8_SB(0, 1), b2 + hstepB, voffB); PG8_STAGE(PG8_SA(0, 0), a2, voffA);
;             PG8_WAIT_V(8); PG8_WAIT_L(0); PG8_BAR; PG8_MMA(1, 0, At, B0); PG8_MMA(1, 1, At, B1); PG8_BAR; PG8_SCHED;
.Lpeel_464:
	v_add_u32_e32 v140, 0x10000, v146
	ds_read_b128 v[128:131], v140
	ds_read_b128 v[132:135], v140 offset:1024
	ds_read_b128 v[136:139], v140 offset:2048
	ds_read_b128 v[148:151], v140 offset:3072
	v_add_u32_e32 v140, 0x14000, v146
	ds_read_b128 v[152:155], v140
	ds_read_b128 v[156:159], v140 offset:1024
	ds_read_b128 v[160:163], v140 offset:2048
	ds_read_b128 v[164:167], v140 offset:3072
	s_cmp_eq_u32 s1, 28
	s_cselect_b32 s48, s83, s85
	s_cselect_b32 s49, s27, s86
	s_cselect_b32 s46, s84, s87
	s_cselect_b32 s47, s23, s0
	s_add_u32 s44, s48, 0x80
	s_addc_u32 s45, s49, 0
	ds_read_b128 v[168:171], v147
	ds_read_b128 v[172:175], v147 offset:1024
	ds_read_b128 v[176:179], v147 offset:2048
	ds_read_b128 v[180:183], v147 offset:3072
	ds_read_b128 v[184:187], v147 offset:4096
	ds_read_b128 v[188:191], v147 offset:5120
	ds_read_b128 v[192:195], v147 offset:6144
	ds_read_b128 v[196:199], v147 offset:7168
	s_mov_b32 s4, m0
	s_mov_b32 m0, s77
	s_nop 0
	global_load_lds_dwordx4 v142, s[40:41]
	s_mov_b32 m0, s4
	s_nop 0
	s_mov_b32 s4, m0
	s_mov_b32 m0, s79
	s_nop 0
	global_load_lds_dwordx4 v144, s[40:41]
	s_mov_b32 m0, s4
	s_waitcnt vmcnt(8)
	s_waitcnt lgkmcnt(0)
	s_barrier
	s_waitcnt lgkmcnt(7)
	v_mfma_f32_16x16x32_f16 v[124:127], v[128:131], v[168:171], 0
	v_mfma_f32_16x16x32_f16 v[120:123], v[136:139], v[168:171], 0
	s_waitcnt lgkmcnt(5)
	v_mfma_f32_16x16x32_f16 v[116:119], v[128:131], v[176:179], 0
	v_mfma_f32_16x16x32_f16 v[112:115], v[136:139], v[176:179], 0
	s_waitcnt lgkmcnt(3)
	v_mfma_f32_16x16x32_f16 v[108:111], v[128:131], v[184:187], 0
	v_mfma_f32_16x16x32_f16 v[104:107], v[136:139], v[184:187], 0
	s_waitcnt lgkmcnt(1)
	v_mfma_f32_16x16x32_f16 v[100:103], v[128:131], v[192:195], 0
	v_mfma_f32_16x16x32_f16 v[96:99], v[136:139], v[192:195], 0
	v_mfma_f32_16x16x32_f16 v[124:127], v[132:135], v[172:175], v[124:127]
	v_mfma_f32_16x16x32_f16 v[120:123], v[148:151], v[172:175], v[120:123]
	v_mfma_f32_16x16x32_f16 v[116:119], v[132:135], v[180:183], v[116:119]
	v_mfma_f32_16x16x32_f16 v[112:115], v[148:151], v[180:183], v[112:115]
	v_mfma_f32_16x16x32_f16 v[108:111], v[132:135], v[188:191], v[108:111]
	v_mfma_f32_16x16x32_f16 v[104:107], v[148:151], v[188:191], v[104:107]
	s_waitcnt lgkmcnt(0)
	v_mfma_f32_16x16x32_f16 v[100:103], v[132:135], v[196:199], v[100:103]
	v_mfma_f32_16x16x32_f16 v[96:99], v[148:151], v[196:199], v[96:99]
	v_mfma_f32_16x16x32_f16 v[64:67], v[152:155], v[168:171], 0
	v_mfma_f32_16x16x32_f16 v[56:59], v[160:163], v[168:171], 0
	v_mfma_f32_16x16x32_f16 v[52:55], v[152:155], v[176:179], 0
	v_mfma_f32_16x16x32_f16 v[48:51], v[160:163], v[176:179], 0
	v_mfma_f32_16x16x32_f16 v[44:47], v[152:155], v[184:187], 0
	v_mfma_f32_16x16x32_f16 v[40:43], v[160:163], v[184:187], 0
	v_mfma_f32_16x16x32_f16 v[36:39], v[152:155], v[192:195], 0
	v_mfma_f32_16x16x32_f16 v[32:35], v[160:163], v[192:195], 0
	v_mfma_f32_16x16x32_f16 v[64:67], v[156:159], v[172:175], v[64:67]
	v_mfma_f32_16x16x32_f16 v[56:59], v[164:167], v[172:175], v[56:59]
	v_mfma_f32_16x16x32_f16 v[52:55], v[156:159], v[180:183], v[52:55]
	v_mfma_f32_16x16x32_f16 v[48:51], v[164:167], v[180:183], v[48:51]
	v_mfma_f32_16x16x32_f16 v[44:47], v[156:159], v[188:191], v[44:47]
	v_mfma_f32_16x16x32_f16 v[40:43], v[164:167], v[188:191], v[40:43]
	v_mfma_f32_16x16x32_f16 v[36:39], v[156:159], v[196:199], v[36:39]
	v_mfma_f32_16x16x32_f16 v[32:35], v[164:167], v[196:199], v[32:35]
	s_barrier
	ds_read_b128 v[168:171], v147 offset:16384
	ds_read_b128 v[172:175], v147 offset:17408
	ds_read_b128 v[176:179], v147 offset:18432
	ds_read_b128 v[180:183], v147 offset:19456
	ds_read_b128 v[184:187], v147 offset:20480
	ds_read_b128 v[188:191], v147 offset:21504
	ds_read_b128 v[192:195], v147 offset:22528
	ds_read_b128 v[196:199], v147 offset:23552
	s_mov_b32 s4, m0
	s_mov_b32 m0, s51
	s_nop 0
	global_load_lds_dwordx4 v143, s[46:47]
	s_mov_b32 m0, s4
	s_nop 0
	s_mov_b32 s4, m0
	s_mov_b32 m0, s56
	s_nop 0
	global_load_lds_dwordx4 v145, s[46:47]
	s_mov_b32 m0, s4
	s_add_u32 s4, s46, 0x80000
	s_addc_u32 s5, s47, 0
	s_mov_b32 s6, m0
	s_mov_b32 m0, s57
	s_nop 0
	global_load_lds_dwordx4 v143, s[4:5]
	s_mov_b32 m0, s6
	s_nop 0
	s_mov_b32 s6, m0
	s_mov_b32 m0, s60
	s_nop 0
	global_load_lds_dwordx4 v145, s[4:5]
	s_mov_b32 m0, s6
	s_mov_b32 s4, m0
	s_mov_b32 m0, s50
	s_nop 0
	global_load_lds_dwordx4 v142, s[48:49]
	s_mov_b32 m0, s4
	s_nop 0
	s_mov_b32 s4, m0
	s_mov_b32 m0, s61
	s_nop 0
	global_load_lds_dwordx4 v144, s[48:49]
	s_mov_b32 m0, s4
	s_waitcnt vmcnt(8)
	s_waitcnt lgkmcnt(0)
	s_barrier
	s_waitcnt lgkmcnt(7)
	v_mfma_f32_16x16x32_f16 v[92:95], v[128:131], v[168:171], 0
	v_mfma_f32_16x16x32_f16 v[88:91], v[136:139], v[168:171], 0
	s_waitcnt lgkmcnt(5)
	v_mfma_f32_16x16x32_f16 v[84:87], v[128:131], v[176:179], 0
	v_mfma_f32_16x16x32_f16 v[80:83], v[136:139], v[176:179], 0
	s_waitcnt lgkmcnt(3)
	v_mfma_f32_16x16x32_f16 v[76:79], v[128:131], v[184:187], 0
	v_mfma_f32_16x16x32_f16 v[72:75], v[136:139], v[184:187], 0
	s_waitcnt lgkmcnt(1)
	v_mfma_f32_16x16x32_f16 v[68:71], v[128:131], v[192:195], 0
	v_mfma_f32_16x16x32_f16 v[60:63], v[136:139], v[192:195], 0
	v_mfma_f32_16x16x32_f16 v[92:95], v[132:135], v[172:175], v[92:95]
	v_mfma_f32_16x16x32_f16 v[88:91], v[148:151], v[172:175], v[88:91]
	v_mfma_f32_16x16x32_f16 v[84:87], v[132:135], v[180:183], v[84:87]
	v_mfma_f32_16x16x32_f16 v[80:83], v[148:151], v[180:183], v[80:83]
	v_mfma_f32_16x16x32_f16 v[76:79], v[132:135], v[188:191], v[76:79]
	v_mfma_f32_16x16x32_f16 v[72:75], v[148:151], v[188:191], v[72:75]
	s_waitcnt lgkmcnt(0)
	v_mfma_f32_16x16x32_f16 v[68:71], v[132:135], v[196:199], v[68:71]
	v_mfma_f32_16x16x32_f16 v[60:63], v[148:151], v[196:199], v[60:63]
	v_mfma_f32_16x16x32_f16 v[28:31], v[152:155], v[168:171], 0
	v_mfma_f32_16x16x32_f16 v[24:27], v[160:163], v[168:171], 0
	v_mfma_f32_16x16x32_f16 v[20:23], v[152:155], v[176:179], 0
	v_mfma_f32_16x16x32_f16 v[16:19], v[160:163], v[176:179], 0
	v_mfma_f32_16x16x32_f16 v[12:15], v[152:155], v[184:187], 0
	v_mfma_f32_16x16x32_f16 v[8:11], v[160:163], v[184:187], 0
	v_mfma_f32_16x16x32_f16 v[4:7], v[152:155], v[192:195], 0
	v_mfma_f32_16x16x32_f16 v[0:3], v[160:163], v[192:195], 0
	v_mfma_f32_16x16x32_f16 v[28:31], v[156:159], v[172:175], v[28:31]
	v_mfma_f32_16x16x32_f16 v[24:27], v[164:167], v[172:175], v[24:27]
	v_mfma_f32_16x16x32_f16 v[20:23], v[156:159], v[180:183], v[20:23]
	v_mfma_f32_16x16x32_f16 v[16:19], v[164:167], v[180:183], v[16:19]
	v_mfma_f32_16x16x32_f16 v[12:15], v[156:159], v[188:191], v[12:15]
	v_mfma_f32_16x16x32_f16 v[8:11], v[164:167], v[188:191], v[8:11]
	v_mfma_f32_16x16x32_f16 v[4:7], v[156:159], v[196:199], v[4:7]
	v_mfma_f32_16x16x32_f16 v[0:3], v[164:167], v[196:199], v[0:3]
	s_barrier
; #define PG8_STAGE(bufoff, gbase, voff) do { _Pragma("unroll") for (int _i = 0; _i < 2; ++_i) glds16_s((gbase), (voff)[_i], ldsb + (unsigned)((bufoff) + _i * 8192)); } while (0)
; #define PG8_LDA(dst, b, h) do { _Pragma("unroll") for (int m = 0; m < 4; ++m) _Pragma("unroll") for (int k = 0; k < 2; ++k) dst[m][k] = *(const LAS h16x8*)(lds + PG8_SA(b, h) + aoff + m * 2048 + k * 1024); } while (0)
; #define PG8_LDB(dst, b, h) do { _Pragma("unroll") for (int n = 0; n < 2; ++n) _Pragma("unroll") for (int k = 0; k < 2; ++k) dst[n][k] = *(const LAS h16x8*)(lds + PG8_SB(b, h) + boff + n * 2048 + k * 1024); } while (0)
; #define PG8_MMA(ai, bj, At, Bt) do { __builtin_amdgcn_s_setprio(1); _Pragma("unroll") for (int m = 0; m < 4; ++m) _Pragma("unroll") for (int n = 0; n < 2; ++n) _Pragma("unroll") for (int k = 0; k < 2; ++k) \
;         acc[ai][bj][m][n] = mma_step<I8>(Bt[n][k], At[m][k], acc[ai][bj][m][n]); __builtin_amdgcn_s_setprio(0); } while (0)
; #define PG8_WAIT_V(n) asm volatile("s_waitcnt vmcnt(" #n ")" ::: "memory")
; #define PG8_WAIT_L(n) asm volatile("s_waitcnt lgkmcnt(" #n ")" ::: "memory")
; #define PG8_BAR __builtin_amdgcn_s_barrier()
; #define PG8_SCHED __builtin_amdgcn_sched_barrier(0)
; template <class Prob, class Epi, bool I8 = false, bool ALIGN_EPI = true, bool SP2 = true>
; __device__ __forceinline__ void gemm_phase(LAS unsigned char* lds, int wave, const Prob& P, const Epi& E) {
;     ...
;         for (int t = 0; t < nt; t += 2) {
;             const bool last = (t == nt - 2);
;             const char* a1 = cA + (size_t)(t + 1) * kstep;
;             const char* a2 = last ? nA : cA + (size_t)(t + 2) * kstep; const char* b2 = last ? nB : cB + (size_t)(t + 2) * kstep;
;             const char* a3 = a2 + kstep; const char* b3 = b2 + kstep;
;     ...
;             PG8_LDB(B0, 1, 0); PG8_LDB(B1, 1, 1); PG8_SCHED; PG8_LDA(At, 1, 0); PG8_STAGE(PG8_SA(0, 1), a2 + hstepA, voffA);
;             PG8_WAIT_V(8); PG8_WAIT_L(0); PG8_BAR; PG8_MMA(0, 0, At, B0); PG8_MMA(0, 1, At, B1); PG8_BAR; PG8_SCHED;
;             PG8_LDA(At, 1, 1); PG8_STAGE(PG8_SB(1, 0), b3, voffB); PG8_STAGE(PG8_SB(1, 1), b3 + hstepB, voffB); PG8_STAGE(PG8_SA(1, 0), a3, voffA);
;             PG8_WAIT_V(8); PG8_WAIT_L(0); PG8_BAR; PG8_MMA(1, 0, At, B0); PG8_MMA(1, 1, At, B1); PG8_BAR; PG8_SCHED;
	v_add_u32_e32 v140, 0x18000, v146
	ds_read_b128 v[128:131], v140
	ds_read_b128 v[132:135], v140 offset:1024
	ds_read_b128 v[136:139], v140 offset:2048
	ds_read_b128 v[148:151], v140 offset:3072
	v_add_u32_e32 v140, 0x1c000, v146
	ds_read_b128 v[152:155], v140
	ds_read_b128 v[156:159], v140 offset:1024
	ds_read_b128 v[160:163], v140 offset:2048
	ds_read_b128 v[164:167], v140 offset:3072
	ds_read_b128 v[168:171], v147 offset:32768
	ds_read_b128 v[172:175], v147 offset:33792
	ds_read_b128 v[176:179], v147 offset:34816
	ds_read_b128 v[180:183], v147 offset:35840
	ds_read_b128 v[184:187], v147 offset:36864
	ds_read_b128 v[188:191], v147 offset:37888
	ds_read_b128 v[192:195], v147 offset:38912
	ds_read_b128 v[196:199], v147 offset:39936
	s_add_u32 s4, s48, 0x80000
	s_addc_u32 s5, s49, 0
	s_mov_b32 s6, m0
	s_mov_b32 m0, s62
	s_nop 0
	global_load_lds_dwordx4 v142, s[4:5]
	s_mov_b32 m0, s6
	s_nop 0
	s_mov_b32 s6, m0
	s_mov_b32 m0, s63
	s_nop 0
	global_load_lds_dwordx4 v144, s[4:5]
	s_mov_b32 m0, s6
	s_waitcnt vmcnt(8)
	s_waitcnt lgkmcnt(0)
	s_barrier
	s_waitcnt lgkmcnt(7)
	v_mfma_f32_16x16x32_f16 v[124:127], v[128:131], v[168:171], v[124:127]
	v_mfma_f32_16x16x32_f16 v[120:123], v[136:139], v[168:171], v[120:123]
	s_waitcnt lgkmcnt(5)
	v_mfma_f32_16x16x32_f16 v[116:119], v[128:131], v[176:179], v[116:119]
	v_mfma_f32_16x16x32_f16 v[112:115], v[136:139], v[176:179], v[112:115]
	s_waitcnt lgkmcnt(3)
	v_mfma_f32_16x16x32_f16 v[108:111], v[128:131], v[184:187], v[108:111]
	v_mfma_f32_16x16x32_f16 v[104:107], v[136:139], v[184:187], v[104:107]
	s_waitcnt lgkmcnt(1)
	v_mfma_f32_16x16x32_f16 v[100:103], v[128:131], v[192:195], v[100:103]
	v_mfma_f32_16x16x32_f16 v[96:99], v[136:139], v[192:195], v[96:99]
	v_mfma_f32_16x16x32_f16 v[124:127], v[132:135], v[172:175], v[124:127]
	v_mfma_f32_16x16x32_f16 v[120:123], v[148:151], v[172:175], v[120:123]
	v_mfma_f32_16x16x32_f16 v[116:119], v[132:135], v[180:183], v[116:119]
	v_mfma_f32_16x16x32_f16 v[112:115], v[148:151], v[180:183], v[112:115]
	v_mfma_f32_16x16x32_f16 v[108:111], v[132:135], v[188:191], v[108:111]
	v_mfma_f32_16x16x32_f16 v[104:107], v[148:151], v[188:191], v[104:107]
	s_waitcnt lgkmcnt(0)
	v_mfma_f32_16x16x32_f16 v[100:103], v[132:135], v[196:199], v[100:103]
	v_mfma_f32_16x16x32_f16 v[96:99], v[148:151], v[196:199], v[96:99]
	v_mfma_f32_16x16x32_f16 v[64:67], v[152:155], v[168:171], v[64:67]
	v_mfma_f32_16x16x32_f16 v[56:59], v[160:163], v[168:171], v[56:59]
	v_mfma_f32_16x16x32_f16 v[52:55], v[152:155], v[176:179], v[52:55]
	v_mfma_f32_16x16x32_f16 v[48:51], v[160:163], v[176:179], v[48:51]
	v_mfma_f32_16x16x32_f16 v[44:47], v[152:155], v[184:187], v[44:47]
	v_mfma_f32_16x16x32_f16 v[40:43], v[160:163], v[184:187], v[40:43]
	v_mfma_f32_16x16x32_f16 v[36:39], v[152:155], v[192:195], v[36:39]
	v_mfma_f32_16x16x32_f16 v[32:35], v[160:163], v[192:195], v[32:35]
	v_mfma_f32_16x16x32_f16 v[64:67], v[156:159], v[172:175], v[64:67]
	v_mfma_f32_16x16x32_f16 v[56:59], v[164:167], v[172:175], v[56:59]
	v_mfma_f32_16x16x32_f16 v[52:55], v[156:159], v[180:183], v[52:55]
	v_mfma_f32_16x16x32_f16 v[48:51], v[164:167], v[180:183], v[48:51]
	v_mfma_f32_16x16x32_f16 v[44:47], v[156:159], v[188:191], v[44:47]
	v_mfma_f32_16x16x32_f16 v[40:43], v[164:167], v[188:191], v[40:43]
	v_mfma_f32_16x16x32_f16 v[36:39], v[156:159], v[196:199], v[36:39]
	v_mfma_f32_16x16x32_f16 v[32:35], v[164:167], v[196:199], v[32:35]
	s_barrier
	ds_read_b128 v[168:171], v147 offset:49152
	ds_read_b128 v[172:175], v147 offset:50176
	ds_read_b128 v[176:179], v147 offset:51200
	ds_read_b128 v[180:183], v147 offset:52224
	ds_read_b128 v[184:187], v147 offset:53248
	ds_read_b128 v[188:191], v147 offset:54272
	ds_read_b128 v[192:195], v147 offset:55296
	ds_read_b128 v[196:199], v147 offset:56320
	s_add_u32 s4, s46, 0x80
	s_addc_u32 s5, s47, 0
	s_mov_b32 s6, m0
	s_mov_b32 m0, s69
	s_nop 0
	global_load_lds_dwordx4 v143, s[4:5]
	s_mov_b32 m0, s6
	s_nop 0
	s_mov_b32 s6, m0
	s_mov_b32 m0, s72
	s_nop 0
	global_load_lds_dwordx4 v145, s[4:5]
	s_mov_b32 m0, s6
	s_add_u32 s4, s46, 0x80080
	s_addc_u32 s5, s47, 0
	s_mov_b32 s6, m0
	s_mov_b32 m0, s75
	s_nop 0
	global_load_lds_dwordx4 v143, s[4:5]
	s_mov_b32 m0, s6
	s_nop 0
	s_mov_b32 s6, m0
	s_mov_b32 m0, s76
	s_nop 0
	global_load_lds_dwordx4 v145, s[4:5]
	s_mov_b32 m0, s6
	s_mov_b32 s4, m0
	s_mov_b32 m0, s73
	s_nop 0
	global_load_lds_dwordx4 v142, s[44:45]
	s_mov_b32 m0, s4
	s_nop 0
	s_mov_b32 s4, m0
	s_mov_b32 m0, s74
	s_nop 0
	global_load_lds_dwordx4 v144, s[44:45]
	s_mov_b32 m0, s4
	s_waitcnt vmcnt(8)
	s_waitcnt lgkmcnt(0)
	s_barrier
	s_waitcnt lgkmcnt(7)
	v_mfma_f32_16x16x32_f16 v[92:95], v[128:131], v[168:171], v[92:95]
	v_mfma_f32_16x16x32_f16 v[88:91], v[136:139], v[168:171], v[88:91]
	s_waitcnt lgkmcnt(5)
	v_mfma_f32_16x16x32_f16 v[84:87], v[128:131], v[176:179], v[84:87]
	v_mfma_f32_16x16x32_f16 v[80:83], v[136:139], v[176:179], v[80:83]
	s_waitcnt lgkmcnt(3)
	v_mfma_f32_16x16x32_f16 v[76:79], v[128:131], v[184:187], v[76:79]
	v_mfma_f32_16x16x32_f16 v[72:75], v[136:139], v[184:187], v[72:75]
	s_waitcnt lgkmcnt(1)
	v_mfma_f32_16x16x32_f16 v[68:71], v[128:131], v[192:195], v[68:71]
	v_mfma_f32_16x16x32_f16 v[60:63], v[136:139], v[192:195], v[60:63]
	v_mfma_f32_16x16x32_f16 v[92:95], v[132:135], v[172:175], v[92:95]
	v_mfma_f32_16x16x32_f16 v[88:91], v[148:151], v[172:175], v[88:91]
	v_mfma_f32_16x16x32_f16 v[84:87], v[132:135], v[180:183], v[84:87]
	v_mfma_f32_16x16x32_f16 v[80:83], v[148:151], v[180:183], v[80:83]
	v_mfma_f32_16x16x32_f16 v[76:79], v[132:135], v[188:191], v[76:79]
	v_mfma_f32_16x16x32_f16 v[72:75], v[148:151], v[188:191], v[72:75]
	s_waitcnt lgkmcnt(0)
	v_mfma_f32_16x16x32_f16 v[68:71], v[132:135], v[196:199], v[68:71]
	v_mfma_f32_16x16x32_f16 v[60:63], v[148:151], v[196:199], v[60:63]
	v_mfma_f32_16x16x32_f16 v[28:31], v[152:155], v[168:171], v[28:31]
	v_mfma_f32_16x16x32_f16 v[24:27], v[160:163], v[168:171], v[24:27]
	v_mfma_f32_16x16x32_f16 v[20:23], v[152:155], v[176:179], v[20:23]
	v_mfma_f32_16x16x32_f16 v[16:19], v[160:163], v[176:179], v[16:19]
	v_mfma_f32_16x16x32_f16 v[12:15], v[152:155], v[184:187], v[12:15]
	v_mfma_f32_16x16x32_f16 v[8:11], v[160:163], v[184:187], v[8:11]
	v_mfma_f32_16x16x32_f16 v[4:7], v[152:155], v[192:195], v[4:7]
	v_mfma_f32_16x16x32_f16 v[0:3], v[160:163], v[192:195], v[0:3]
	v_mfma_f32_16x16x32_f16 v[28:31], v[156:159], v[172:175], v[28:31]
	v_mfma_f32_16x16x32_f16 v[24:27], v[164:167], v[172:175], v[24:27]
	v_mfma_f32_16x16x32_f16 v[20:23], v[156:159], v[180:183], v[20:23]
	v_mfma_f32_16x16x32_f16 v[16:19], v[164:167], v[180:183], v[16:19]
	v_mfma_f32_16x16x32_f16 v[12:15], v[156:159], v[188:191], v[12:15]
	v_mfma_f32_16x16x32_f16 v[8:11], v[164:167], v[188:191], v[8:11]
	v_mfma_f32_16x16x32_f16 v[4:7], v[156:159], v[196:199], v[4:7]
	v_mfma_f32_16x16x32_f16 v[0:3], v[164:167], v[196:199], v[0:3]
	s_barrier
	s_add_i32 s1, s1, 2
	s_add_u32 s85, s85, 0x100
	s_addc_u32 s86, s86, 0
	s_add_u32 s87, s87, 0x100
	s_addc_u32 s0, s0, 0
	s_add_u32 s40, s40, 0x100
	s_addc_u32 s41, s41, 0
	s_cmp_gt_u32 s1, 29
	.p2align 6

; #define PG8_STAGE(bufoff, gbase, voff) do { _Pragma("unroll") for (int _i = 0; _i < 2; ++_i) glds16_s((gbase), (voff)[_i], ldsb + (unsigned)((bufoff) + _i * 8192)); } while (0)
; #define PG8_LDA(dst, b, h) do { _Pragma("unroll") for (int m = 0; m < 4; ++m) _Pragma("unroll") for (int k = 0; k < 2; ++k) dst[m][k] = *(const LAS h16x8*)(lds + PG8_SA(b, h) + aoff + m * 2048 + k * 1024); } while (0)
; #define PG8_LDB(dst, b, h) do { _Pragma("unroll") for (int n = 0; n < 2; ++n) _Pragma("unroll") for (int k = 0; k < 2; ++k) dst[n][k] = *(const LAS h16x8*)(lds + PG8_SB(b, h) + boff + n * 2048 + k * 1024); } while (0)
; #define PG8_MMA(ai, bj, At, Bt) do { __builtin_amdgcn_s_setprio(1); _Pragma("unroll") for (int m = 0; m < 4; ++m) _Pragma("unroll") for (int n = 0; n < 2; ++n) _Pragma("unroll") for (int k = 0; k < 2; ++k) \
;         acc[ai][bj][m][n] = mma_step<I8>(Bt[n][k], At[m][k], acc[ai][bj][m][n]); __builtin_amdgcn_s_setprio(0); } while (0)
; #define PG8_WAIT_V(n) asm volatile("s_waitcnt vmcnt(" #n ")" ::: "memory")
; #define PG8_WAIT_L(n) asm volatile("s_waitcnt lgkmcnt(" #n ")" ::: "memory")
; #define PG8_BAR __builtin_amdgcn_s_barrier()
; #define PG8_SCHED __builtin_amdgcn_sched_barrier(0)
; template <class Prob, class Epi, bool I8 = false, bool ALIGN_EPI = true, bool SP2 = true>
; __device__ __forceinline__ void gemm_phase(LAS unsigned char* lds, int wave, const Prob& P, const Epi& E) {
;     ...
;             PG8_LDB(B0, 0, 0); PG8_LDB(B1, 0, 1); PG8_SCHED; PG8_LDA(At, 0, 0); PG8_STAGE(PG8_SA(1, 1), a1 + hstepA, voffA);
;             PG8_WAIT_V(8); PG8_WAIT_L(0); PG8_BAR; PG8_MMA(0, 0, At, B0); PG8_MMA(0, 1, At, B1); PG8_BAR; PG8_SCHED;
;             PG8_LDA(At, 0, 1); PG8_STAGE(PG8_SB(0, 0), b2, voffB); PG8_STAGE(PG8_SB(0, 1), b2 + hstepB, voffB); PG8_STAGE(PG8_SA(0, 0), a2, voffA);
;             PG8_WAIT_V(8); PG8_WAIT_L(0); PG8_BAR; PG8_MMA(1, 0, At, B0); PG8_MMA(1, 1, At, B1); PG8_BAR; PG8_SCHED;
.Lpeel_536:
	v_add_u32_e32 v146, 0x10000, v136
	v_add_u32_e32 v162, 0x14000, v136
	ds_read_b128 v[128:131], v146
	ds_read_b128 v[138:141], v146 offset:1024
	ds_read_b128 v[142:145], v146 offset:2048
	ds_read_b128 v[146:149], v146 offset:3072
	ds_read_b128 v[150:153], v162
	ds_read_b128 v[154:157], v162 offset:1024
	ds_read_b128 v[158:161], v162 offset:2048
	ds_read_b128 v[162:165], v162 offset:3072
	s_cmp_eq_u32 s1, 28
	s_cselect_b32 s44, s57, s73
	s_cselect_b32 s45, s51, s74
	s_cselect_b32 s42, s72, s75
	s_cselect_b32 s43, s49, s0
	s_add_u32 s40, s44, 0x80
	s_addc_u32 s41, s45, 0
	ds_read_b128 v[166:169], v137
	ds_read_b128 v[170:173], v137 offset:1024
	ds_read_b128 v[174:177], v137 offset:2048
	ds_read_b128 v[178:181], v137 offset:3072
	ds_read_b128 v[182:185], v137 offset:4096
	ds_read_b128 v[186:189], v137 offset:5120
	ds_read_b128 v[190:193], v137 offset:6144
	ds_read_b128 v[194:197], v137 offset:7168
	s_mov_b32 s4, m0
	s_mov_b32 m0, s91
	s_nop 0
	global_load_lds_dwordx4 v132, s[38:39]
	s_mov_b32 m0, s4
	s_nop 0
	s_mov_b32 s4, m0
	s_mov_b32 m0, s94
	s_nop 0
	global_load_lds_dwordx4 v134, s[38:39]
	s_mov_b32 m0, s4
	s_waitcnt vmcnt(8)
	s_waitcnt lgkmcnt(0)
	s_barrier
	s_waitcnt lgkmcnt(7)
	v_mfma_f32_16x16x32_f16 v[124:127], v[128:131], v[166:169], 0
	v_mfma_f32_16x16x32_f16 v[120:123], v[142:145], v[166:169], 0
	s_waitcnt lgkmcnt(5)
	v_mfma_f32_16x16x32_f16 v[108:111], v[128:131], v[174:177], 0
	v_mfma_f32_16x16x32_f16 v[104:107], v[142:145], v[174:177], 0
	s_waitcnt lgkmcnt(3)
	v_mfma_f32_16x16x32_f16 v[92:95], v[128:131], v[182:185], 0
	v_mfma_f32_16x16x32_f16 v[88:91], v[142:145], v[182:185], 0
	s_waitcnt lgkmcnt(1)
	v_mfma_f32_16x16x32_f16 v[76:79], v[128:131], v[190:193], 0
	v_mfma_f32_16x16x32_f16 v[72:75], v[142:145], v[190:193], 0
	v_mfma_f32_16x16x32_f16 v[124:127], v[138:141], v[170:173], v[124:127]
	v_mfma_f32_16x16x32_f16 v[120:123], v[146:149], v[170:173], v[120:123]
	v_mfma_f32_16x16x32_f16 v[108:111], v[138:141], v[178:181], v[108:111]
	v_mfma_f32_16x16x32_f16 v[104:107], v[146:149], v[178:181], v[104:107]
	v_mfma_f32_16x16x32_f16 v[92:95], v[138:141], v[186:189], v[92:95]
	v_mfma_f32_16x16x32_f16 v[88:91], v[146:149], v[186:189], v[88:91]
	s_waitcnt lgkmcnt(0)
	v_mfma_f32_16x16x32_f16 v[76:79], v[138:141], v[194:197], v[76:79]
	v_mfma_f32_16x16x32_f16 v[72:75], v[146:149], v[194:197], v[72:75]
	v_mfma_f32_16x16x32_f16 v[116:119], v[150:153], v[166:169], 0
	v_mfma_f32_16x16x32_f16 v[112:115], v[158:161], v[166:169], 0
	v_mfma_f32_16x16x32_f16 v[100:103], v[150:153], v[174:177], 0
	v_mfma_f32_16x16x32_f16 v[96:99], v[158:161], v[174:177], 0
	v_mfma_f32_16x16x32_f16 v[84:87], v[150:153], v[182:185], 0
	v_mfma_f32_16x16x32_f16 v[80:83], v[158:161], v[182:185], 0
	v_mfma_f32_16x16x32_f16 v[68:71], v[150:153], v[190:193], 0
	v_mfma_f32_16x16x32_f16 v[64:67], v[158:161], v[190:193], 0
	v_mfma_f32_16x16x32_f16 v[116:119], v[154:157], v[170:173], v[116:119]
	v_mfma_f32_16x16x32_f16 v[112:115], v[162:165], v[170:173], v[112:115]
	v_mfma_f32_16x16x32_f16 v[100:103], v[154:157], v[178:181], v[100:103]
	v_mfma_f32_16x16x32_f16 v[96:99], v[162:165], v[178:181], v[96:99]
	v_mfma_f32_16x16x32_f16 v[84:87], v[154:157], v[186:189], v[84:87]
	v_mfma_f32_16x16x32_f16 v[80:83], v[162:165], v[186:189], v[80:83]
	v_mfma_f32_16x16x32_f16 v[68:71], v[154:157], v[194:197], v[68:71]
	v_mfma_f32_16x16x32_f16 v[64:67], v[162:165], v[194:197], v[64:67]
	s_barrier
	ds_read_b128 v[166:169], v137 offset:16384
	ds_read_b128 v[170:173], v137 offset:17408
	ds_read_b128 v[174:177], v137 offset:18432
	ds_read_b128 v[178:181], v137 offset:19456
	ds_read_b128 v[182:185], v137 offset:20480
	ds_read_b128 v[186:189], v137 offset:21504
	ds_read_b128 v[190:193], v137 offset:22528
	ds_read_b128 v[194:197], v137 offset:23552
	s_mov_b32 s4, m0
	s_mov_b32 m0, s64
	s_nop 0
	global_load_lds_dwordx4 v133, s[42:43]
	s_mov_b32 m0, s4
	s_nop 0
	s_mov_b32 s4, m0
	s_mov_b32 m0, s68
	s_nop 0
	global_load_lds_dwordx4 v135, s[42:43]
	s_mov_b32 m0, s4
	s_add_u32 s4, s42, 0x80000
	s_addc_u32 s5, s43, 0
	s_mov_b32 s6, m0
	s_mov_b32 m0, s69
	s_nop 0
	global_load_lds_dwordx4 v133, s[4:5]
	s_mov_b32 m0, s6
	s_nop 0
	s_mov_b32 s6, m0
	s_mov_b32 m0, s79
	s_nop 0
	global_load_lds_dwordx4 v135, s[4:5]
	s_mov_b32 m0, s6
	s_mov_b32 s4, m0
	s_mov_b32 m0, s63
	s_nop 0
	global_load_lds_dwordx4 v132, s[44:45]
	s_mov_b32 m0, s4
	s_nop 0
	s_mov_b32 s4, m0
	s_mov_b32 m0, s80
	s_nop 0
	global_load_lds_dwordx4 v134, s[44:45]
	s_mov_b32 m0, s4
	s_waitcnt vmcnt(8)
	s_waitcnt lgkmcnt(0)
	s_barrier
	s_waitcnt lgkmcnt(7)
	v_mfma_f32_16x16x32_f16 v[60:63], v[128:131], v[166:169], 0
	v_mfma_f32_16x16x32_f16 v[56:59], v[142:145], v[166:169], 0
	s_waitcnt lgkmcnt(5)
	v_mfma_f32_16x16x32_f16 v[44:47], v[128:131], v[174:177], 0
	v_mfma_f32_16x16x32_f16 v[40:43], v[142:145], v[174:177], 0
	s_waitcnt lgkmcnt(3)
	v_mfma_f32_16x16x32_f16 v[28:31], v[128:131], v[182:185], 0
	v_mfma_f32_16x16x32_f16 v[24:27], v[142:145], v[182:185], 0
	s_waitcnt lgkmcnt(1)
	v_mfma_f32_16x16x32_f16 v[12:15], v[128:131], v[190:193], 0
	v_mfma_f32_16x16x32_f16 v[8:11], v[142:145], v[190:193], 0
	v_mfma_f32_16x16x32_f16 v[60:63], v[138:141], v[170:173], v[60:63]
	v_mfma_f32_16x16x32_f16 v[56:59], v[146:149], v[170:173], v[56:59]
	v_mfma_f32_16x16x32_f16 v[44:47], v[138:141], v[178:181], v[44:47]
	v_mfma_f32_16x16x32_f16 v[40:43], v[146:149], v[178:181], v[40:43]
	v_mfma_f32_16x16x32_f16 v[28:31], v[138:141], v[186:189], v[28:31]
	v_mfma_f32_16x16x32_f16 v[24:27], v[146:149], v[186:189], v[24:27]
	s_waitcnt lgkmcnt(0)
	v_mfma_f32_16x16x32_f16 v[12:15], v[138:141], v[194:197], v[12:15]
	v_mfma_f32_16x16x32_f16 v[8:11], v[146:149], v[194:197], v[8:11]
	v_mfma_f32_16x16x32_f16 v[52:55], v[150:153], v[166:169], 0
	v_mfma_f32_16x16x32_f16 v[48:51], v[158:161], v[166:169], 0
	v_mfma_f32_16x16x32_f16 v[36:39], v[150:153], v[174:177], 0
	v_mfma_f32_16x16x32_f16 v[32:35], v[158:161], v[174:177], 0
	v_mfma_f32_16x16x32_f16 v[20:23], v[150:153], v[182:185], 0
	v_mfma_f32_16x16x32_f16 v[16:19], v[158:161], v[182:185], 0
	v_mfma_f32_16x16x32_f16 v[4:7], v[150:153], v[190:193], 0
	v_mfma_f32_16x16x32_f16 v[0:3], v[158:161], v[190:193], 0
	v_mfma_f32_16x16x32_f16 v[52:55], v[154:157], v[170:173], v[52:55]
	v_mfma_f32_16x16x32_f16 v[48:51], v[162:165], v[170:173], v[48:51]
	v_mfma_f32_16x16x32_f16 v[36:39], v[154:157], v[178:181], v[36:39]
	v_mfma_f32_16x16x32_f16 v[32:35], v[162:165], v[178:181], v[32:35]
	v_mfma_f32_16x16x32_f16 v[20:23], v[154:157], v[186:189], v[20:23]
	v_mfma_f32_16x16x32_f16 v[16:19], v[162:165], v[186:189], v[16:19]
	v_mfma_f32_16x16x32_f16 v[4:7], v[154:157], v[194:197], v[4:7]
	v_mfma_f32_16x16x32_f16 v[0:3], v[162:165], v[194:197], v[0:3]
	s_barrier
; #define PG8_STAGE(bufoff, gbase, voff) do { _Pragma("unroll") for (int _i = 0; _i < 2; ++_i) glds16_s((gbase), (voff)[_i], ldsb + (unsigned)((bufoff) + _i * 8192)); } while (0)
; #define PG8_LDA(dst, b, h) do { _Pragma("unroll") for (int m = 0; m < 4; ++m) _Pragma("unroll") for (int k = 0; k < 2; ++k) dst[m][k] = *(const LAS h16x8*)(lds + PG8_SA(b, h) + aoff + m * 2048 + k * 1024); } while (0)
; #define PG8_LDB(dst, b, h) do { _Pragma("unroll") for (int n = 0; n < 2; ++n) _Pragma("unroll") for (int k = 0; k < 2; ++k) dst[n][k] = *(const LAS h16x8*)(lds + PG8_SB(b, h) + boff + n * 2048 + k * 1024); } while (0)
; #define PG8_MMA(ai, bj, At, Bt) do { __builtin_amdgcn_s_setprio(1); _Pragma("unroll") for (int m = 0; m < 4; ++m) _Pragma("unroll") for (int n = 0; n < 2; ++n) _Pragma("unroll") for (int k = 0; k < 2; ++k) \
;         acc[ai][bj][m][n] = mma_step<I8>(Bt[n][k], At[m][k], acc[ai][bj][m][n]); __builtin_amdgcn_s_setprio(0); } while (0)
; #define PG8_WAIT_V(n) asm volatile("s_waitcnt vmcnt(" #n ")" ::: "memory")
; #define PG8_WAIT_L(n) asm volatile("s_waitcnt lgkmcnt(" #n ")" ::: "memory")
; #define PG8_BAR __builtin_amdgcn_s_barrier()
; #define PG8_SCHED __builtin_amdgcn_sched_barrier(0)
; template <class Prob, class Epi, bool I8 = false, bool ALIGN_EPI = true, bool SP2 = true>
; __device__ __forceinline__ void gemm_phase(LAS unsigned char* lds, int wave, const Prob& P, const Epi& E) {
;     ...
;         for (int t = 0; t < nt; t += 2) {
;             const bool last = (t == nt - 2);
;             const char* a1 = cA + (size_t)(t + 1) * kstep;
;             const char* a2 = last ? nA : cA + (size_t)(t + 2) * kstep; const char* b2 = last ? nB : cB + (size_t)(t + 2) * kstep;
;             const char* a3 = a2 + kstep; const char* b3 = b2 + kstep;
;     ...
;             PG8_LDB(B0, 1, 0); PG8_LDB(B1, 1, 1); PG8_SCHED; PG8_LDA(At, 1, 0); PG8_STAGE(PG8_SA(0, 1), a2 + hstepA, voffA);
;             PG8_WAIT_V(8); PG8_WAIT_L(0); PG8_BAR; PG8_MMA(0, 0, At, B0); PG8_MMA(0, 1, At, B1); PG8_BAR; PG8_SCHED;
;             PG8_LDA(At, 1, 1); PG8_STAGE(PG8_SB(1, 0), b3, voffB); PG8_STAGE(PG8_SB(1, 1), b3 + hstepB, voffB); PG8_STAGE(PG8_SA(1, 0), a3, voffA);
;             PG8_WAIT_V(8); PG8_WAIT_L(0); PG8_BAR; PG8_MMA(1, 0, At, B0); PG8_MMA(1, 1, At, B1); PG8_BAR; PG8_SCHED;
	v_add_u32_e32 v146, 0x18000, v136
	v_add_u32_e32 v162, 0x1c000, v136
	ds_read_b128 v[128:131], v146
	ds_read_b128 v[138:141], v146 offset:1024
	ds_read_b128 v[142:145], v146 offset:2048
	ds_read_b128 v[146:149], v146 offset:3072
	ds_read_b128 v[150:153], v162
	ds_read_b128 v[154:157], v162 offset:1024
	ds_read_b128 v[158:161], v162 offset:2048
	ds_read_b128 v[162:165], v162 offset:3072
	ds_read_b128 v[166:169], v137 offset:32768
	ds_read_b128 v[170:173], v137 offset:33792
	ds_read_b128 v[174:177], v137 offset:34816
	ds_read_b128 v[178:181], v137 offset:35840
	ds_read_b128 v[182:185], v137 offset:36864
	ds_read_b128 v[186:189], v137 offset:37888
	ds_read_b128 v[190:193], v137 offset:38912
	ds_read_b128 v[194:197], v137 offset:39936
	s_add_u32 s4, s44, 0x80000
	s_addc_u32 s5, s45, 0
	s_mov_b32 s6, m0
	s_mov_b32 m0, s81
	s_nop 0
	global_load_lds_dwordx4 v132, s[4:5]
	s_mov_b32 m0, s6
	s_nop 0
	s_mov_b32 s6, m0
	s_mov_b32 m0, s82
	s_nop 0
	global_load_lds_dwordx4 v134, s[4:5]
	s_mov_b32 m0, s6
	s_waitcnt vmcnt(8)
	s_waitcnt lgkmcnt(0)
	s_barrier
	s_waitcnt lgkmcnt(7)
	v_mfma_f32_16x16x32_f16 v[124:127], v[128:131], v[166:169], v[124:127]
	v_mfma_f32_16x16x32_f16 v[120:123], v[142:145], v[166:169], v[120:123]
	s_waitcnt lgkmcnt(5)
	v_mfma_f32_16x16x32_f16 v[108:111], v[128:131], v[174:177], v[108:111]
	v_mfma_f32_16x16x32_f16 v[104:107], v[142:145], v[174:177], v[104:107]
	s_waitcnt lgkmcnt(3)
	v_mfma_f32_16x16x32_f16 v[92:95], v[128:131], v[182:185], v[92:95]
	v_mfma_f32_16x16x32_f16 v[88:91], v[142:145], v[182:185], v[88:91]
	s_waitcnt lgkmcnt(1)
	v_mfma_f32_16x16x32_f16 v[76:79], v[128:131], v[190:193], v[76:79]
	v_mfma_f32_16x16x32_f16 v[72:75], v[142:145], v[190:193], v[72:75]
	v_mfma_f32_16x16x32_f16 v[124:127], v[138:141], v[170:173], v[124:127]
	v_mfma_f32_16x16x32_f16 v[120:123], v[146:149], v[170:173], v[120:123]
	v_mfma_f32_16x16x32_f16 v[108:111], v[138:141], v[178:181], v[108:111]
	v_mfma_f32_16x16x32_f16 v[104:107], v[146:149], v[178:181], v[104:107]
	v_mfma_f32_16x16x32_f16 v[92:95], v[138:141], v[186:189], v[92:95]
	v_mfma_f32_16x16x32_f16 v[88:91], v[146:149], v[186:189], v[88:91]
	s_waitcnt lgkmcnt(0)
	v_mfma_f32_16x16x32_f16 v[76:79], v[138:141], v[194:197], v[76:79]
	v_mfma_f32_16x16x32_f16 v[72:75], v[146:149], v[194:197], v[72:75]
	v_mfma_f32_16x16x32_f16 v[116:119], v[150:153], v[166:169], v[116:119]
	v_mfma_f32_16x16x32_f16 v[112:115], v[158:161], v[166:169], v[112:115]
	v_mfma_f32_16x16x32_f16 v[100:103], v[150:153], v[174:177], v[100:103]
	v_mfma_f32_16x16x32_f16 v[96:99], v[158:161], v[174:177], v[96:99]
	v_mfma_f32_16x16x32_f16 v[84:87], v[150:153], v[182:185], v[84:87]
	v_mfma_f32_16x16x32_f16 v[80:83], v[158:161], v[182:185], v[80:83]
	v_mfma_f32_16x16x32_f16 v[68:71], v[150:153], v[190:193], v[68:71]
	v_mfma_f32_16x16x32_f16 v[64:67], v[158:161], v[190:193], v[64:67]
	v_mfma_f32_16x16x32_f16 v[116:119], v[154:157], v[170:173], v[116:119]
	v_mfma_f32_16x16x32_f16 v[112:115], v[162:165], v[170:173], v[112:115]
	v_mfma_f32_16x16x32_f16 v[100:103], v[154:157], v[178:181], v[100:103]
	v_mfma_f32_16x16x32_f16 v[96:99], v[162:165], v[178:181], v[96:99]
	v_mfma_f32_16x16x32_f16 v[84:87], v[154:157], v[186:189], v[84:87]
	v_mfma_f32_16x16x32_f16 v[80:83], v[162:165], v[186:189], v[80:83]
	v_mfma_f32_16x16x32_f16 v[68:71], v[154:157], v[194:197], v[68:71]
	v_mfma_f32_16x16x32_f16 v[64:67], v[162:165], v[194:197], v[64:67]
	s_barrier
	ds_read_b128 v[166:169], v137 offset:49152
	ds_read_b128 v[170:173], v137 offset:50176
	ds_read_b128 v[174:177], v137 offset:51200
	ds_read_b128 v[178:181], v137 offset:52224
	ds_read_b128 v[182:185], v137 offset:53248
	ds_read_b128 v[186:189], v137 offset:54272
	ds_read_b128 v[190:193], v137 offset:55296
	ds_read_b128 v[194:197], v137 offset:56320
	s_add_u32 s4, s42, 0x80
	s_addc_u32 s5, s43, 0
	s_mov_b32 s6, m0
	s_mov_b32 m0, s85
	s_nop 0
	global_load_lds_dwordx4 v133, s[4:5]
	s_mov_b32 m0, s6
	s_nop 0
	s_mov_b32 s6, m0
	s_mov_b32 m0, s86
	s_nop 0
	global_load_lds_dwordx4 v135, s[4:5]
	s_mov_b32 m0, s6
	s_add_u32 s4, s42, 0x80080
	s_addc_u32 s5, s43, 0
	s_mov_b32 s6, m0
	s_mov_b32 m0, s89
	s_nop 0
	global_load_lds_dwordx4 v133, s[4:5]
	s_mov_b32 m0, s6
	s_nop 0
	s_mov_b32 s6, m0
	s_mov_b32 m0, s90
	s_nop 0
	global_load_lds_dwordx4 v135, s[4:5]
	s_mov_b32 m0, s6
	s_mov_b32 s4, m0
	s_mov_b32 m0, s87
	s_nop 0
	global_load_lds_dwordx4 v132, s[40:41]
	s_mov_b32 m0, s4
	s_nop 0
	s_mov_b32 s4, m0
	s_mov_b32 m0, s88
	s_nop 0
	global_load_lds_dwordx4 v134, s[40:41]
	s_mov_b32 m0, s4
	s_waitcnt vmcnt(8)
	s_waitcnt lgkmcnt(0)
	s_barrier
	s_waitcnt lgkmcnt(7)
	v_mfma_f32_16x16x32_f16 v[60:63], v[128:131], v[166:169], v[60:63]
	v_mfma_f32_16x16x32_f16 v[56:59], v[142:145], v[166:169], v[56:59]
	s_waitcnt lgkmcnt(5)
	v_mfma_f32_16x16x32_f16 v[44:47], v[128:131], v[174:177], v[44:47]
	v_mfma_f32_16x16x32_f16 v[40:43], v[142:145], v[174:177], v[40:43]
	s_waitcnt lgkmcnt(3)
	v_mfma_f32_16x16x32_f16 v[28:31], v[128:131], v[182:185], v[28:31]
	v_mfma_f32_16x16x32_f16 v[24:27], v[142:145], v[182:185], v[24:27]
	s_waitcnt lgkmcnt(1)
	v_mfma_f32_16x16x32_f16 v[12:15], v[128:131], v[190:193], v[12:15]
	v_mfma_f32_16x16x32_f16 v[8:11], v[142:145], v[190:193], v[8:11]
	v_mfma_f32_16x16x32_f16 v[60:63], v[138:141], v[170:173], v[60:63]
	v_mfma_f32_16x16x32_f16 v[56:59], v[146:149], v[170:173], v[56:59]
	v_mfma_f32_16x16x32_f16 v[44:47], v[138:141], v[178:181], v[44:47]
	v_mfma_f32_16x16x32_f16 v[40:43], v[146:149], v[178:181], v[40:43]
	v_mfma_f32_16x16x32_f16 v[28:31], v[138:141], v[186:189], v[28:31]
	v_mfma_f32_16x16x32_f16 v[24:27], v[146:149], v[186:189], v[24:27]
	s_waitcnt lgkmcnt(0)
	v_mfma_f32_16x16x32_f16 v[12:15], v[138:141], v[194:197], v[12:15]
	v_mfma_f32_16x16x32_f16 v[8:11], v[146:149], v[194:197], v[8:11]
	v_mfma_f32_16x16x32_f16 v[52:55], v[150:153], v[166:169], v[52:55]
	v_mfma_f32_16x16x32_f16 v[48:51], v[158:161], v[166:169], v[48:51]
	v_mfma_f32_16x16x32_f16 v[36:39], v[150:153], v[174:177], v[36:39]
	v_mfma_f32_16x16x32_f16 v[32:35], v[158:161], v[174:177], v[32:35]
	v_mfma_f32_16x16x32_f16 v[20:23], v[150:153], v[182:185], v[20:23]
	v_mfma_f32_16x16x32_f16 v[16:19], v[158:161], v[182:185], v[16:19]
	v_mfma_f32_16x16x32_f16 v[4:7], v[150:153], v[190:193], v[4:7]
	v_mfma_f32_16x16x32_f16 v[0:3], v[158:161], v[190:193], v[0:3]
	v_mfma_f32_16x16x32_f16 v[52:55], v[154:157], v[170:173], v[52:55]
	v_mfma_f32_16x16x32_f16 v[48:51], v[162:165], v[170:173], v[48:51]
	v_mfma_f32_16x16x32_f16 v[36:39], v[154:157], v[178:181], v[36:39]
	v_mfma_f32_16x16x32_f16 v[32:35], v[162:165], v[178:181], v[32:35]
	v_mfma_f32_16x16x32_f16 v[20:23], v[154:157], v[186:189], v[20:23]
	v_mfma_f32_16x16x32_f16 v[16:19], v[162:165], v[186:189], v[16:19]
	v_mfma_f32_16x16x32_f16 v[4:7], v[154:157], v[194:197], v[4:7]
	v_mfma_f32_16x16x32_f16 v[0:3], v[162:165], v[194:197], v[0:3]
	s_barrier
	s_add_i32 s1, s1, 2
	s_add_u32 s73, s73, 0x100
	s_addc_u32 s74, s74, 0
	s_add_u32 s75, s75, 0x100
	s_addc_u32 s0, s0, 0
	s_add_u32 s38, s38, 0x100
	s_addc_u32 s39, s39, 0
	s_cmp_gt_u32 s1, 29
	.p2align 6

; #define PG8_STAGE(bufoff, gbase, voff) do { _Pragma("unroll") for (int _i = 0; _i < 2; ++_i) glds16_s((gbase), (voff)[_i], ldsb + (unsigned)((bufoff) + _i * 8192)); } while (0)
; #define PG8_LDA(dst, b, h) do { _Pragma("unroll") for (int m = 0; m < 4; ++m) _Pragma("unroll") for (int k = 0; k < 2; ++k) dst[m][k] = *(const LAS h16x8*)(lds + PG8_SA(b, h) + aoff + m * 2048 + k * 1024); } while (0)
; #define PG8_LDB(dst, b, h) do { _Pragma("unroll") for (int n = 0; n < 2; ++n) _Pragma("unroll") for (int k = 0; k < 2; ++k) dst[n][k] = *(const LAS h16x8*)(lds + PG8_SB(b, h) + boff + n * 2048 + k * 1024); } while (0)
; #define PG8_MMA(ai, bj, At, Bt) do { __builtin_amdgcn_s_setprio(1); _Pragma("unroll") for (int m = 0; m < 4; ++m) _Pragma("unroll") for (int n = 0; n < 2; ++n) _Pragma("unroll") for (int k = 0; k < 2; ++k) \
;         acc[ai][bj][m][n] = mma_step<I8>(Bt[n][k], At[m][k], acc[ai][bj][m][n]); __builtin_amdgcn_s_setprio(0); } while (0)
; #define PG8_WAIT_V(n) asm volatile("s_waitcnt vmcnt(" #n ")" ::: "memory")
; #define PG8_WAIT_L(n) asm volatile("s_waitcnt lgkmcnt(" #n ")" ::: "memory")
; #define PG8_BAR __builtin_amdgcn_s_barrier()
; #define PG8_SCHED __builtin_amdgcn_sched_barrier(0)
; template <bool I8> __device__ __forceinline__ f32x4 mma_step(const h16x8& b, const h16x8& a, const f32x4& c) {
;     if constexpr (I8) return __builtin_bit_cast(f32x4, __builtin_amdgcn_mfma_i32_16x16x64_i8(__builtin_bit_cast(i32x4, b), __builtin_bit_cast(i32x4, a), __builtin_bit_cast(i32x4, c), 0, 0, 0));
;     else return __builtin_amdgcn_mfma_f32_16x16x32_f16(b, a, c, 0, 0, 0);
; template <class Prob, class Epi, bool I8 = false, bool ALIGN_EPI = true, bool SP2 = true>
; __device__ __forceinline__ void gemm_phase(LAS unsigned char* lds, int wave, const Prob& P, const Epi& E) {
;     ...
;             PG8_LDB(B0, 0, 0); PG8_LDB(B1, 0, 1); PG8_SCHED; PG8_LDA(At, 0, 0); PG8_STAGE(PG8_SA(1, 1), a1 + hstepA, voffA);
;             PG8_WAIT_V(8); PG8_WAIT_L(0); PG8_BAR; PG8_MMA(0, 0, At, B0); PG8_MMA(0, 1, At, B1); PG8_BAR; PG8_SCHED;
;             PG8_LDA(At, 0, 1); PG8_STAGE(PG8_SB(0, 0), b2, voffB); PG8_STAGE(PG8_SB(0, 1), b2 + hstepB, voffB); PG8_STAGE(PG8_SA(0, 0), a2, voffA);
;             PG8_WAIT_V(8); PG8_WAIT_L(0); PG8_BAR; PG8_MMA(1, 0, At, B0); PG8_MMA(1, 1, At, B1); PG8_BAR; PG8_SCHED;
.Lpeel_616:
	v_add_u32_e32 v140, 0x10000, v152
	v_add_u32_e32 v162, 0x14000, v152
	ds_read_b128 v[128:131], v140
	ds_read_b128 v[132:135], v140 offset:1024
	ds_read_b128 v[136:139], v140 offset:2048
	ds_read_b128 v[140:143], v140 offset:3072
	ds_read_b128 v[144:147], v162
	ds_read_b128 v[154:157], v162 offset:1024
	ds_read_b128 v[158:161], v162 offset:2048
	ds_read_b128 v[162:165], v162 offset:3072
	s_cmp_eq_u32 s1, 12
	s_cselect_b32 s62, s43, s73
	s_cselect_b32 s63, s39, vcc_lo
	s_cselect_b32 s68, s61, vcc_hi
	s_cselect_b32 s69, s41, s0
	s_add_u32 s56, s62, 0x80
	s_addc_u32 s57, s63, 0
	ds_read_b128 v[166:169], v153
	ds_read_b128 v[170:173], v153 offset:1024
	ds_read_b128 v[174:177], v153 offset:2048
	ds_read_b128 v[178:181], v153 offset:3072
	ds_read_b128 v[182:185], v153 offset:4096
	ds_read_b128 v[186:189], v153 offset:5120
	ds_read_b128 v[190:193], v153 offset:6144
	ds_read_b128 v[194:197], v153 offset:7168
	s_mov_b32 s4, m0
	s_mov_b32 m0, s96
	s_nop 0
	global_load_lds_dwordx4 v148, s[44:45]
	s_mov_b32 m0, s4
	s_nop 0
	s_mov_b32 s4, m0
	s_mov_b32 m0, s75
	s_nop 0
	global_load_lds_dwordx4 v150, s[44:45]
	s_mov_b32 m0, s4
	s_waitcnt vmcnt(8)
	s_waitcnt lgkmcnt(0)
	s_barrier
	s_waitcnt lgkmcnt(7)
	v_mfma_i32_16x16x64_i8 v[124:127], v[128:131], v[166:169], 0
	v_mfma_i32_16x16x64_i8 v[120:123], v[136:139], v[166:169], 0
	s_waitcnt lgkmcnt(5)
	v_mfma_i32_16x16x64_i8 v[108:111], v[128:131], v[174:177], 0
	v_mfma_i32_16x16x64_i8 v[104:107], v[136:139], v[174:177], 0
	s_waitcnt lgkmcnt(3)
	v_mfma_i32_16x16x64_i8 v[92:95], v[128:131], v[182:185], 0
	v_mfma_i32_16x16x64_i8 v[88:91], v[136:139], v[182:185], 0
	s_waitcnt lgkmcnt(1)
	v_mfma_i32_16x16x64_i8 v[76:79], v[128:131], v[190:193], 0
	v_mfma_i32_16x16x64_i8 v[72:75], v[136:139], v[190:193], 0
	v_mfma_i32_16x16x64_i8 v[124:127], v[132:135], v[170:173], v[124:127]
	v_mfma_i32_16x16x64_i8 v[120:123], v[140:143], v[170:173], v[120:123]
	v_mfma_i32_16x16x64_i8 v[108:111], v[132:135], v[178:181], v[108:111]
	v_mfma_i32_16x16x64_i8 v[104:107], v[140:143], v[178:181], v[104:107]
	v_mfma_i32_16x16x64_i8 v[92:95], v[132:135], v[186:189], v[92:95]
	v_mfma_i32_16x16x64_i8 v[88:91], v[140:143], v[186:189], v[88:91]
	s_waitcnt lgkmcnt(0)
	v_mfma_i32_16x16x64_i8 v[76:79], v[132:135], v[194:197], v[76:79]
	v_mfma_i32_16x16x64_i8 v[72:75], v[140:143], v[194:197], v[72:75]
	v_mfma_i32_16x16x64_i8 v[116:119], v[144:147], v[166:169], 0
	v_mfma_i32_16x16x64_i8 v[112:115], v[158:161], v[166:169], 0
	v_mfma_i32_16x16x64_i8 v[100:103], v[144:147], v[174:177], 0
	v_mfma_i32_16x16x64_i8 v[96:99], v[158:161], v[174:177], 0
	v_mfma_i32_16x16x64_i8 v[84:87], v[144:147], v[182:185], 0
	v_mfma_i32_16x16x64_i8 v[80:83], v[158:161], v[182:185], 0
	v_mfma_i32_16x16x64_i8 v[68:71], v[144:147], v[190:193], 0
	v_mfma_i32_16x16x64_i8 v[64:67], v[158:161], v[190:193], 0
	v_mfma_i32_16x16x64_i8 v[116:119], v[154:157], v[170:173], v[116:119]
	v_mfma_i32_16x16x64_i8 v[112:115], v[162:165], v[170:173], v[112:115]
	v_mfma_i32_16x16x64_i8 v[100:103], v[154:157], v[178:181], v[100:103]
	v_mfma_i32_16x16x64_i8 v[96:99], v[162:165], v[178:181], v[96:99]
	v_mfma_i32_16x16x64_i8 v[84:87], v[154:157], v[186:189], v[84:87]
	v_mfma_i32_16x16x64_i8 v[80:83], v[162:165], v[186:189], v[80:83]
	v_mfma_i32_16x16x64_i8 v[68:71], v[154:157], v[194:197], v[68:71]
	v_mfma_i32_16x16x64_i8 v[64:67], v[162:165], v[194:197], v[64:67]
	s_barrier
	ds_read_b128 v[166:169], v153 offset:16384
	ds_read_b128 v[170:173], v153 offset:17408
	ds_read_b128 v[174:177], v153 offset:18432
	ds_read_b128 v[178:181], v153 offset:19456
	ds_read_b128 v[182:185], v153 offset:20480
	ds_read_b128 v[186:189], v153 offset:21504
	ds_read_b128 v[190:193], v153 offset:22528
	ds_read_b128 v[194:197], v153 offset:23552
	s_mov_b32 s4, m0
	s_mov_b32 m0, s81
	s_nop 0
	global_load_lds_dwordx4 v149, s[68:69]
	s_mov_b32 m0, s4
	s_nop 0
	s_mov_b32 s4, m0
	s_mov_b32 m0, s82
	s_nop 0
	global_load_lds_dwordx4 v151, s[68:69]
	s_mov_b32 m0, s4
	s_add_u32 s4, s68, 0x40000
	s_addc_u32 s5, s69, 0
	s_mov_b32 s6, m0
	s_mov_b32 m0, s83
	s_nop 0
	global_load_lds_dwordx4 v149, s[4:5]
	s_mov_b32 m0, s6
	s_nop 0
	s_mov_b32 s6, m0
	s_mov_b32 m0, s84
	s_nop 0
	global_load_lds_dwordx4 v151, s[4:5]
	s_mov_b32 m0, s6
	s_mov_b32 s4, m0
	s_mov_b32 m0, s2
	s_nop 0
	global_load_lds_dwordx4 v148, s[62:63]
	s_mov_b32 m0, s4
	s_nop 0
	s_mov_b32 s4, m0
	s_mov_b32 m0, s85
	s_nop 0
	global_load_lds_dwordx4 v150, s[62:63]
	s_mov_b32 m0, s4
	s_waitcnt vmcnt(8)
	s_waitcnt lgkmcnt(0)
	s_barrier
	s_waitcnt lgkmcnt(7)
	v_mfma_i32_16x16x64_i8 v[60:63], v[128:131], v[166:169], 0
	v_mfma_i32_16x16x64_i8 v[56:59], v[136:139], v[166:169], 0
	s_waitcnt lgkmcnt(5)
	v_mfma_i32_16x16x64_i8 v[44:47], v[128:131], v[174:177], 0
	v_mfma_i32_16x16x64_i8 v[40:43], v[136:139], v[174:177], 0
	s_waitcnt lgkmcnt(3)
	v_mfma_i32_16x16x64_i8 v[28:31], v[128:131], v[182:185], 0
	v_mfma_i32_16x16x64_i8 v[24:27], v[136:139], v[182:185], 0
	s_waitcnt lgkmcnt(1)
	v_mfma_i32_16x16x64_i8 v[12:15], v[128:131], v[190:193], 0
	v_mfma_i32_16x16x64_i8 v[8:11], v[136:139], v[190:193], 0
	v_mfma_i32_16x16x64_i8 v[60:63], v[132:135], v[170:173], v[60:63]
	v_mfma_i32_16x16x64_i8 v[56:59], v[140:143], v[170:173], v[56:59]
	v_mfma_i32_16x16x64_i8 v[44:47], v[132:135], v[178:181], v[44:47]
	v_mfma_i32_16x16x64_i8 v[40:43], v[140:143], v[178:181], v[40:43]
	v_mfma_i32_16x16x64_i8 v[28:31], v[132:135], v[186:189], v[28:31]
	v_mfma_i32_16x16x64_i8 v[24:27], v[140:143], v[186:189], v[24:27]
	s_waitcnt lgkmcnt(0)
	v_mfma_i32_16x16x64_i8 v[12:15], v[132:135], v[194:197], v[12:15]
	v_mfma_i32_16x16x64_i8 v[8:11], v[140:143], v[194:197], v[8:11]
	v_mfma_i32_16x16x64_i8 v[52:55], v[144:147], v[166:169], 0
	v_mfma_i32_16x16x64_i8 v[48:51], v[158:161], v[166:169], 0
	v_mfma_i32_16x16x64_i8 v[36:39], v[144:147], v[174:177], 0
	v_mfma_i32_16x16x64_i8 v[32:35], v[158:161], v[174:177], 0
	v_mfma_i32_16x16x64_i8 v[20:23], v[144:147], v[182:185], 0
	v_mfma_i32_16x16x64_i8 v[16:19], v[158:161], v[182:185], 0
	v_mfma_i32_16x16x64_i8 v[4:7], v[144:147], v[190:193], 0
	v_mfma_i32_16x16x64_i8 v[0:3], v[158:161], v[190:193], 0
	v_mfma_i32_16x16x64_i8 v[52:55], v[154:157], v[170:173], v[52:55]
	v_mfma_i32_16x16x64_i8 v[48:51], v[162:165], v[170:173], v[48:51]
	v_mfma_i32_16x16x64_i8 v[36:39], v[154:157], v[178:181], v[36:39]
	v_mfma_i32_16x16x64_i8 v[32:35], v[162:165], v[178:181], v[32:35]
	v_mfma_i32_16x16x64_i8 v[20:23], v[154:157], v[186:189], v[20:23]
	v_mfma_i32_16x16x64_i8 v[16:19], v[162:165], v[186:189], v[16:19]
	v_mfma_i32_16x16x64_i8 v[4:7], v[154:157], v[194:197], v[4:7]
	v_mfma_i32_16x16x64_i8 v[0:3], v[162:165], v[194:197], v[0:3]
	s_barrier
; #define PG8_STAGE(bufoff, gbase, voff) do { _Pragma("unroll") for (int _i = 0; _i < 2; ++_i) glds16_s((gbase), (voff)[_i], ldsb + (unsigned)((bufoff) + _i * 8192)); } while (0)
; #define PG8_LDA(dst, b, h) do { _Pragma("unroll") for (int m = 0; m < 4; ++m) _Pragma("unroll") for (int k = 0; k < 2; ++k) dst[m][k] = *(const LAS h16x8*)(lds + PG8_SA(b, h) + aoff + m * 2048 + k * 1024); } while (0)
; #define PG8_LDB(dst, b, h) do { _Pragma("unroll") for (int n = 0; n < 2; ++n) _Pragma("unroll") for (int k = 0; k < 2; ++k) dst[n][k] = *(const LAS h16x8*)(lds + PG8_SB(b, h) + boff + n * 2048 + k * 1024); } while (0)
; #define PG8_MMA(ai, bj, At, Bt) do { __builtin_amdgcn_s_setprio(1); _Pragma("unroll") for (int m = 0; m < 4; ++m) _Pragma("unroll") for (int n = 0; n < 2; ++n) _Pragma("unroll") for (int k = 0; k < 2; ++k) \
;         acc[ai][bj][m][n] = mma_step<I8>(Bt[n][k], At[m][k], acc[ai][bj][m][n]); __builtin_amdgcn_s_setprio(0); } while (0)
; #define PG8_WAIT_V(n) asm volatile("s_waitcnt vmcnt(" #n ")" ::: "memory")
; #define PG8_WAIT_L(n) asm volatile("s_waitcnt lgkmcnt(" #n ")" ::: "memory")
; #define PG8_BAR __builtin_amdgcn_s_barrier()
; #define PG8_SCHED __builtin_amdgcn_sched_barrier(0)
; template <class Prob, class Epi, bool I8 = false, bool ALIGN_EPI = true, bool SP2 = true>
; __device__ __forceinline__ void gemm_phase(LAS unsigned char* lds, int wave, const Prob& P, const Epi& E) {
;     ...
;         for (int t = 0; t < nt; t += 2) {
;             const bool last = (t == nt - 2);
;             const char* a1 = cA + (size_t)(t + 1) * kstep;
;             const char* a2 = last ? nA : cA + (size_t)(t + 2) * kstep; const char* b2 = last ? nB : cB + (size_t)(t + 2) * kstep;
;             const char* a3 = a2 + kstep; const char* b3 = b2 + kstep;
;     ...
;             PG8_LDB(B0, 1, 0); PG8_LDB(B1, 1, 1); PG8_SCHED; PG8_LDA(At, 1, 0); PG8_STAGE(PG8_SA(0, 1), a2 + hstepA, voffA);
;             PG8_WAIT_V(8); PG8_WAIT_L(0); PG8_BAR; PG8_MMA(0, 0, At, B0); PG8_MMA(0, 1, At, B1); PG8_BAR; PG8_SCHED;
;             PG8_LDA(At, 1, 1); PG8_STAGE(PG8_SB(1, 0), b3, voffB); PG8_STAGE(PG8_SB(1, 1), b3 + hstepB, voffB); PG8_STAGE(PG8_SA(1, 0), a3, voffA);
;             PG8_WAIT_V(8); PG8_WAIT_L(0); PG8_BAR; PG8_MMA(1, 0, At, B0); PG8_MMA(1, 1, At, B1); PG8_BAR; PG8_SCHED;
	v_add_u32_e32 v140, 0x18000, v152
	v_add_u32_e32 v162, 0x1c000, v152
	ds_read_b128 v[128:131], v140
	ds_read_b128 v[132:135], v140 offset:1024
	ds_read_b128 v[136:139], v140 offset:2048
	ds_read_b128 v[140:143], v140 offset:3072
	ds_read_b128 v[144:147], v162
	ds_read_b128 v[154:157], v162 offset:1024
	ds_read_b128 v[158:161], v162 offset:2048
	ds_read_b128 v[162:165], v162 offset:3072
	ds_read_b128 v[166:169], v153 offset:32768
	ds_read_b128 v[170:173], v153 offset:33792
	ds_read_b128 v[174:177], v153 offset:34816
	ds_read_b128 v[178:181], v153 offset:35840
	ds_read_b128 v[182:185], v153 offset:36864
	ds_read_b128 v[186:189], v153 offset:37888
	ds_read_b128 v[190:193], v153 offset:38912
	ds_read_b128 v[194:197], v153 offset:39936
	s_add_u32 s4, s62, 0x40000
	s_addc_u32 s5, s63, 0
	s_mov_b32 s6, m0
	s_mov_b32 m0, s86
	s_nop 0
	global_load_lds_dwordx4 v148, s[4:5]
	s_mov_b32 m0, s6
	s_nop 0
	s_mov_b32 s6, m0
	s_mov_b32 m0, s87
	s_nop 0
	global_load_lds_dwordx4 v150, s[4:5]
	s_mov_b32 m0, s6
	s_waitcnt vmcnt(8)
	s_waitcnt lgkmcnt(0)
	s_barrier
	s_waitcnt lgkmcnt(7)
	v_mfma_i32_16x16x64_i8 v[124:127], v[128:131], v[166:169], v[124:127]
	v_mfma_i32_16x16x64_i8 v[120:123], v[136:139], v[166:169], v[120:123]
	s_waitcnt lgkmcnt(5)
	v_mfma_i32_16x16x64_i8 v[108:111], v[128:131], v[174:177], v[108:111]
	v_mfma_i32_16x16x64_i8 v[104:107], v[136:139], v[174:177], v[104:107]
	s_waitcnt lgkmcnt(3)
	v_mfma_i32_16x16x64_i8 v[92:95], v[128:131], v[182:185], v[92:95]
	v_mfma_i32_16x16x64_i8 v[88:91], v[136:139], v[182:185], v[88:91]
	s_waitcnt lgkmcnt(1)
	v_mfma_i32_16x16x64_i8 v[76:79], v[128:131], v[190:193], v[76:79]
	v_mfma_i32_16x16x64_i8 v[72:75], v[136:139], v[190:193], v[72:75]
	v_mfma_i32_16x16x64_i8 v[124:127], v[132:135], v[170:173], v[124:127]
	v_mfma_i32_16x16x64_i8 v[120:123], v[140:143], v[170:173], v[120:123]
	v_mfma_i32_16x16x64_i8 v[108:111], v[132:135], v[178:181], v[108:111]
	v_mfma_i32_16x16x64_i8 v[104:107], v[140:143], v[178:181], v[104:107]
	v_mfma_i32_16x16x64_i8 v[92:95], v[132:135], v[186:189], v[92:95]
	v_mfma_i32_16x16x64_i8 v[88:91], v[140:143], v[186:189], v[88:91]
	s_waitcnt lgkmcnt(0)
	v_mfma_i32_16x16x64_i8 v[76:79], v[132:135], v[194:197], v[76:79]
	v_mfma_i32_16x16x64_i8 v[72:75], v[140:143], v[194:197], v[72:75]
	v_mfma_i32_16x16x64_i8 v[116:119], v[144:147], v[166:169], v[116:119]
	v_mfma_i32_16x16x64_i8 v[112:115], v[158:161], v[166:169], v[112:115]
	v_mfma_i32_16x16x64_i8 v[100:103], v[144:147], v[174:177], v[100:103]
	v_mfma_i32_16x16x64_i8 v[96:99], v[158:161], v[174:177], v[96:99]
	v_mfma_i32_16x16x64_i8 v[84:87], v[144:147], v[182:185], v[84:87]
	v_mfma_i32_16x16x64_i8 v[80:83], v[158:161], v[182:185], v[80:83]
	v_mfma_i32_16x16x64_i8 v[68:71], v[144:147], v[190:193], v[68:71]
	v_mfma_i32_16x16x64_i8 v[64:67], v[158:161], v[190:193], v[64:67]
	v_mfma_i32_16x16x64_i8 v[116:119], v[154:157], v[170:173], v[116:119]
	v_mfma_i32_16x16x64_i8 v[112:115], v[162:165], v[170:173], v[112:115]
	v_mfma_i32_16x16x64_i8 v[100:103], v[154:157], v[178:181], v[100:103]
	v_mfma_i32_16x16x64_i8 v[96:99], v[162:165], v[178:181], v[96:99]
	v_mfma_i32_16x16x64_i8 v[84:87], v[154:157], v[186:189], v[84:87]
	v_mfma_i32_16x16x64_i8 v[80:83], v[162:165], v[186:189], v[80:83]
	v_mfma_i32_16x16x64_i8 v[68:71], v[154:157], v[194:197], v[68:71]
	v_mfma_i32_16x16x64_i8 v[64:67], v[162:165], v[194:197], v[64:67]
	s_barrier
	ds_read_b128 v[166:169], v153 offset:49152
	ds_read_b128 v[170:173], v153 offset:50176
	ds_read_b128 v[174:177], v153 offset:51200
	ds_read_b128 v[178:181], v153 offset:52224
	ds_read_b128 v[182:185], v153 offset:53248
	ds_read_b128 v[186:189], v153 offset:54272
	ds_read_b128 v[190:193], v153 offset:55296
	ds_read_b128 v[194:197], v153 offset:56320
	s_add_u32 s4, s68, 0x80
	s_addc_u32 s5, s69, 0
	s_mov_b32 s6, m0
	s_mov_b32 m0, s90
	s_nop 0
	global_load_lds_dwordx4 v149, s[4:5]
	s_mov_b32 m0, s6
	s_nop 0
	s_mov_b32 s6, m0
	s_mov_b32 m0, s91
	s_nop 0
	global_load_lds_dwordx4 v151, s[4:5]
	s_mov_b32 m0, s6
	s_add_u32 s4, s68, 0x40080
	s_addc_u32 s5, s69, 0
	s_mov_b32 s6, m0
	s_mov_b32 m0, s94
	s_nop 0
	global_load_lds_dwordx4 v149, s[4:5]
	s_mov_b32 m0, s6
	s_nop 0
	s_mov_b32 s6, m0
	s_mov_b32 m0, s95
	s_nop 0
	global_load_lds_dwordx4 v151, s[4:5]
	s_mov_b32 m0, s6
	s_mov_b32 s4, m0
	s_mov_b32 m0, s92
	s_nop 0
	global_load_lds_dwordx4 v148, s[56:57]
	s_mov_b32 m0, s4
	s_nop 0
	s_mov_b32 s4, m0
	s_mov_b32 m0, s93
	s_nop 0
	global_load_lds_dwordx4 v150, s[56:57]
	s_mov_b32 m0, s4
	s_waitcnt vmcnt(8)
	s_waitcnt lgkmcnt(0)
	s_barrier
	s_waitcnt lgkmcnt(7)
	v_mfma_i32_16x16x64_i8 v[60:63], v[128:131], v[166:169], v[60:63]
	v_mfma_i32_16x16x64_i8 v[56:59], v[136:139], v[166:169], v[56:59]
	s_waitcnt lgkmcnt(5)
	v_mfma_i32_16x16x64_i8 v[44:47], v[128:131], v[174:177], v[44:47]
	v_mfma_i32_16x16x64_i8 v[40:43], v[136:139], v[174:177], v[40:43]
	s_waitcnt lgkmcnt(3)
	v_mfma_i32_16x16x64_i8 v[28:31], v[128:131], v[182:185], v[28:31]
	v_mfma_i32_16x16x64_i8 v[24:27], v[136:139], v[182:185], v[24:27]
	s_waitcnt lgkmcnt(1)
	v_mfma_i32_16x16x64_i8 v[12:15], v[128:131], v[190:193], v[12:15]
	v_mfma_i32_16x16x64_i8 v[8:11], v[136:139], v[190:193], v[8:11]
	v_mfma_i32_16x16x64_i8 v[60:63], v[132:135], v[170:173], v[60:63]
	v_mfma_i32_16x16x64_i8 v[56:59], v[140:143], v[170:173], v[56:59]
	v_mfma_i32_16x16x64_i8 v[44:47], v[132:135], v[178:181], v[44:47]
	v_mfma_i32_16x16x64_i8 v[40:43], v[140:143], v[178:181], v[40:43]
	v_mfma_i32_16x16x64_i8 v[28:31], v[132:135], v[186:189], v[28:31]
	v_mfma_i32_16x16x64_i8 v[24:27], v[140:143], v[186:189], v[24:27]
	s_waitcnt lgkmcnt(0)
	v_mfma_i32_16x16x64_i8 v[12:15], v[132:135], v[194:197], v[12:15]
	v_mfma_i32_16x16x64_i8 v[8:11], v[140:143], v[194:197], v[8:11]
	v_mfma_i32_16x16x64_i8 v[52:55], v[144:147], v[166:169], v[52:55]
	v_mfma_i32_16x16x64_i8 v[48:51], v[158:161], v[166:169], v[48:51]
	v_mfma_i32_16x16x64_i8 v[36:39], v[144:147], v[174:177], v[36:39]
	v_mfma_i32_16x16x64_i8 v[32:35], v[158:161], v[174:177], v[32:35]
	v_mfma_i32_16x16x64_i8 v[20:23], v[144:147], v[182:185], v[20:23]
	v_mfma_i32_16x16x64_i8 v[16:19], v[158:161], v[182:185], v[16:19]
	v_mfma_i32_16x16x64_i8 v[4:7], v[144:147], v[190:193], v[4:7]
	v_mfma_i32_16x16x64_i8 v[0:3], v[158:161], v[190:193], v[0:3]
	v_mfma_i32_16x16x64_i8 v[52:55], v[154:157], v[170:173], v[52:55]
	v_mfma_i32_16x16x64_i8 v[48:51], v[162:165], v[170:173], v[48:51]
	v_mfma_i32_16x16x64_i8 v[36:39], v[154:157], v[178:181], v[36:39]
	v_mfma_i32_16x16x64_i8 v[32:35], v[162:165], v[178:181], v[32:35]
	v_mfma_i32_16x16x64_i8 v[20:23], v[154:157], v[186:189], v[20:23]
	v_mfma_i32_16x16x64_i8 v[16:19], v[162:165], v[186:189], v[16:19]
	v_mfma_i32_16x16x64_i8 v[4:7], v[154:157], v[194:197], v[4:7]
	v_mfma_i32_16x16x64_i8 v[0:3], v[162:165], v[194:197], v[0:3]
	s_barrier
	s_add_i32 s1, s1, 2
	s_add_u32 s73, s73, 0x100
	s_addc_u32 vcc_lo, vcc_lo, 0
	s_add_u32 vcc_hi, vcc_hi, 0x100
	s_addc_u32 s0, s0, 0
	s_add_u32 s44, s44, 0x100
	s_addc_u32 s45, s45, 0
	s_cmp_gt_u32 s1, 13
	.p2align 6

; #define PG8_STAGE(bufoff, gbase, voff) do { _Pragma("unroll") for (int _i = 0; _i < 2; ++_i) glds16_s((gbase), (voff)[_i], ldsb + (unsigned)((bufoff) + _i * 8192)); } while (0)
; #define PG8_LDA(dst, b, h) do { _Pragma("unroll") for (int m = 0; m < 4; ++m) _Pragma("unroll") for (int k = 0; k < 2; ++k) dst[m][k] = *(const LAS h16x8*)(lds + PG8_SA(b, h) + aoff + m * 2048 + k * 1024); } while (0)
; #define PG8_LDB(dst, b, h) do { _Pragma("unroll") for (int n = 0; n < 2; ++n) _Pragma("unroll") for (int k = 0; k < 2; ++k) dst[n][k] = *(const LAS h16x8*)(lds + PG8_SB(b, h) + boff + n * 2048 + k * 1024); } while (0)
; #define PG8_MMA(ai, bj, At, Bt) do { __builtin_amdgcn_s_setprio(1); _Pragma("unroll") for (int m = 0; m < 4; ++m) _Pragma("unroll") for (int n = 0; n < 2; ++n) _Pragma("unroll") for (int k = 0; k < 2; ++k) \
;         acc[ai][bj][m][n] = mma_step<I8>(Bt[n][k], At[m][k], acc[ai][bj][m][n]); __builtin_amdgcn_s_setprio(0); } while (0)
; #define PG8_WAIT_V(n) asm volatile("s_waitcnt vmcnt(" #n ")" ::: "memory")
; #define PG8_WAIT_L(n) asm volatile("s_waitcnt lgkmcnt(" #n ")" ::: "memory")
; #define PG8_BAR __builtin_amdgcn_s_barrier()
; #define PG8_SCHED __builtin_amdgcn_sched_barrier(0)
; template <class Prob, class Epi, bool I8 = false, bool ALIGN_EPI = true, bool SP2 = true>
; __device__ __forceinline__ void gemm_phase(LAS unsigned char* lds, int wave, const Prob& P, const Epi& E) {
;     ...
;             PG8_LDB(B0, 0, 0); PG8_LDB(B1, 0, 1); PG8_SCHED; PG8_LDA(At, 0, 0); PG8_STAGE(PG8_SA(1, 1), a1 + hstepA, voffA);
;             PG8_WAIT_V(8); PG8_WAIT_L(0); PG8_BAR; PG8_MMA(0, 0, At, B0); PG8_MMA(0, 1, At, B1); PG8_BAR; PG8_SCHED;
;             PG8_LDA(At, 0, 1); PG8_STAGE(PG8_SB(0, 0), b2, voffB); PG8_STAGE(PG8_SB(0, 1), b2 + hstepB, voffB); PG8_STAGE(PG8_SA(0, 0), a2, voffA);
;             PG8_WAIT_V(8); PG8_WAIT_L(0); PG8_BAR; PG8_MMA(1, 0, At, B0); PG8_MMA(1, 1, At, B1); PG8_BAR; PG8_SCHED;
.Lpeel_863:
	v_add_u32_e32 v140, 0x10000, v146
	ds_read_b128 v[128:131], v140
	ds_read_b128 v[132:135], v140 offset:1024
	ds_read_b128 v[136:139], v140 offset:2048
	ds_read_b128 v[148:151], v140 offset:3072
	v_add_u32_e32 v140, 0x14000, v146
	ds_read_b128 v[152:155], v140
	ds_read_b128 v[156:159], v140 offset:1024
	ds_read_b128 v[160:163], v140 offset:2048
	ds_read_b128 v[164:167], v140 offset:3072
	s_cmp_eq_u32 s1, 28
	s_cselect_b32 s46, s83, s85
	s_cselect_b32 s47, s27, s86
	s_cselect_b32 s44, s84, s87
	s_cselect_b32 s45, s23, s0
	s_add_u32 s42, s46, 0x80
	s_addc_u32 s43, s47, 0
	ds_read_b128 v[168:171], v147
	ds_read_b128 v[172:175], v147 offset:1024
	ds_read_b128 v[176:179], v147 offset:2048
	ds_read_b128 v[180:183], v147 offset:3072
	ds_read_b128 v[184:187], v147 offset:4096
	ds_read_b128 v[188:191], v147 offset:5120
	ds_read_b128 v[192:195], v147 offset:6144
	ds_read_b128 v[196:199], v147 offset:7168
	s_mov_b32 s4, m0
	s_mov_b32 m0, s75
	s_nop 0
	global_load_lds_dwordx4 v142, s[40:41]
	s_mov_b32 m0, s4
	s_nop 0
	s_mov_b32 s4, m0
	s_mov_b32 m0, s79
	s_nop 0
	global_load_lds_dwordx4 v144, s[40:41]
	s_mov_b32 m0, s4
	s_waitcnt vmcnt(8)
	s_waitcnt lgkmcnt(0)
	s_barrier
	s_waitcnt lgkmcnt(7)
	v_mfma_f32_16x16x32_f16 v[124:127], v[128:131], v[168:171], 0
	v_mfma_f32_16x16x32_f16 v[120:123], v[136:139], v[168:171], 0
	s_waitcnt lgkmcnt(5)
	v_mfma_f32_16x16x32_f16 v[116:119], v[128:131], v[176:179], 0
	v_mfma_f32_16x16x32_f16 v[112:115], v[136:139], v[176:179], 0
	s_waitcnt lgkmcnt(3)
	v_mfma_f32_16x16x32_f16 v[108:111], v[128:131], v[184:187], 0
	v_mfma_f32_16x16x32_f16 v[104:107], v[136:139], v[184:187], 0
	s_waitcnt lgkmcnt(1)
	v_mfma_f32_16x16x32_f16 v[100:103], v[128:131], v[192:195], 0
	v_mfma_f32_16x16x32_f16 v[96:99], v[136:139], v[192:195], 0
	v_mfma_f32_16x16x32_f16 v[124:127], v[132:135], v[172:175], v[124:127]
	v_mfma_f32_16x16x32_f16 v[120:123], v[148:151], v[172:175], v[120:123]
	v_mfma_f32_16x16x32_f16 v[116:119], v[132:135], v[180:183], v[116:119]
	v_mfma_f32_16x16x32_f16 v[112:115], v[148:151], v[180:183], v[112:115]
	v_mfma_f32_16x16x32_f16 v[108:111], v[132:135], v[188:191], v[108:111]
	v_mfma_f32_16x16x32_f16 v[104:107], v[148:151], v[188:191], v[104:107]
	s_waitcnt lgkmcnt(0)
	v_mfma_f32_16x16x32_f16 v[100:103], v[132:135], v[196:199], v[100:103]
	v_mfma_f32_16x16x32_f16 v[96:99], v[148:151], v[196:199], v[96:99]
	v_mfma_f32_16x16x32_f16 v[64:67], v[152:155], v[168:171], 0
	v_mfma_f32_16x16x32_f16 v[56:59], v[160:163], v[168:171], 0
	v_mfma_f32_16x16x32_f16 v[52:55], v[152:155], v[176:179], 0
	v_mfma_f32_16x16x32_f16 v[48:51], v[160:163], v[176:179], 0
	v_mfma_f32_16x16x32_f16 v[44:47], v[152:155], v[184:187], 0
	v_mfma_f32_16x16x32_f16 v[40:43], v[160:163], v[184:187], 0
	v_mfma_f32_16x16x32_f16 v[36:39], v[152:155], v[192:195], 0
	v_mfma_f32_16x16x32_f16 v[32:35], v[160:163], v[192:195], 0
	v_mfma_f32_16x16x32_f16 v[64:67], v[156:159], v[172:175], v[64:67]
	v_mfma_f32_16x16x32_f16 v[56:59], v[164:167], v[172:175], v[56:59]
	v_mfma_f32_16x16x32_f16 v[52:55], v[156:159], v[180:183], v[52:55]
	v_mfma_f32_16x16x32_f16 v[48:51], v[164:167], v[180:183], v[48:51]
	v_mfma_f32_16x16x32_f16 v[44:47], v[156:159], v[188:191], v[44:47]
	v_mfma_f32_16x16x32_f16 v[40:43], v[164:167], v[188:191], v[40:43]
	v_mfma_f32_16x16x32_f16 v[36:39], v[156:159], v[196:199], v[36:39]
	v_mfma_f32_16x16x32_f16 v[32:35], v[164:167], v[196:199], v[32:35]
	s_barrier
	ds_read_b128 v[168:171], v147 offset:16384
	ds_read_b128 v[172:175], v147 offset:17408
	ds_read_b128 v[176:179], v147 offset:18432
	ds_read_b128 v[180:183], v147 offset:19456
	ds_read_b128 v[184:187], v147 offset:20480
	ds_read_b128 v[188:191], v147 offset:21504
	ds_read_b128 v[192:195], v147 offset:22528
	ds_read_b128 v[196:199], v147 offset:23552
	s_mov_b32 s4, m0
	s_mov_b32 m0, s49
	s_nop 0
	global_load_lds_dwordx4 v143, s[44:45]
	s_mov_b32 m0, s4
	s_nop 0
	s_mov_b32 s4, m0
	s_mov_b32 m0, s50
	s_nop 0
	global_load_lds_dwordx4 v145, s[44:45]
	s_mov_b32 m0, s4
	s_add_u32 s4, s44, 0x80000
	s_addc_u32 s5, s45, 0
	s_mov_b32 s6, m0
	s_mov_b32 m0, s51
	s_nop 0
	global_load_lds_dwordx4 v143, s[4:5]
	s_mov_b32 m0, s6
	s_nop 0
	s_mov_b32 s6, m0
	s_mov_b32 m0, s56
	s_nop 0
	global_load_lds_dwordx4 v145, s[4:5]
	s_mov_b32 m0, s6
	s_mov_b32 s4, m0
	s_mov_b32 m0, s48
	s_nop 0
	global_load_lds_dwordx4 v142, s[46:47]
	s_mov_b32 m0, s4
	s_nop 0
	s_mov_b32 s4, m0
	s_mov_b32 m0, s57
	s_nop 0
	global_load_lds_dwordx4 v144, s[46:47]
	s_mov_b32 m0, s4
	s_waitcnt vmcnt(8)
	s_waitcnt lgkmcnt(0)
	s_barrier
	s_waitcnt lgkmcnt(7)
	v_mfma_f32_16x16x32_f16 v[92:95], v[128:131], v[168:171], 0
	v_mfma_f32_16x16x32_f16 v[88:91], v[136:139], v[168:171], 0
	s_waitcnt lgkmcnt(5)
	v_mfma_f32_16x16x32_f16 v[84:87], v[128:131], v[176:179], 0
	v_mfma_f32_16x16x32_f16 v[80:83], v[136:139], v[176:179], 0
	s_waitcnt lgkmcnt(3)
	v_mfma_f32_16x16x32_f16 v[76:79], v[128:131], v[184:187], 0
	v_mfma_f32_16x16x32_f16 v[72:75], v[136:139], v[184:187], 0
	s_waitcnt lgkmcnt(1)
	v_mfma_f32_16x16x32_f16 v[68:71], v[128:131], v[192:195], 0
	v_mfma_f32_16x16x32_f16 v[60:63], v[136:139], v[192:195], 0
	v_mfma_f32_16x16x32_f16 v[92:95], v[132:135], v[172:175], v[92:95]
	v_mfma_f32_16x16x32_f16 v[88:91], v[148:151], v[172:175], v[88:91]
	v_mfma_f32_16x16x32_f16 v[84:87], v[132:135], v[180:183], v[84:87]
	v_mfma_f32_16x16x32_f16 v[80:83], v[148:151], v[180:183], v[80:83]
	v_mfma_f32_16x16x32_f16 v[76:79], v[132:135], v[188:191], v[76:79]
	v_mfma_f32_16x16x32_f16 v[72:75], v[148:151], v[188:191], v[72:75]
	s_waitcnt lgkmcnt(0)
	v_mfma_f32_16x16x32_f16 v[68:71], v[132:135], v[196:199], v[68:71]
	v_mfma_f32_16x16x32_f16 v[60:63], v[148:151], v[196:199], v[60:63]
	v_mfma_f32_16x16x32_f16 v[28:31], v[152:155], v[168:171], 0
	v_mfma_f32_16x16x32_f16 v[24:27], v[160:163], v[168:171], 0
	v_mfma_f32_16x16x32_f16 v[20:23], v[152:155], v[176:179], 0
	v_mfma_f32_16x16x32_f16 v[16:19], v[160:163], v[176:179], 0
	v_mfma_f32_16x16x32_f16 v[12:15], v[152:155], v[184:187], 0
	v_mfma_f32_16x16x32_f16 v[8:11], v[160:163], v[184:187], 0
	v_mfma_f32_16x16x32_f16 v[4:7], v[152:155], v[192:195], 0
	v_mfma_f32_16x16x32_f16 v[0:3], v[160:163], v[192:195], 0
	v_mfma_f32_16x16x32_f16 v[28:31], v[156:159], v[172:175], v[28:31]
	v_mfma_f32_16x16x32_f16 v[24:27], v[164:167], v[172:175], v[24:27]
	v_mfma_f32_16x16x32_f16 v[20:23], v[156:159], v[180:183], v[20:23]
	v_mfma_f32_16x16x32_f16 v[16:19], v[164:167], v[180:183], v[16:19]
	v_mfma_f32_16x16x32_f16 v[12:15], v[156:159], v[188:191], v[12:15]
	v_mfma_f32_16x16x32_f16 v[8:11], v[164:167], v[188:191], v[8:11]
	v_mfma_f32_16x16x32_f16 v[4:7], v[156:159], v[196:199], v[4:7]
	v_mfma_f32_16x16x32_f16 v[0:3], v[164:167], v[196:199], v[0:3]
	s_barrier
; #define PG8_STAGE(bufoff, gbase, voff) do { _Pragma("unroll") for (int _i = 0; _i < 2; ++_i) glds16_s((gbase), (voff)[_i], ldsb + (unsigned)((bufoff) + _i * 8192)); } while (0)
; #define PG8_LDA(dst, b, h) do { _Pragma("unroll") for (int m = 0; m < 4; ++m) _Pragma("unroll") for (int k = 0; k < 2; ++k) dst[m][k] = *(const LAS h16x8*)(lds + PG8_SA(b, h) + aoff + m * 2048 + k * 1024); } while (0)
; #define PG8_LDB(dst, b, h) do { _Pragma("unroll") for (int n = 0; n < 2; ++n) _Pragma("unroll") for (int k = 0; k < 2; ++k) dst[n][k] = *(const LAS h16x8*)(lds + PG8_SB(b, h) + boff + n * 2048 + k * 1024); } while (0)
; #define PG8_MMA(ai, bj, At, Bt) do { __builtin_amdgcn_s_setprio(1); _Pragma("unroll") for (int m = 0; m < 4; ++m) _Pragma("unroll") for (int n = 0; n < 2; ++n) _Pragma("unroll") for (int k = 0; k < 2; ++k) \
;         acc[ai][bj][m][n] = mma_step<I8>(Bt[n][k], At[m][k], acc[ai][bj][m][n]); __builtin_amdgcn_s_setprio(0); } while (0)
; #define PG8_WAIT_V(n) asm volatile("s_waitcnt vmcnt(" #n ")" ::: "memory")
; #define PG8_WAIT_L(n) asm volatile("s_waitcnt lgkmcnt(" #n ")" ::: "memory")
; #define PG8_BAR __builtin_amdgcn_s_barrier()
; #define PG8_SCHED __builtin_amdgcn_sched_barrier(0)
; template <class Prob, class Epi, bool I8 = false, bool ALIGN_EPI = true, bool SP2 = true>
; __device__ __forceinline__ void gemm_phase(LAS unsigned char* lds, int wave, const Prob& P, const Epi& E) {
;     ...
;         for (int t = 0; t < nt; t += 2) {
;             const bool last = (t == nt - 2);
;             const char* a1 = cA + (size_t)(t + 1) * kstep;
;             const char* a2 = last ? nA : cA + (size_t)(t + 2) * kstep; const char* b2 = last ? nB : cB + (size_t)(t + 2) * kstep;
;             const char* a3 = a2 + kstep; const char* b3 = b2 + kstep;
;     ...
;             PG8_LDB(B0, 1, 0); PG8_LDB(B1, 1, 1); PG8_SCHED; PG8_LDA(At, 1, 0); PG8_STAGE(PG8_SA(0, 1), a2 + hstepA, voffA);
;             PG8_WAIT_V(8); PG8_WAIT_L(0); PG8_BAR; PG8_MMA(0, 0, At, B0); PG8_MMA(0, 1, At, B1); PG8_BAR; PG8_SCHED;
;             PG8_LDA(At, 1, 1); PG8_STAGE(PG8_SB(1, 0), b3, voffB); PG8_STAGE(PG8_SB(1, 1), b3 + hstepB, voffB); PG8_STAGE(PG8_SA(1, 0), a3, voffA);
;             PG8_WAIT_V(8); PG8_WAIT_L(0); PG8_BAR; PG8_MMA(1, 0, At, B0); PG8_MMA(1, 1, At, B1); PG8_BAR; PG8_SCHED;
	v_add_u32_e32 v140, 0x18000, v146
	ds_read_b128 v[128:131], v140
	ds_read_b128 v[132:135], v140 offset:1024
	ds_read_b128 v[136:139], v140 offset:2048
	ds_read_b128 v[148:151], v140 offset:3072
	v_add_u32_e32 v140, 0x1c000, v146
	ds_read_b128 v[152:155], v140
	ds_read_b128 v[156:159], v140 offset:1024
	ds_read_b128 v[160:163], v140 offset:2048
	ds_read_b128 v[164:167], v140 offset:3072
	ds_read_b128 v[168:171], v147 offset:32768
	ds_read_b128 v[172:175], v147 offset:33792
	ds_read_b128 v[176:179], v147 offset:34816
	ds_read_b128 v[180:183], v147 offset:35840
	ds_read_b128 v[184:187], v147 offset:36864
	ds_read_b128 v[188:191], v147 offset:37888
	ds_read_b128 v[192:195], v147 offset:38912
	ds_read_b128 v[196:199], v147 offset:39936
	s_add_u32 s4, s46, 0x80000
	s_addc_u32 s5, s47, 0
	s_mov_b32 s6, m0
	s_mov_b32 m0, s60
	s_nop 0
	global_load_lds_dwordx4 v142, s[4:5]
	s_mov_b32 m0, s6
	s_nop 0
	s_mov_b32 s6, m0
	s_mov_b32 m0, s61
	s_nop 0
	global_load_lds_dwordx4 v144, s[4:5]
	s_mov_b32 m0, s6
	s_waitcnt vmcnt(8)
	s_waitcnt lgkmcnt(0)
	s_barrier
	s_waitcnt lgkmcnt(7)
	v_mfma_f32_16x16x32_f16 v[124:127], v[128:131], v[168:171], v[124:127]
	v_mfma_f32_16x16x32_f16 v[120:123], v[136:139], v[168:171], v[120:123]
	s_waitcnt lgkmcnt(5)
	v_mfma_f32_16x16x32_f16 v[116:119], v[128:131], v[176:179], v[116:119]
	v_mfma_f32_16x16x32_f16 v[112:115], v[136:139], v[176:179], v[112:115]
	s_waitcnt lgkmcnt(3)
	v_mfma_f32_16x16x32_f16 v[108:111], v[128:131], v[184:187], v[108:111]
	v_mfma_f32_16x16x32_f16 v[104:107], v[136:139], v[184:187], v[104:107]
	s_waitcnt lgkmcnt(1)
	v_mfma_f32_16x16x32_f16 v[100:103], v[128:131], v[192:195], v[100:103]
	v_mfma_f32_16x16x32_f16 v[96:99], v[136:139], v[192:195], v[96:99]
	v_mfma_f32_16x16x32_f16 v[124:127], v[132:135], v[172:175], v[124:127]
	v_mfma_f32_16x16x32_f16 v[120:123], v[148:151], v[172:175], v[120:123]
	v_mfma_f32_16x16x32_f16 v[116:119], v[132:135], v[180:183], v[116:119]
	v_mfma_f32_16x16x32_f16 v[112:115], v[148:151], v[180:183], v[112:115]
	v_mfma_f32_16x16x32_f16 v[108:111], v[132:135], v[188:191], v[108:111]
	v_mfma_f32_16x16x32_f16 v[104:107], v[148:151], v[188:191], v[104:107]
	s_waitcnt lgkmcnt(0)
	v_mfma_f32_16x16x32_f16 v[100:103], v[132:135], v[196:199], v[100:103]
	v_mfma_f32_16x16x32_f16 v[96:99], v[148:151], v[196:199], v[96:99]
	v_mfma_f32_16x16x32_f16 v[64:67], v[152:155], v[168:171], v[64:67]
	v_mfma_f32_16x16x32_f16 v[56:59], v[160:163], v[168:171], v[56:59]
	v_mfma_f32_16x16x32_f16 v[52:55], v[152:155], v[176:179], v[52:55]
	v_mfma_f32_16x16x32_f16 v[48:51], v[160:163], v[176:179], v[48:51]
	v_mfma_f32_16x16x32_f16 v[44:47], v[152:155], v[184:187], v[44:47]
	v_mfma_f32_16x16x32_f16 v[40:43], v[160:163], v[184:187], v[40:43]
	v_mfma_f32_16x16x32_f16 v[36:39], v[152:155], v[192:195], v[36:39]
	v_mfma_f32_16x16x32_f16 v[32:35], v[160:163], v[192:195], v[32:35]
	v_mfma_f32_16x16x32_f16 v[64:67], v[156:159], v[172:175], v[64:67]
	v_mfma_f32_16x16x32_f16 v[56:59], v[164:167], v[172:175], v[56:59]
	v_mfma_f32_16x16x32_f16 v[52:55], v[156:159], v[180:183], v[52:55]
	v_mfma_f32_16x16x32_f16 v[48:51], v[164:167], v[180:183], v[48:51]
	v_mfma_f32_16x16x32_f16 v[44:47], v[156:159], v[188:191], v[44:47]
	v_mfma_f32_16x16x32_f16 v[40:43], v[164:167], v[188:191], v[40:43]
	v_mfma_f32_16x16x32_f16 v[36:39], v[156:159], v[196:199], v[36:39]
	v_mfma_f32_16x16x32_f16 v[32:35], v[164:167], v[196:199], v[32:35]
	s_barrier
	ds_read_b128 v[168:171], v147 offset:49152
	ds_read_b128 v[172:175], v147 offset:50176
	ds_read_b128 v[176:179], v147 offset:51200
	ds_read_b128 v[180:183], v147 offset:52224
	ds_read_b128 v[184:187], v147 offset:53248
	ds_read_b128 v[188:191], v147 offset:54272
	ds_read_b128 v[192:195], v147 offset:55296
	ds_read_b128 v[196:199], v147 offset:56320
	s_add_u32 s4, s44, 0x80
	s_addc_u32 s5, s45, 0
	s_mov_b32 s6, m0
	s_mov_b32 m0, s64
	s_nop 0
	global_load_lds_dwordx4 v143, s[4:5]
	s_mov_b32 m0, s6
	s_nop 0
	s_mov_b32 s6, m0
	s_mov_b32 m0, s68
	s_nop 0
	global_load_lds_dwordx4 v145, s[4:5]
	s_mov_b32 m0, s6
	s_add_u32 s4, s44, 0x80080
	s_addc_u32 s5, s45, 0
	s_mov_b32 s6, m0
	s_mov_b32 m0, s73
	s_nop 0
	global_load_lds_dwordx4 v143, s[4:5]
	s_mov_b32 m0, s6
	s_nop 0
	s_mov_b32 s6, m0
	s_mov_b32 m0, s74
	s_nop 0
	global_load_lds_dwordx4 v145, s[4:5]
	s_mov_b32 m0, s6
	s_mov_b32 s4, m0
	s_mov_b32 m0, s69
	s_nop 0
	global_load_lds_dwordx4 v142, s[42:43]
	s_mov_b32 m0, s4
	s_nop 0
	s_mov_b32 s4, m0
	s_mov_b32 m0, s72
	s_nop 0
	global_load_lds_dwordx4 v144, s[42:43]
	s_mov_b32 m0, s4
	s_waitcnt vmcnt(8)
	s_waitcnt lgkmcnt(0)
	s_barrier
	s_waitcnt lgkmcnt(7)
	v_mfma_f32_16x16x32_f16 v[92:95], v[128:131], v[168:171], v[92:95]
	v_mfma_f32_16x16x32_f16 v[88:91], v[136:139], v[168:171], v[88:91]
	s_waitcnt lgkmcnt(5)
	v_mfma_f32_16x16x32_f16 v[84:87], v[128:131], v[176:179], v[84:87]
	v_mfma_f32_16x16x32_f16 v[80:83], v[136:139], v[176:179], v[80:83]
	s_waitcnt lgkmcnt(3)
	v_mfma_f32_16x16x32_f16 v[76:79], v[128:131], v[184:187], v[76:79]
	v_mfma_f32_16x16x32_f16 v[72:75], v[136:139], v[184:187], v[72:75]
	s_waitcnt lgkmcnt(1)
	v_mfma_f32_16x16x32_f16 v[68:71], v[128:131], v[192:195], v[68:71]
	v_mfma_f32_16x16x32_f16 v[60:63], v[136:139], v[192:195], v[60:63]
	v_mfma_f32_16x16x32_f16 v[92:95], v[132:135], v[172:175], v[92:95]
	v_mfma_f32_16x16x32_f16 v[88:91], v[148:151], v[172:175], v[88:91]
	v_mfma_f32_16x16x32_f16 v[84:87], v[132:135], v[180:183], v[84:87]
	v_mfma_f32_16x16x32_f16 v[80:83], v[148:151], v[180:183], v[80:83]
	v_mfma_f32_16x16x32_f16 v[76:79], v[132:135], v[188:191], v[76:79]
	v_mfma_f32_16x16x32_f16 v[72:75], v[148:151], v[188:191], v[72:75]
	s_waitcnt lgkmcnt(0)
	v_mfma_f32_16x16x32_f16 v[68:71], v[132:135], v[196:199], v[68:71]
	v_mfma_f32_16x16x32_f16 v[60:63], v[148:151], v[196:199], v[60:63]
	v_mfma_f32_16x16x32_f16 v[28:31], v[152:155], v[168:171], v[28:31]
	v_mfma_f32_16x16x32_f16 v[24:27], v[160:163], v[168:171], v[24:27]
	v_mfma_f32_16x16x32_f16 v[20:23], v[152:155], v[176:179], v[20:23]
	v_mfma_f32_16x16x32_f16 v[16:19], v[160:163], v[176:179], v[16:19]
	v_mfma_f32_16x16x32_f16 v[12:15], v[152:155], v[184:187], v[12:15]
	v_mfma_f32_16x16x32_f16 v[8:11], v[160:163], v[184:187], v[8:11]
	v_mfma_f32_16x16x32_f16 v[4:7], v[152:155], v[192:195], v[4:7]
	v_mfma_f32_16x16x32_f16 v[0:3], v[160:163], v[192:195], v[0:3]
	v_mfma_f32_16x16x32_f16 v[28:31], v[156:159], v[172:175], v[28:31]
	v_mfma_f32_16x16x32_f16 v[24:27], v[164:167], v[172:175], v[24:27]
	v_mfma_f32_16x16x32_f16 v[20:23], v[156:159], v[180:183], v[20:23]
	v_mfma_f32_16x16x32_f16 v[16:19], v[164:167], v[180:183], v[16:19]
	v_mfma_f32_16x16x32_f16 v[12:15], v[156:159], v[188:191], v[12:15]
	v_mfma_f32_16x16x32_f16 v[8:11], v[164:167], v[188:191], v[8:11]
	v_mfma_f32_16x16x32_f16 v[4:7], v[156:159], v[196:199], v[4:7]
	v_mfma_f32_16x16x32_f16 v[0:3], v[164:167], v[196:199], v[0:3]
	s_barrier
	s_add_i32 s1, s1, 2
	s_add_u32 s85, s85, 0x100
	s_addc_u32 s86, s86, 0
	s_add_u32 s87, s87, 0x100
	s_addc_u32 s0, s0, 0
	s_add_u32 s40, s40, 0x100
	s_addc_u32 s41, s41, 0
	s_cmp_gt_u32 s1, 29
	.p2align 6

; #define PG8_STAGE(bufoff, gbase, voff) do { _Pragma("unroll") for (int _i = 0; _i < 2; ++_i) glds16_s((gbase), (voff)[_i], ldsb + (unsigned)((bufoff) + _i * 8192)); } while (0)
; #define PG8_LDA(dst, b, h) do { _Pragma("unroll") for (int m = 0; m < 4; ++m) _Pragma("unroll") for (int k = 0; k < 2; ++k) dst[m][k] = *(const LAS h16x8*)(lds + PG8_SA(b, h) + aoff + m * 2048 + k * 1024); } while (0)
; #define PG8_LDB(dst, b, h) do { _Pragma("unroll") for (int n = 0; n < 2; ++n) _Pragma("unroll") for (int k = 0; k < 2; ++k) dst[n][k] = *(const LAS h16x8*)(lds + PG8_SB(b, h) + boff + n * 2048 + k * 1024); } while (0)
; #define PG8_MMA(ai, bj, At, Bt) do { __builtin_amdgcn_s_setprio(1); _Pragma("unroll") for (int m = 0; m < 4; ++m) _Pragma("unroll") for (int n = 0; n < 2; ++n) _Pragma("unroll") for (int k = 0; k < 2; ++k) \
;         acc[ai][bj][m][n] = mma_step<I8>(Bt[n][k], At[m][k], acc[ai][bj][m][n]); __builtin_amdgcn_s_setprio(0); } while (0)
; #define PG8_WAIT_V(n) asm volatile("s_waitcnt vmcnt(" #n ")" ::: "memory")
; #define PG8_WAIT_L(n) asm volatile("s_waitcnt lgkmcnt(" #n ")" ::: "memory")
; #define PG8_BAR __builtin_amdgcn_s_barrier()
; #define PG8_SCHED __builtin_amdgcn_sched_barrier(0)
;     __device__ unsigned a_rowoff(int R) const { const int r = upmap ? (128 * (R >> 6) + 8 * (R & 15) + ((R >> 4) & 3)) : R; return (unsigned)r * (unsigned)lda * 2u; }
; template <class Prob, class Epi, bool I8 = false, bool ALIGN_EPI = true, bool SP2 = true>
; __device__ __forceinline__ void gemm_phase(LAS unsigned char* lds, int wave, const Prob& P, const Epi& E) {
;     ...
;             PG8_LDB(B0, 0, 0); PG8_LDB(B1, 0, 1); PG8_SCHED; PG8_LDA(At, 0, 0); PG8_STAGE(PG8_SA(1, 1), a1 + hstepA, voffA);
;             PG8_WAIT_V(8); PG8_WAIT_L(0); PG8_BAR; PG8_MMA(0, 0, At, B0); PG8_MMA(0, 1, At, B1); PG8_BAR; PG8_SCHED;
;             PG8_LDA(At, 0, 1); PG8_STAGE(PG8_SB(0, 0), b2, voffB); PG8_STAGE(PG8_SB(0, 1), b2 + hstepB, voffB); PG8_STAGE(PG8_SA(0, 0), a2, voffA);
;             PG8_WAIT_V(8); PG8_WAIT_L(0); PG8_BAR; PG8_MMA(1, 0, At, B0); PG8_MMA(1, 1, At, B1); PG8_BAR; PG8_SCHED;
;     __device__ unsigned a_rowoff(int R) const { return (unsigned)(64 * R + 65 * (R & 1)) * (unsigned)lda * 2u; }
;     __device__ unsigned b_rowoff(int R) const { return (unsigned)R * (unsigned)ldb * 2u; }
;     __device__ size_t a_hstep() const { return (size_t)64 * 128 * lda * 2; }
.Lpeel_995:
	v_add_u32_e32 v128, 0x10000, v133
	ds_read_b128 v[136:139], v128
	ds_read_b128 v[140:143], v128 offset:1024
	ds_read_b128 v[144:147], v128 offset:2048
	ds_read_b128 v[148:151], v128 offset:3072
	v_add_u32_e32 v128, 0x14000, v133
	ds_read_b128 v[152:155], v128
	ds_read_b128 v[156:159], v128 offset:1024
	ds_read_b128 v[160:163], v128 offset:2048
	ds_read_b128 v[164:167], v128 offset:3072
	s_cmp_eq_u32 s1, 12
	s_cselect_b32 s60, s89, s91
	s_cselect_b32 s61, s29, s92
	s_cselect_b32 s56, s90, s93
	s_cselect_b32 s57, s23, s0
	s_add_u32 s50, s60, 0x80
	s_addc_u32 s51, s61, 0
	ds_read_b128 v[168:171], v134
	ds_read_b128 v[172:175], v134 offset:1024
	ds_read_b128 v[176:179], v134 offset:2048
	ds_read_b128 v[180:183], v134 offset:3072
	ds_read_b128 v[184:187], v134 offset:4096
	ds_read_b128 v[188:191], v134 offset:5120
	ds_read_b128 v[192:195], v134 offset:6144
	ds_read_b128 v[196:199], v134 offset:7168
	s_mov_b32 s4, m0
	s_mov_b32 m0, s84
	s_nop 0
	global_load_lds_dwordx4 v129, s[44:45]
	s_mov_b32 m0, s4
	s_nop 0
	s_mov_b32 s4, m0
	s_mov_b32 m0, s85
	s_nop 0
	global_load_lds_dwordx4 v131, s[44:45]
	s_mov_b32 m0, s4
	s_waitcnt vmcnt(8)
	s_waitcnt lgkmcnt(0)
	s_barrier
	s_waitcnt lgkmcnt(7)
	v_mfma_i32_16x16x64_i8 v[16:19], v[136:139], v[168:171], 0
	v_mfma_i32_16x16x64_i8 v[20:23], v[144:147], v[168:171], 0
	s_waitcnt lgkmcnt(5)
	v_mfma_i32_16x16x64_i8 v[48:51], v[136:139], v[176:179], 0
	v_mfma_i32_16x16x64_i8 v[52:55], v[144:147], v[176:179], 0
	s_waitcnt lgkmcnt(3)
	v_mfma_i32_16x16x64_i8 v[72:75], v[136:139], v[184:187], 0
	v_mfma_i32_16x16x64_i8 v[76:79], v[144:147], v[184:187], 0
	s_waitcnt lgkmcnt(1)
	v_mfma_i32_16x16x64_i8 v[96:99], v[136:139], v[192:195], 0
	v_mfma_i32_16x16x64_i8 v[100:103], v[144:147], v[192:195], 0
	v_mfma_i32_16x16x64_i8 v[16:19], v[140:143], v[172:175], v[16:19]
	v_mfma_i32_16x16x64_i8 v[20:23], v[148:151], v[172:175], v[20:23]
	v_mfma_i32_16x16x64_i8 v[48:51], v[140:143], v[180:183], v[48:51]
	v_mfma_i32_16x16x64_i8 v[52:55], v[148:151], v[180:183], v[52:55]
	v_mfma_i32_16x16x64_i8 v[72:75], v[140:143], v[188:191], v[72:75]
	v_mfma_i32_16x16x64_i8 v[76:79], v[148:151], v[188:191], v[76:79]
	s_waitcnt lgkmcnt(0)
	v_mfma_i32_16x16x64_i8 v[96:99], v[140:143], v[196:199], v[96:99]
	v_mfma_i32_16x16x64_i8 v[100:103], v[148:151], v[196:199], v[100:103]
	v_mfma_i32_16x16x64_i8 v[24:27], v[152:155], v[168:171], 0
	v_mfma_i32_16x16x64_i8 v[28:31], v[160:163], v[168:171], 0
	v_mfma_i32_16x16x64_i8 v[56:59], v[152:155], v[176:179], 0
	v_mfma_i32_16x16x64_i8 v[60:63], v[160:163], v[176:179], 0
	v_mfma_i32_16x16x64_i8 v[80:83], v[152:155], v[184:187], 0
	v_mfma_i32_16x16x64_i8 v[84:87], v[160:163], v[184:187], 0
	v_mfma_i32_16x16x64_i8 v[104:107], v[152:155], v[192:195], 0
	v_mfma_i32_16x16x64_i8 v[108:111], v[160:163], v[192:195], 0
	v_mfma_i32_16x16x64_i8 v[24:27], v[156:159], v[172:175], v[24:27]
	v_mfma_i32_16x16x64_i8 v[28:31], v[164:167], v[172:175], v[28:31]
	v_mfma_i32_16x16x64_i8 v[56:59], v[156:159], v[180:183], v[56:59]
	v_mfma_i32_16x16x64_i8 v[60:63], v[164:167], v[180:183], v[60:63]
	v_mfma_i32_16x16x64_i8 v[80:83], v[156:159], v[188:191], v[80:83]
	v_mfma_i32_16x16x64_i8 v[84:87], v[164:167], v[188:191], v[84:87]
	v_mfma_i32_16x16x64_i8 v[104:107], v[156:159], v[196:199], v[104:107]
	v_mfma_i32_16x16x64_i8 v[108:111], v[164:167], v[196:199], v[108:111]
	s_barrier
	ds_read_b128 v[168:171], v134 offset:16384
	ds_read_b128 v[172:175], v134 offset:17408
	ds_read_b128 v[176:179], v134 offset:18432
	ds_read_b128 v[180:183], v134 offset:19456
	ds_read_b128 v[184:187], v134 offset:20480
	ds_read_b128 v[188:191], v134 offset:21504
	ds_read_b128 v[192:195], v134 offset:22528
	ds_read_b128 v[196:199], v134 offset:23552
	s_mov_b32 s4, m0
	s_mov_b32 m0, s62
	s_nop 0
	global_load_lds_dwordx4 v130, s[56:57]
	s_mov_b32 m0, s4
	s_nop 0
	s_mov_b32 s4, m0
	s_mov_b32 m0, s63
	s_nop 0
	global_load_lds_dwordx4 v132, s[56:57]
	s_mov_b32 m0, s4
	s_add_u32 s4, s56, 0x40000
	s_addc_u32 s5, s57, 0
	s_mov_b32 s6, m0
	s_mov_b32 m0, s64
	s_nop 0
	global_load_lds_dwordx4 v130, s[4:5]
	s_mov_b32 m0, s6
	s_nop 0
	s_mov_b32 s6, m0
	s_mov_b32 m0, s68
	s_nop 0
	global_load_lds_dwordx4 v132, s[4:5]
	s_mov_b32 m0, s6
	s_mov_b32 s4, m0
	s_mov_b32 m0, s2
	s_nop 0
	global_load_lds_dwordx4 v129, s[60:61]
	s_mov_b32 m0, s4
	s_nop 0
	s_mov_b32 s4, m0
	s_mov_b32 m0, s69
	s_nop 0
	global_load_lds_dwordx4 v131, s[60:61]
	s_mov_b32 m0, s4
	s_waitcnt vmcnt(8)
	s_waitcnt lgkmcnt(0)
	s_barrier
	s_waitcnt lgkmcnt(7)
	v_mfma_i32_16x16x64_i8 v[124:127], v[136:139], v[168:171], 0
	v_mfma_i32_16x16x64_i8 v[120:123], v[144:147], v[168:171], 0
	s_waitcnt lgkmcnt(5)
	v_mfma_i32_16x16x64_i8 v[92:95], v[136:139], v[176:179], 0
	v_mfma_i32_16x16x64_i8 v[88:91], v[144:147], v[176:179], 0
	s_waitcnt lgkmcnt(3)
	v_mfma_i32_16x16x64_i8 v[44:47], v[136:139], v[184:187], 0
	v_mfma_i32_16x16x64_i8 v[40:43], v[144:147], v[184:187], 0
	s_waitcnt lgkmcnt(1)
	v_mfma_i32_16x16x64_i8 v[12:15], v[136:139], v[192:195], 0
	v_mfma_i32_16x16x64_i8 v[8:11], v[144:147], v[192:195], 0
	v_mfma_i32_16x16x64_i8 v[124:127], v[140:143], v[172:175], v[124:127]
	v_mfma_i32_16x16x64_i8 v[120:123], v[148:151], v[172:175], v[120:123]
	v_mfma_i32_16x16x64_i8 v[92:95], v[140:143], v[180:183], v[92:95]
	v_mfma_i32_16x16x64_i8 v[88:91], v[148:151], v[180:183], v[88:91]
	v_mfma_i32_16x16x64_i8 v[44:47], v[140:143], v[188:191], v[44:47]
	v_mfma_i32_16x16x64_i8 v[40:43], v[148:151], v[188:191], v[40:43]
	s_waitcnt lgkmcnt(0)
	v_mfma_i32_16x16x64_i8 v[12:15], v[140:143], v[196:199], v[12:15]
	v_mfma_i32_16x16x64_i8 v[8:11], v[148:151], v[196:199], v[8:11]
	v_mfma_i32_16x16x64_i8 v[116:119], v[152:155], v[168:171], 0
	v_mfma_i32_16x16x64_i8 v[112:115], v[160:163], v[168:171], 0
	v_mfma_i32_16x16x64_i8 v[68:71], v[152:155], v[176:179], 0
	v_mfma_i32_16x16x64_i8 v[64:67], v[160:163], v[176:179], 0
	v_mfma_i32_16x16x64_i8 v[36:39], v[152:155], v[184:187], 0
	v_mfma_i32_16x16x64_i8 v[32:35], v[160:163], v[184:187], 0
	v_mfma_i32_16x16x64_i8 v[4:7], v[152:155], v[192:195], 0
	v_mfma_i32_16x16x64_i8 v[0:3], v[160:163], v[192:195], 0
	v_mfma_i32_16x16x64_i8 v[116:119], v[156:159], v[172:175], v[116:119]
	v_mfma_i32_16x16x64_i8 v[112:115], v[164:167], v[172:175], v[112:115]
	v_mfma_i32_16x16x64_i8 v[68:71], v[156:159], v[180:183], v[68:71]
	v_mfma_i32_16x16x64_i8 v[64:67], v[164:167], v[180:183], v[64:67]
	v_mfma_i32_16x16x64_i8 v[36:39], v[156:159], v[188:191], v[36:39]
	v_mfma_i32_16x16x64_i8 v[32:35], v[164:167], v[188:191], v[32:35]
	v_mfma_i32_16x16x64_i8 v[4:7], v[156:159], v[196:199], v[4:7]
	v_mfma_i32_16x16x64_i8 v[0:3], v[164:167], v[196:199], v[0:3]
	s_barrier
; #define PG8_STAGE(bufoff, gbase, voff) do { _Pragma("unroll") for (int _i = 0; _i < 2; ++_i) glds16_s((gbase), (voff)[_i], ldsb + (unsigned)((bufoff) + _i * 8192)); } while (0)
; #define PG8_LDA(dst, b, h) do { _Pragma("unroll") for (int m = 0; m < 4; ++m) _Pragma("unroll") for (int k = 0; k < 2; ++k) dst[m][k] = *(const LAS h16x8*)(lds + PG8_SA(b, h) + aoff + m * 2048 + k * 1024); } while (0)
; #define PG8_LDB(dst, b, h) do { _Pragma("unroll") for (int n = 0; n < 2; ++n) _Pragma("unroll") for (int k = 0; k < 2; ++k) dst[n][k] = *(const LAS h16x8*)(lds + PG8_SB(b, h) + boff + n * 2048 + k * 1024); } while (0)
; #define PG8_MMA(ai, bj, At, Bt) do { __builtin_amdgcn_s_setprio(1); _Pragma("unroll") for (int m = 0; m < 4; ++m) _Pragma("unroll") for (int n = 0; n < 2; ++n) _Pragma("unroll") for (int k = 0; k < 2; ++k) \
;         acc[ai][bj][m][n] = mma_step<I8>(Bt[n][k], At[m][k], acc[ai][bj][m][n]); __builtin_amdgcn_s_setprio(0); } while (0)
; #define PG8_WAIT_V(n) asm volatile("s_waitcnt vmcnt(" #n ")" ::: "memory")
; #define PG8_WAIT_L(n) asm volatile("s_waitcnt lgkmcnt(" #n ")" ::: "memory")
; #define PG8_BAR __builtin_amdgcn_s_barrier()
; #define PG8_SCHED __builtin_amdgcn_sched_barrier(0)
; template <class Prob, class Epi, bool I8 = false, bool ALIGN_EPI = true, bool SP2 = true>
; __device__ __forceinline__ void gemm_phase(LAS unsigned char* lds, int wave, const Prob& P, const Epi& E) {
;     ...
;         for (int t = 0; t < nt; t += 2) {
;             const bool last = (t == nt - 2);
;             const char* a1 = cA + (size_t)(t + 1) * kstep;
;             const char* a2 = last ? nA : cA + (size_t)(t + 2) * kstep; const char* b2 = last ? nB : cB + (size_t)(t + 2) * kstep;
;             const char* a3 = a2 + kstep; const char* b3 = b2 + kstep;
;     ...
;             PG8_LDB(B0, 1, 0); PG8_LDB(B1, 1, 1); PG8_SCHED; PG8_LDA(At, 1, 0); PG8_STAGE(PG8_SA(0, 1), a2 + hstepA, voffA);
;             PG8_WAIT_V(8); PG8_WAIT_L(0); PG8_BAR; PG8_MMA(0, 0, At, B0); PG8_MMA(0, 1, At, B1); PG8_BAR; PG8_SCHED;
;             PG8_LDA(At, 1, 1); PG8_STAGE(PG8_SB(1, 0), b3, voffB); PG8_STAGE(PG8_SB(1, 1), b3 + hstepB, voffB); PG8_STAGE(PG8_SA(1, 0), a3, voffA);
;             PG8_WAIT_V(8); PG8_WAIT_L(0); PG8_BAR; PG8_MMA(1, 0, At, B0); PG8_MMA(1, 1, At, B1); PG8_BAR; PG8_SCHED;
	v_add_u32_e32 v128, 0x18000, v133
	ds_read_b128 v[136:139], v128
	ds_read_b128 v[140:143], v128 offset:1024
	ds_read_b128 v[144:147], v128 offset:2048
	ds_read_b128 v[148:151], v128 offset:3072
	v_add_u32_e32 v128, 0x1c000, v133
	ds_read_b128 v[152:155], v128
	ds_read_b128 v[156:159], v128 offset:1024
	ds_read_b128 v[160:163], v128 offset:2048
	ds_read_b128 v[164:167], v128 offset:3072
	ds_read_b128 v[168:171], v134 offset:32768
	ds_read_b128 v[172:175], v134 offset:33792
	ds_read_b128 v[176:179], v134 offset:34816
	ds_read_b128 v[180:183], v134 offset:35840
	ds_read_b128 v[184:187], v134 offset:36864
	ds_read_b128 v[188:191], v134 offset:37888
	ds_read_b128 v[192:195], v134 offset:38912
	ds_read_b128 v[196:199], v134 offset:39936
	s_add_u32 s4, s60, 0x1000000
	s_addc_u32 s5, s61, 0
	s_mov_b32 s6, m0
	s_mov_b32 m0, s72
	s_nop 0
	global_load_lds_dwordx4 v129, s[4:5]
	s_mov_b32 m0, s6
	s_nop 0
	s_mov_b32 s6, m0
	s_mov_b32 m0, s73
	s_nop 0
	global_load_lds_dwordx4 v131, s[4:5]
	s_mov_b32 m0, s6
	s_waitcnt vmcnt(8)
	s_waitcnt lgkmcnt(0)
	s_barrier
	s_waitcnt lgkmcnt(7)
	v_mfma_i32_16x16x64_i8 v[16:19], v[136:139], v[168:171], v[16:19]
	v_mfma_i32_16x16x64_i8 v[20:23], v[144:147], v[168:171], v[20:23]
	s_waitcnt lgkmcnt(5)
	v_mfma_i32_16x16x64_i8 v[48:51], v[136:139], v[176:179], v[48:51]
	v_mfma_i32_16x16x64_i8 v[52:55], v[144:147], v[176:179], v[52:55]
	s_waitcnt lgkmcnt(3)
	v_mfma_i32_16x16x64_i8 v[72:75], v[136:139], v[184:187], v[72:75]
	v_mfma_i32_16x16x64_i8 v[76:79], v[144:147], v[184:187], v[76:79]
	s_waitcnt lgkmcnt(1)
	v_mfma_i32_16x16x64_i8 v[96:99], v[136:139], v[192:195], v[96:99]
	v_mfma_i32_16x16x64_i8 v[100:103], v[144:147], v[192:195], v[100:103]
	v_mfma_i32_16x16x64_i8 v[16:19], v[140:143], v[172:175], v[16:19]
	v_mfma_i32_16x16x64_i8 v[20:23], v[148:151], v[172:175], v[20:23]
	v_mfma_i32_16x16x64_i8 v[48:51], v[140:143], v[180:183], v[48:51]
	v_mfma_i32_16x16x64_i8 v[52:55], v[148:151], v[180:183], v[52:55]
	v_mfma_i32_16x16x64_i8 v[72:75], v[140:143], v[188:191], v[72:75]
	v_mfma_i32_16x16x64_i8 v[76:79], v[148:151], v[188:191], v[76:79]
	s_waitcnt lgkmcnt(0)
	v_mfma_i32_16x16x64_i8 v[96:99], v[140:143], v[196:199], v[96:99]
	v_mfma_i32_16x16x64_i8 v[100:103], v[148:151], v[196:199], v[100:103]
	v_mfma_i32_16x16x64_i8 v[24:27], v[152:155], v[168:171], v[24:27]
	v_mfma_i32_16x16x64_i8 v[28:31], v[160:163], v[168:171], v[28:31]
	v_mfma_i32_16x16x64_i8 v[56:59], v[152:155], v[176:179], v[56:59]
	v_mfma_i32_16x16x64_i8 v[60:63], v[160:163], v[176:179], v[60:63]
	v_mfma_i32_16x16x64_i8 v[80:83], v[152:155], v[184:187], v[80:83]
	v_mfma_i32_16x16x64_i8 v[84:87], v[160:163], v[184:187], v[84:87]
	v_mfma_i32_16x16x64_i8 v[104:107], v[152:155], v[192:195], v[104:107]
	v_mfma_i32_16x16x64_i8 v[108:111], v[160:163], v[192:195], v[108:111]
	v_mfma_i32_16x16x64_i8 v[24:27], v[156:159], v[172:175], v[24:27]
	v_mfma_i32_16x16x64_i8 v[28:31], v[164:167], v[172:175], v[28:31]
	v_mfma_i32_16x16x64_i8 v[56:59], v[156:159], v[180:183], v[56:59]
	v_mfma_i32_16x16x64_i8 v[60:63], v[164:167], v[180:183], v[60:63]
	v_mfma_i32_16x16x64_i8 v[80:83], v[156:159], v[188:191], v[80:83]
	v_mfma_i32_16x16x64_i8 v[84:87], v[164:167], v[188:191], v[84:87]
	v_mfma_i32_16x16x64_i8 v[104:107], v[156:159], v[196:199], v[104:107]
	v_mfma_i32_16x16x64_i8 v[108:111], v[164:167], v[196:199], v[108:111]
	s_barrier
	ds_read_b128 v[168:171], v134 offset:49152
	ds_read_b128 v[172:175], v134 offset:50176
	ds_read_b128 v[176:179], v134 offset:51200
	ds_read_b128 v[180:183], v134 offset:52224
	ds_read_b128 v[184:187], v134 offset:53248
	ds_read_b128 v[188:191], v134 offset:54272
	ds_read_b128 v[192:195], v134 offset:55296
	ds_read_b128 v[196:199], v134 offset:56320
	s_add_u32 s4, s56, 0x80
	s_addc_u32 s5, s57, 0
	s_mov_b32 s6, m0
	s_mov_b32 m0, s76
	s_nop 0
	global_load_lds_dwordx4 v130, s[4:5]
	s_mov_b32 m0, s6
	s_nop 0
	s_mov_b32 s6, m0
	s_mov_b32 m0, s77
	s_nop 0
	global_load_lds_dwordx4 v132, s[4:5]
	s_mov_b32 m0, s6
	s_add_u32 s4, s56, 0x40080
	s_addc_u32 s5, s57, 0
	s_mov_b32 s6, m0
	s_mov_b32 m0, s82
	s_nop 0
	global_load_lds_dwordx4 v130, s[4:5]
	s_mov_b32 m0, s6
	s_nop 0
	s_mov_b32 s6, m0
	s_mov_b32 m0, s83
	s_nop 0
	global_load_lds_dwordx4 v132, s[4:5]
	s_mov_b32 m0, s6
	s_mov_b32 s4, m0
	s_mov_b32 m0, s80
	s_nop 0
	global_load_lds_dwordx4 v129, s[50:51]
	s_mov_b32 m0, s4
	s_nop 0
	s_mov_b32 s4, m0
	s_mov_b32 m0, s81
	s_nop 0
	global_load_lds_dwordx4 v131, s[50:51]
	s_mov_b32 m0, s4
	s_waitcnt vmcnt(8)
	s_waitcnt lgkmcnt(0)
	s_barrier
	s_waitcnt lgkmcnt(7)
	v_mfma_i32_16x16x64_i8 v[124:127], v[136:139], v[168:171], v[124:127]
	v_mfma_i32_16x16x64_i8 v[120:123], v[144:147], v[168:171], v[120:123]
	s_waitcnt lgkmcnt(5)
	v_mfma_i32_16x16x64_i8 v[92:95], v[136:139], v[176:179], v[92:95]
	v_mfma_i32_16x16x64_i8 v[88:91], v[144:147], v[176:179], v[88:91]
	s_waitcnt lgkmcnt(3)
	v_mfma_i32_16x16x64_i8 v[44:47], v[136:139], v[184:187], v[44:47]
	v_mfma_i32_16x16x64_i8 v[40:43], v[144:147], v[184:187], v[40:43]
	s_waitcnt lgkmcnt(1)
	v_mfma_i32_16x16x64_i8 v[12:15], v[136:139], v[192:195], v[12:15]
	v_mfma_i32_16x16x64_i8 v[8:11], v[144:147], v[192:195], v[8:11]
	v_mfma_i32_16x16x64_i8 v[124:127], v[140:143], v[172:175], v[124:127]
	v_mfma_i32_16x16x64_i8 v[120:123], v[148:151], v[172:175], v[120:123]
	v_mfma_i32_16x16x64_i8 v[92:95], v[140:143], v[180:183], v[92:95]
	v_mfma_i32_16x16x64_i8 v[88:91], v[148:151], v[180:183], v[88:91]
	v_mfma_i32_16x16x64_i8 v[44:47], v[140:143], v[188:191], v[44:47]
	v_mfma_i32_16x16x64_i8 v[40:43], v[148:151], v[188:191], v[40:43]
	s_waitcnt lgkmcnt(0)
	v_mfma_i32_16x16x64_i8 v[12:15], v[140:143], v[196:199], v[12:15]
	v_mfma_i32_16x16x64_i8 v[8:11], v[148:151], v[196:199], v[8:11]
	v_mfma_i32_16x16x64_i8 v[116:119], v[152:155], v[168:171], v[116:119]
	v_mfma_i32_16x16x64_i8 v[112:115], v[160:163], v[168:171], v[112:115]
	v_mfma_i32_16x16x64_i8 v[68:71], v[152:155], v[176:179], v[68:71]
	v_mfma_i32_16x16x64_i8 v[64:67], v[160:163], v[176:179], v[64:67]
	v_mfma_i32_16x16x64_i8 v[36:39], v[152:155], v[184:187], v[36:39]
	v_mfma_i32_16x16x64_i8 v[32:35], v[160:163], v[184:187], v[32:35]
	v_mfma_i32_16x16x64_i8 v[4:7], v[152:155], v[192:195], v[4:7]
	v_mfma_i32_16x16x64_i8 v[0:3], v[160:163], v[192:195], v[0:3]
	v_mfma_i32_16x16x64_i8 v[116:119], v[156:159], v[172:175], v[116:119]
	v_mfma_i32_16x16x64_i8 v[112:115], v[164:167], v[172:175], v[112:115]
	v_mfma_i32_16x16x64_i8 v[68:71], v[156:159], v[180:183], v[68:71]
	v_mfma_i32_16x16x64_i8 v[64:67], v[164:167], v[180:183], v[64:67]
	v_mfma_i32_16x16x64_i8 v[36:39], v[156:159], v[188:191], v[36:39]
	v_mfma_i32_16x16x64_i8 v[32:35], v[164:167], v[188:191], v[32:35]
	v_mfma_i32_16x16x64_i8 v[4:7], v[156:159], v[196:199], v[4:7]
	v_mfma_i32_16x16x64_i8 v[0:3], v[164:167], v[196:199], v[0:3]
	s_barrier
	s_add_i32 s1, s1, 2
	s_add_u32 s91, s91, 0x100
	s_addc_u32 s92, s92, 0
	s_add_u32 s93, s93, 0x100
	s_addc_u32 s0, s0, 0
	s_add_u32 s44, s44, 0x100
	s_addc_u32 s45, s45, 0
	s_cmp_gt_u32 s1, 13
	.p2align 6

; #define PG8_STAGE(bufoff, gbase, voff) do { _Pragma("unroll") for (int _i = 0; _i < 2; ++_i) glds16_s((gbase), (voff)[_i], ldsb + (unsigned)((bufoff) + _i * 8192)); } while (0)
; #define PG8_LDA(dst, b, h) do { _Pragma("unroll") for (int m = 0; m < 4; ++m) _Pragma("unroll") for (int k = 0; k < 2; ++k) dst[m][k] = *(const LAS h16x8*)(lds + PG8_SA(b, h) + aoff + m * 2048 + k * 1024); } while (0)
; #define PG8_LDB(dst, b, h) do { _Pragma("unroll") for (int n = 0; n < 2; ++n) _Pragma("unroll") for (int k = 0; k < 2; ++k) dst[n][k] = *(const LAS h16x8*)(lds + PG8_SB(b, h) + boff + n * 2048 + k * 1024); } while (0)
; #define PG8_MMA(ai, bj, At, Bt) do { __builtin_amdgcn_s_setprio(1); _Pragma("unroll") for (int m = 0; m < 4; ++m) _Pragma("unroll") for (int n = 0; n < 2; ++n) _Pragma("unroll") for (int k = 0; k < 2; ++k) \
;         acc[ai][bj][m][n] = mma_step<I8>(Bt[n][k], At[m][k], acc[ai][bj][m][n]); __builtin_amdgcn_s_setprio(0); } while (0)
; #define PG8_WAIT_V(n) asm volatile("s_waitcnt vmcnt(" #n ")" ::: "memory")
; #define PG8_WAIT_L(n) asm volatile("s_waitcnt lgkmcnt(" #n ")" ::: "memory")
; #define PG8_BAR __builtin_amdgcn_s_barrier()
; #define PG8_SCHED __builtin_amdgcn_sched_barrier(0)
; template <class Prob, class Epi, bool I8 = false, bool ALIGN_EPI = true, bool SP2 = true>
; __device__ __forceinline__ void gemm_phase(LAS unsigned char* lds, int wave, const Prob& P, const Epi& E) {
;     ...
;             PG8_LDB(B0, 0, 0); PG8_LDB(B1, 0, 1); PG8_SCHED; PG8_LDA(At, 0, 0); PG8_STAGE(PG8_SA(1, 1), a1 + hstepA, voffA);
;             PG8_WAIT_V(8); PG8_WAIT_L(0); PG8_BAR; PG8_MMA(0, 0, At, B0); PG8_MMA(0, 1, At, B1); PG8_BAR; PG8_SCHED;
;             PG8_LDA(At, 0, 1); PG8_STAGE(PG8_SB(0, 0), b2, voffB); PG8_STAGE(PG8_SB(0, 1), b2 + hstepB, voffB); PG8_STAGE(PG8_SA(0, 0), a2, voffA);
;             PG8_WAIT_V(8); PG8_WAIT_L(0); PG8_BAR; PG8_MMA(1, 0, At, B0); PG8_MMA(1, 1, At, B1); PG8_BAR; PG8_SCHED;
;     __device__ __forceinline__ void operator()(Acc& acc, const Unit& u, int wr, int wc, int fr, int fq, LAS unsigned char* lds, int tid) const {
;     ...
;                         for (int n = 0; n < 2; ++n) { const pg8::i32x4 iv = __builtin_bit_cast(pg8::i32x4, acc[ai][bj][m][n]); acc[ai][bj][m][n] = __builtin_convertvector(iv, f32x4) * sa[m]; }
.Lpeel_1065:
	v_add_u32_e32 v124, 0x10000, v210
	v_add_u32_e32 v140, 0x14000, v210
	ds_read_b128 v[104:107], v124
	ds_read_b128 v[112:115], v124 offset:1024
	ds_read_b128 v[120:123], v124 offset:2048
	ds_read_b128 v[124:127], v124 offset:3072
	ds_read_b128 v[128:131], v140
	ds_read_b128 v[132:135], v140 offset:1024
	ds_read_b128 v[136:139], v140 offset:2048
	ds_read_b128 v[140:143], v140 offset:3072
	s_cmp_eq_u32 s4, 12
	s_cselect_b32 s62, s96, vcc_lo
	s_cselect_b32 s63, s51, vcc_hi
	s_cselect_b32 s68, s97, s0
	s_cselect_b32 s69, s49, s1
	s_add_u32 s60, s62, 0x80
	s_addc_u32 s61, s63, 0
	ds_read_b128 v[144:147], v211
	ds_read_b128 v[164:167], v211 offset:1024
	ds_read_b128 v[168:171], v211 offset:2048
	ds_read_b128 v[172:175], v211 offset:3072
	ds_read_b128 v[176:179], v211 offset:4096
	ds_read_b128 v[180:183], v211 offset:5120
	ds_read_b128 v[184:187], v211 offset:6144
	ds_read_b128 v[188:191], v211 offset:7168
	s_mov_b32 s5, m0
	s_mov_b32 m0, s90
	s_nop 0
	global_load_lds_dwordx4 v250, s[44:45]
	s_mov_b32 m0, s5
	s_nop 0
	s_mov_b32 s5, m0
	s_mov_b32 m0, s92
	s_nop 0
	global_load_lds_dwordx4 v247, s[44:45]
	s_mov_b32 m0, s5
	s_waitcnt vmcnt(8)
	s_waitcnt lgkmcnt(0)
	s_barrier
	s_waitcnt lgkmcnt(7)
	v_mfma_i32_16x16x64_i8 v[160:163], v[104:107], v[144:147], 0
	v_mfma_i32_16x16x64_i8 v[152:155], v[120:123], v[144:147], 0
	s_waitcnt lgkmcnt(5)
	v_mfma_i32_16x16x64_i8 v[52:55], v[104:107], v[168:171], 0
	v_mfma_i32_16x16x64_i8 v[80:83], v[120:123], v[168:171], 0
	s_waitcnt lgkmcnt(3)
	v_mfma_i32_16x16x64_i8 v[48:51], v[104:107], v[176:179], 0
	v_mfma_i32_16x16x64_i8 v[72:75], v[120:123], v[176:179], 0
	s_waitcnt lgkmcnt(1)
	v_mfma_i32_16x16x64_i8 v[44:47], v[104:107], v[184:187], 0
	v_mfma_i32_16x16x64_i8 v[68:71], v[120:123], v[184:187], 0
	v_mfma_i32_16x16x64_i8 v[160:163], v[112:115], v[164:167], v[160:163]
	v_mfma_i32_16x16x64_i8 v[152:155], v[124:127], v[164:167], v[152:155]
	v_mfma_i32_16x16x64_i8 v[52:55], v[112:115], v[172:175], v[52:55]
	v_mfma_i32_16x16x64_i8 v[80:83], v[124:127], v[172:175], v[80:83]
	v_mfma_i32_16x16x64_i8 v[48:51], v[112:115], v[180:183], v[48:51]
	v_mfma_i32_16x16x64_i8 v[72:75], v[124:127], v[180:183], v[72:75]
	s_waitcnt lgkmcnt(0)
	v_mfma_i32_16x16x64_i8 v[44:47], v[112:115], v[188:191], v[44:47]
	v_mfma_i32_16x16x64_i8 v[68:71], v[124:127], v[188:191], v[68:71]
	v_mfma_i32_16x16x64_i8 v[116:119], v[128:131], v[144:147], 0
	v_mfma_i32_16x16x64_i8 v[28:31], v[136:139], v[144:147], 0
	v_mfma_i32_16x16x64_i8 v[100:103], v[128:131], v[168:171], 0
	v_mfma_i32_16x16x64_i8 v[24:27], v[136:139], v[168:171], 0
	v_mfma_i32_16x16x64_i8 v[96:99], v[128:131], v[176:179], 0
	v_mfma_i32_16x16x64_i8 v[20:23], v[136:139], v[176:179], 0
	v_mfma_i32_16x16x64_i8 v[92:95], v[128:131], v[184:187], 0
	v_mfma_i32_16x16x64_i8 v[16:19], v[136:139], v[184:187], 0
	v_mfma_i32_16x16x64_i8 v[116:119], v[132:135], v[164:167], v[116:119]
	v_mfma_i32_16x16x64_i8 v[28:31], v[140:143], v[164:167], v[28:31]
	v_mfma_i32_16x16x64_i8 v[100:103], v[132:135], v[172:175], v[100:103]
	v_mfma_i32_16x16x64_i8 v[24:27], v[140:143], v[172:175], v[24:27]
	v_mfma_i32_16x16x64_i8 v[96:99], v[132:135], v[180:183], v[96:99]
	v_mfma_i32_16x16x64_i8 v[20:23], v[140:143], v[180:183], v[20:23]
	v_mfma_i32_16x16x64_i8 v[92:95], v[132:135], v[188:191], v[92:95]
	v_mfma_i32_16x16x64_i8 v[16:19], v[140:143], v[188:191], v[16:19]
	s_barrier
	ds_read_b128 v[144:147], v211 offset:16384
	ds_read_b128 v[164:167], v211 offset:17408
	ds_read_b128 v[168:171], v211 offset:18432
	ds_read_b128 v[172:175], v211 offset:19456
	ds_read_b128 v[176:179], v211 offset:20480
	ds_read_b128 v[180:183], v211 offset:21504
	ds_read_b128 v[184:187], v211 offset:22528
	ds_read_b128 v[188:191], v211 offset:23552
	s_mov_b32 s5, m0
	s_mov_b32 m0, s73
	s_nop 0
	global_load_lds_dwordx4 v217, s[68:69]
	s_mov_b32 m0, s5
	s_add_u32 s6, s68, 0x40000
	s_mov_b32 s5, m0
	s_mov_b32 m0, s74
	s_nop 0
	global_load_lds_dwordx4 v248, s[68:69]
	s_mov_b32 m0, s5
	s_addc_u32 s7, s69, 0
	s_mov_b32 s5, m0
	s_mov_b32 m0, s75
	s_nop 0
	global_load_lds_dwordx4 v217, s[6:7]
	s_mov_b32 m0, s5
	s_nop 0
	s_mov_b32 s5, m0
	s_mov_b32 m0, s80
	s_nop 0
	global_load_lds_dwordx4 v248, s[6:7]
	s_mov_b32 m0, s5
	s_nop 0
	s_mov_b32 s5, m0
	s_mov_b32 m0, s72
	s_nop 0
	global_load_lds_dwordx4 v250, s[62:63]
	s_mov_b32 m0, s5
	s_nop 0
	s_mov_b32 s5, m0
	s_mov_b32 m0, s81
	s_nop 0
	global_load_lds_dwordx4 v247, s[62:63]
	s_mov_b32 m0, s5
	s_waitcnt vmcnt(8)
	s_waitcnt lgkmcnt(0)
	s_barrier
	s_waitcnt lgkmcnt(7)
	v_mfma_i32_16x16x64_i8 v[40:43], v[104:107], v[144:147], 0
	v_mfma_i32_16x16x64_i8 v[64:67], v[120:123], v[144:147], 0
	s_waitcnt lgkmcnt(5)
	v_mfma_i32_16x16x64_i8 v[36:39], v[104:107], v[168:171], 0
	v_mfma_i32_16x16x64_i8 v[60:63], v[120:123], v[168:171], 0
	s_waitcnt lgkmcnt(3)
	v_mfma_i32_16x16x64_i8 v[32:35], v[104:107], v[176:179], 0
	v_mfma_i32_16x16x64_i8 v[56:59], v[120:123], v[176:179], 0
	s_waitcnt lgkmcnt(1)
	v_mfma_i32_16x16x64_i8 v[104:107], v[104:107], v[184:187], 0
	v_mfma_i32_16x16x64_i8 v[40:43], v[112:115], v[164:167], v[40:43]
	v_mfma_i32_16x16x64_i8 v[64:67], v[124:127], v[164:167], v[64:67]
	v_mfma_i32_16x16x64_i8 v[36:39], v[112:115], v[172:175], v[36:39]
	v_mfma_i32_16x16x64_i8 v[60:63], v[124:127], v[172:175], v[60:63]
	v_mfma_i32_16x16x64_i8 v[32:35], v[112:115], v[180:183], v[32:35]
	v_mfma_i32_16x16x64_i8 v[56:59], v[124:127], v[180:183], v[56:59]
	s_waitcnt lgkmcnt(0)
	v_mfma_i32_16x16x64_i8 v[104:107], v[112:115], v[188:191], v[104:107]
	v_mfma_i32_16x16x64_i8 v[112:115], v[120:123], v[184:187], 0
	v_mfma_i32_16x16x64_i8 v[112:115], v[124:127], v[188:191], v[112:115]
	v_mfma_i32_16x16x64_i8 v[88:91], v[128:131], v[144:147], 0
	v_mfma_i32_16x16x64_i8 v[12:15], v[136:139], v[144:147], 0
	v_mfma_i32_16x16x64_i8 v[84:87], v[128:131], v[168:171], 0
	v_mfma_i32_16x16x64_i8 v[8:11], v[136:139], v[168:171], 0
	v_mfma_i32_16x16x64_i8 v[76:79], v[128:131], v[176:179], 0
	v_mfma_i32_16x16x64_i8 v[4:7], v[136:139], v[176:179], 0
	v_mfma_i32_16x16x64_i8 v[108:111], v[128:131], v[184:187], 0
	v_mfma_i32_16x16x64_i8 v[0:3], v[136:139], v[184:187], 0
	v_mfma_i32_16x16x64_i8 v[88:91], v[132:135], v[164:167], v[88:91]
	v_mfma_i32_16x16x64_i8 v[12:15], v[140:143], v[164:167], v[12:15]
	v_mfma_i32_16x16x64_i8 v[84:87], v[132:135], v[172:175], v[84:87]
	v_mfma_i32_16x16x64_i8 v[8:11], v[140:143], v[172:175], v[8:11]
	v_mfma_i32_16x16x64_i8 v[76:79], v[132:135], v[180:183], v[76:79]
	v_mfma_i32_16x16x64_i8 v[4:7], v[140:143], v[180:183], v[4:7]
	v_mfma_i32_16x16x64_i8 v[108:111], v[132:135], v[188:191], v[108:111]
	v_mfma_i32_16x16x64_i8 v[0:3], v[140:143], v[188:191], v[0:3]
	s_barrier
; #define PG8_STAGE(bufoff, gbase, voff) do { _Pragma("unroll") for (int _i = 0; _i < 2; ++_i) glds16_s((gbase), (voff)[_i], ldsb + (unsigned)((bufoff) + _i * 8192)); } while (0)
; #define PG8_LDA(dst, b, h) do { _Pragma("unroll") for (int m = 0; m < 4; ++m) _Pragma("unroll") for (int k = 0; k < 2; ++k) dst[m][k] = *(const LAS h16x8*)(lds + PG8_SA(b, h) + aoff + m * 2048 + k * 1024); } while (0)
; #define PG8_LDB(dst, b, h) do { _Pragma("unroll") for (int n = 0; n < 2; ++n) _Pragma("unroll") for (int k = 0; k < 2; ++k) dst[n][k] = *(const LAS h16x8*)(lds + PG8_SB(b, h) + boff + n * 2048 + k * 1024); } while (0)
; #define PG8_MMA(ai, bj, At, Bt) do { __builtin_amdgcn_s_setprio(1); _Pragma("unroll") for (int m = 0; m < 4; ++m) _Pragma("unroll") for (int n = 0; n < 2; ++n) _Pragma("unroll") for (int k = 0; k < 2; ++k) \
;         acc[ai][bj][m][n] = mma_step<I8>(Bt[n][k], At[m][k], acc[ai][bj][m][n]); __builtin_amdgcn_s_setprio(0); } while (0)
; #define PG8_WAIT_V(n) asm volatile("s_waitcnt vmcnt(" #n ")" ::: "memory")
; #define PG8_WAIT_L(n) asm volatile("s_waitcnt lgkmcnt(" #n ")" ::: "memory")
; #define PG8_BAR __builtin_amdgcn_s_barrier()
; #define PG8_SCHED __builtin_amdgcn_sched_barrier(0)
; template <class Prob, class Epi, bool I8 = false, bool ALIGN_EPI = true, bool SP2 = true>
; __device__ __forceinline__ void gemm_phase(LAS unsigned char* lds, int wave, const Prob& P, const Epi& E) {
;     ...
;         for (int t = 0; t < nt; t += 2) {
;             const bool last = (t == nt - 2);
;             const char* a1 = cA + (size_t)(t + 1) * kstep;
;             const char* a2 = last ? nA : cA + (size_t)(t + 2) * kstep; const char* b2 = last ? nB : cB + (size_t)(t + 2) * kstep;
;             const char* a3 = a2 + kstep; const char* b3 = b2 + kstep;
;     ...
;             PG8_LDB(B0, 1, 0); PG8_LDB(B1, 1, 1); PG8_SCHED; PG8_LDA(At, 1, 0); PG8_STAGE(PG8_SA(0, 1), a2 + hstepA, voffA);
;             PG8_WAIT_V(8); PG8_WAIT_L(0); PG8_BAR; PG8_MMA(0, 0, At, B0); PG8_MMA(0, 1, At, B1); PG8_BAR; PG8_SCHED;
;             PG8_LDA(At, 1, 1); PG8_STAGE(PG8_SB(1, 0), b3, voffB); PG8_STAGE(PG8_SB(1, 1), b3 + hstepB, voffB); PG8_STAGE(PG8_SA(1, 0), a3, voffA);
;             PG8_WAIT_V(8); PG8_WAIT_L(0); PG8_BAR; PG8_MMA(1, 0, At, B0); PG8_MMA(1, 1, At, B1); PG8_BAR; PG8_SCHED;
	v_add_u32_e32 v132, 0x18000, v210
	v_add_u32_e32 v148, 0x1c000, v210
	ds_read_b128 v[120:123], v132
	ds_read_b128 v[124:127], v132 offset:1024
	ds_read_b128 v[128:131], v132 offset:2048
	ds_read_b128 v[132:135], v132 offset:3072
	ds_read_b128 v[136:139], v148
	ds_read_b128 v[140:143], v148 offset:1024
	ds_read_b128 v[144:147], v148 offset:2048
	ds_read_b128 v[164:167], v148 offset:3072
	ds_read_b128 v[148:151], v211 offset:32768
	ds_read_b128 v[156:159], v211 offset:33792
	ds_read_b128 v[168:171], v211 offset:34816
	ds_read_b128 v[172:175], v211 offset:35840
	ds_read_b128 v[176:179], v211 offset:36864
	ds_read_b128 v[180:183], v211 offset:37888
	ds_read_b128 v[184:187], v211 offset:38912
	ds_read_b128 v[188:191], v211 offset:39936
	s_add_u32 s6, s62, 0x2000
	s_addc_u32 s7, s63, 0
	s_mov_b32 s5, m0
	s_mov_b32 m0, s82
	s_nop 0
	global_load_lds_dwordx4 v250, s[6:7]
	s_mov_b32 m0, s5
	s_nop 0
	s_mov_b32 s5, m0
	s_mov_b32 m0, s83
	s_nop 0
	global_load_lds_dwordx4 v247, s[6:7]
	s_mov_b32 m0, s5
	s_waitcnt vmcnt(8)
	s_waitcnt lgkmcnt(0)
	s_barrier
	s_waitcnt lgkmcnt(7)
	v_mfma_i32_16x16x64_i8 v[160:163], v[120:123], v[148:151], v[160:163]
	v_mfma_i32_16x16x64_i8 v[152:155], v[128:131], v[148:151], v[152:155]
	s_waitcnt lgkmcnt(5)
	v_mfma_i32_16x16x64_i8 v[52:55], v[120:123], v[168:171], v[52:55]
	v_mfma_i32_16x16x64_i8 v[80:83], v[128:131], v[168:171], v[80:83]
	s_waitcnt lgkmcnt(3)
	v_mfma_i32_16x16x64_i8 v[48:51], v[120:123], v[176:179], v[48:51]
	v_mfma_i32_16x16x64_i8 v[72:75], v[128:131], v[176:179], v[72:75]
	s_waitcnt lgkmcnt(1)
	v_mfma_i32_16x16x64_i8 v[44:47], v[120:123], v[184:187], v[44:47]
	v_mfma_i32_16x16x64_i8 v[68:71], v[128:131], v[184:187], v[68:71]
	v_mfma_i32_16x16x64_i8 v[160:163], v[124:127], v[156:159], v[160:163]
	v_mfma_i32_16x16x64_i8 v[152:155], v[132:135], v[156:159], v[152:155]
	v_mfma_i32_16x16x64_i8 v[52:55], v[124:127], v[172:175], v[52:55]
	v_mfma_i32_16x16x64_i8 v[80:83], v[132:135], v[172:175], v[80:83]
	v_mfma_i32_16x16x64_i8 v[48:51], v[124:127], v[180:183], v[48:51]
	v_mfma_i32_16x16x64_i8 v[72:75], v[132:135], v[180:183], v[72:75]
	s_waitcnt lgkmcnt(0)
	v_mfma_i32_16x16x64_i8 v[44:47], v[124:127], v[188:191], v[44:47]
	v_mfma_i32_16x16x64_i8 v[68:71], v[132:135], v[188:191], v[68:71]
	v_mfma_i32_16x16x64_i8 v[116:119], v[136:139], v[148:151], v[116:119]
	v_mfma_i32_16x16x64_i8 v[28:31], v[144:147], v[148:151], v[28:31]
	v_mfma_i32_16x16x64_i8 v[100:103], v[136:139], v[168:171], v[100:103]
	v_mfma_i32_16x16x64_i8 v[24:27], v[144:147], v[168:171], v[24:27]
	v_mfma_i32_16x16x64_i8 v[96:99], v[136:139], v[176:179], v[96:99]
	v_mfma_i32_16x16x64_i8 v[20:23], v[144:147], v[176:179], v[20:23]
	v_mfma_i32_16x16x64_i8 v[92:95], v[136:139], v[184:187], v[92:95]
	v_mfma_i32_16x16x64_i8 v[16:19], v[144:147], v[184:187], v[16:19]
	v_mfma_i32_16x16x64_i8 v[116:119], v[140:143], v[156:159], v[116:119]
	v_mfma_i32_16x16x64_i8 v[28:31], v[164:167], v[156:159], v[28:31]
	v_mfma_i32_16x16x64_i8 v[100:103], v[140:143], v[172:175], v[100:103]
	v_mfma_i32_16x16x64_i8 v[24:27], v[164:167], v[172:175], v[24:27]
	v_mfma_i32_16x16x64_i8 v[96:99], v[140:143], v[180:183], v[96:99]
	v_mfma_i32_16x16x64_i8 v[20:23], v[164:167], v[180:183], v[20:23]
	v_mfma_i32_16x16x64_i8 v[92:95], v[140:143], v[188:191], v[92:95]
	v_mfma_i32_16x16x64_i8 v[16:19], v[164:167], v[188:191], v[16:19]
	s_barrier
	ds_read_b128 v[168:171], v211 offset:49152
	ds_read_b128 v[172:175], v211 offset:50176
	ds_read_b128 v[176:179], v211 offset:51200
	ds_read_b128 v[180:183], v211 offset:52224
	ds_read_b128 v[184:187], v211 offset:53248
	ds_read_b128 v[188:191], v211 offset:54272
	ds_read_b128 v[192:195], v211 offset:55296
	ds_read_b128 v[196:199], v211 offset:56320
	s_add_u32 s6, s68, 0x80
	s_addc_u32 s7, s69, 0
	s_mov_b32 s5, m0
	s_mov_b32 m0, s2
	s_nop 0
	global_load_lds_dwordx4 v217, s[6:7]
	s_mov_b32 m0, s5
	s_nop 0
	s_mov_b32 s5, m0
	s_mov_b32 m0, s85
	s_nop 0
	global_load_lds_dwordx4 v248, s[6:7]
	s_mov_b32 m0, s5
	s_add_u32 s6, s68, 0x40080
	s_addc_u32 s7, s69, 0
	s_mov_b32 s5, m0
	s_mov_b32 m0, s88
	s_nop 0
	global_load_lds_dwordx4 v217, s[6:7]
	s_mov_b32 m0, s5
	s_nop 0
	s_mov_b32 s5, m0
	s_mov_b32 m0, s89
	s_nop 0
	global_load_lds_dwordx4 v248, s[6:7]
	s_mov_b32 m0, s5
	s_nop 0
	s_mov_b32 s5, m0
	s_mov_b32 m0, s86
	s_nop 0
	global_load_lds_dwordx4 v250, s[60:61]
	s_mov_b32 m0, s5
	s_nop 0
	s_mov_b32 s5, m0
	s_mov_b32 m0, s87
	s_nop 0
	global_load_lds_dwordx4 v247, s[60:61]
	s_mov_b32 m0, s5
	s_waitcnt vmcnt(8)
	s_waitcnt lgkmcnt(0)
	s_barrier
	s_waitcnt lgkmcnt(1)
	v_mfma_i32_16x16x64_i8 v[104:107], v[120:123], v[192:195], v[104:107]
	v_mfma_i32_16x16x64_i8 v[40:43], v[120:123], v[168:171], v[40:43]
	v_mfma_i32_16x16x64_i8 v[64:67], v[128:131], v[168:171], v[64:67]
	v_mfma_i32_16x16x64_i8 v[36:39], v[120:123], v[176:179], v[36:39]
	v_mfma_i32_16x16x64_i8 v[60:63], v[128:131], v[176:179], v[60:63]
	v_mfma_i32_16x16x64_i8 v[32:35], v[120:123], v[184:187], v[32:35]
	v_mfma_i32_16x16x64_i8 v[56:59], v[128:131], v[184:187], v[56:59]
	s_waitcnt lgkmcnt(0)
	v_mfma_i32_16x16x64_i8 v[156:159], v[124:127], v[196:199], v[104:107]
	v_mfma_i32_16x16x64_i8 v[104:107], v[128:131], v[192:195], v[112:115]
	v_mfma_i32_16x16x64_i8 v[40:43], v[124:127], v[172:175], v[40:43]
	v_mfma_i32_16x16x64_i8 v[64:67], v[132:135], v[172:175], v[64:67]
	v_mfma_i32_16x16x64_i8 v[36:39], v[124:127], v[180:183], v[36:39]
	v_mfma_i32_16x16x64_i8 v[60:63], v[132:135], v[180:183], v[60:63]
	v_mfma_i32_16x16x64_i8 v[32:35], v[124:127], v[188:191], v[32:35]
	v_mfma_i32_16x16x64_i8 v[56:59], v[132:135], v[188:191], v[56:59]
	v_mfma_i32_16x16x64_i8 v[148:151], v[132:135], v[196:199], v[104:107]
	v_mfma_i32_16x16x64_i8 v[88:91], v[136:139], v[168:171], v[88:91]
	v_mfma_i32_16x16x64_i8 v[12:15], v[144:147], v[168:171], v[12:15]
	v_mfma_i32_16x16x64_i8 v[84:87], v[136:139], v[176:179], v[84:87]
	v_mfma_i32_16x16x64_i8 v[8:11], v[144:147], v[176:179], v[8:11]
	v_mfma_i32_16x16x64_i8 v[76:79], v[136:139], v[184:187], v[76:79]
	v_mfma_i32_16x16x64_i8 v[4:7], v[144:147], v[184:187], v[4:7]
	v_mfma_i32_16x16x64_i8 v[104:107], v[136:139], v[192:195], v[108:111]
	v_mfma_i32_16x16x64_i8 v[0:3], v[144:147], v[192:195], v[0:3]
	v_mfma_i32_16x16x64_i8 v[88:91], v[140:143], v[172:175], v[88:91]
	v_mfma_i32_16x16x64_i8 v[12:15], v[164:167], v[172:175], v[12:15]
	v_mfma_i32_16x16x64_i8 v[84:87], v[140:143], v[180:183], v[84:87]
	v_mfma_i32_16x16x64_i8 v[8:11], v[164:167], v[180:183], v[8:11]
	v_mfma_i32_16x16x64_i8 v[76:79], v[140:143], v[188:191], v[76:79]
	v_mfma_i32_16x16x64_i8 v[4:7], v[164:167], v[188:191], v[4:7]
	v_mfma_i32_16x16x64_i8 v[108:111], v[140:143], v[196:199], v[104:107]
	v_mfma_i32_16x16x64_i8 v[0:3], v[164:167], v[196:199], v[0:3]
	s_barrier
	s_add_i32 s4, s4, 2
	s_add_u32 vcc_lo, vcc_lo, 0x100
	s_addc_u32 vcc_hi, vcc_hi, 0
	s_add_u32 s0, s0, 0x100
	s_addc_u32 s1, s1, 0
	s_add_u32 s44, s44, 0x100
	s_addc_u32 s45, s45, 0
	s_cmp_gt_u32 s4, 13
	.p2align 6

; #define PG8_STAGE(bufoff, gbase, voff) do { _Pragma("unroll") for (int _i = 0; _i < 2; ++_i) glds16_s((gbase), (voff)[_i], ldsb + (unsigned)((bufoff) + _i * 8192)); } while (0)
; #define PG8_LDA(dst, b, h) do { _Pragma("unroll") for (int m = 0; m < 4; ++m) _Pragma("unroll") for (int k = 0; k < 2; ++k) dst[m][k] = *(const LAS h16x8*)(lds + PG8_SA(b, h) + aoff + m * 2048 + k * 1024); } while (0)
; #define PG8_LDB(dst, b, h) do { _Pragma("unroll") for (int n = 0; n < 2; ++n) _Pragma("unroll") for (int k = 0; k < 2; ++k) dst[n][k] = *(const LAS h16x8*)(lds + PG8_SB(b, h) + boff + n * 2048 + k * 1024); } while (0)
; #define PG8_MMA(ai, bj, At, Bt) do { __builtin_amdgcn_s_setprio(1); _Pragma("unroll") for (int m = 0; m < 4; ++m) _Pragma("unroll") for (int n = 0; n < 2; ++n) _Pragma("unroll") for (int k = 0; k < 2; ++k) \
;         acc[ai][bj][m][n] = mma_step<I8>(Bt[n][k], At[m][k], acc[ai][bj][m][n]); __builtin_amdgcn_s_setprio(0); } while (0)
; #define PG8_WAIT_V(n) asm volatile("s_waitcnt vmcnt(" #n ")" ::: "memory")
; #define PG8_WAIT_L(n) asm volatile("s_waitcnt lgkmcnt(" #n ")" ::: "memory")
; #define PG8_BAR __builtin_amdgcn_s_barrier()
; #define PG8_SCHED __builtin_amdgcn_sched_barrier(0)
; template <bool I8> __device__ __forceinline__ f32x4 mma_step(const h16x8& b, const h16x8& a, const f32x4& c) {
;     if constexpr (I8) return __builtin_bit_cast(f32x4, __builtin_amdgcn_mfma_i32_16x16x64_i8(__builtin_bit_cast(i32x4, b), __builtin_bit_cast(i32x4, a), __builtin_bit_cast(i32x4, c), 0, 0, 0));
;     else return __builtin_amdgcn_mfma_f32_16x16x32_f16(b, a, c, 0, 0, 0);
; template <class Prob, class Epi, bool I8 = false, bool ALIGN_EPI = true, bool SP2 = true>
; __device__ __forceinline__ void gemm_phase(LAS unsigned char* lds, int wave, const Prob& P, const Epi& E) {
;     ...
;             PG8_LDB(B0, 0, 0); PG8_LDB(B1, 0, 1); PG8_SCHED; PG8_LDA(At, 0, 0); PG8_STAGE(PG8_SA(1, 1), a1 + hstepA, voffA);
;             PG8_WAIT_V(8); PG8_WAIT_L(0); PG8_BAR; PG8_MMA(0, 0, At, B0); PG8_MMA(0, 1, At, B1); PG8_BAR; PG8_SCHED;
;             PG8_LDA(At, 0, 1); PG8_STAGE(PG8_SB(0, 0), b2, voffB); PG8_STAGE(PG8_SB(0, 1), b2 + hstepB, voffB); PG8_STAGE(PG8_SA(0, 0), a2, voffA);
;             PG8_WAIT_V(8); PG8_WAIT_L(0); PG8_BAR; PG8_MMA(1, 0, At, B0); PG8_MMA(1, 1, At, B1); PG8_BAR; PG8_SCHED;
.Lpeel_1216:
	v_add_u32_e32 v140, 0x10000, v179
	v_add_u32_e32 v156, 0x14000, v179
	ds_read_b128 v[100:103], v140
	ds_read_b128 v[108:111], v140 offset:1024
	ds_read_b128 v[136:139], v140 offset:2048
	ds_read_b128 v[140:143], v140 offset:3072
	ds_read_b128 v[144:147], v156
	ds_read_b128 v[148:151], v156 offset:1024
	ds_read_b128 v[152:155], v156 offset:2048
	ds_read_b128 v[156:159], v156 offset:3072
	s_cmp_eq_u32 s4, 40
	s_cselect_b32 s60, s38, s74
	s_cselect_b32 s61, s39, s75
	s_cselect_b32 s56, s50, s0
	s_cselect_b32 s57, s51, s1
	s_add_u32 s44, s60, 0x80
	s_addc_u32 s45, s61, 0
	ds_read_b128 v[164:167], v185
	ds_read_b128 v[168:171], v185 offset:1024
	ds_read_b128 v[172:175], v185 offset:2048
	ds_read_b128 v[180:183], v185 offset:3072
	ds_read_b128 v[186:189], v185 offset:4096
	ds_read_b128 v[190:193], v185 offset:5120
	ds_read_b128 v[194:197], v185 offset:6144
	ds_read_b128 v[198:201], v185 offset:7168
	s_mov_b32 s5, m0
	s_mov_b32 m0, s86
	s_nop 0
	global_load_lds_dwordx4 v160, s[14:15]
	s_mov_b32 m0, s5
	s_nop 0
	s_mov_b32 s5, m0
	s_mov_b32 m0, s87
	s_nop 0
	global_load_lds_dwordx4 v162, s[14:15]
	s_mov_b32 m0, s5
	s_waitcnt vmcnt(8)
	s_waitcnt lgkmcnt(0)
	s_barrier
	s_waitcnt lgkmcnt(7)
	v_mfma_i32_16x16x64_i8 v[132:135], v[100:103], v[164:167], 0
	v_mfma_i32_16x16x64_i8 v[128:131], v[136:139], v[164:167], 0
	s_waitcnt lgkmcnt(5)
	v_mfma_i32_16x16x64_i8 v[124:127], v[100:103], v[172:175], 0
	v_mfma_i32_16x16x64_i8 v[120:123], v[136:139], v[172:175], 0
	s_waitcnt lgkmcnt(3)
	v_mfma_i32_16x16x64_i8 v[116:119], v[100:103], v[186:189], 0
	v_mfma_i32_16x16x64_i8 v[112:115], v[136:139], v[186:189], 0
	s_waitcnt lgkmcnt(1)
	v_mfma_i32_16x16x64_i8 v[104:107], v[100:103], v[194:197], 0
	v_mfma_i32_16x16x64_i8 v[96:99], v[136:139], v[194:197], 0
	v_mfma_i32_16x16x64_i8 v[132:135], v[108:111], v[168:171], v[132:135]
	v_mfma_i32_16x16x64_i8 v[128:131], v[140:143], v[168:171], v[128:131]
	v_mfma_i32_16x16x64_i8 v[124:127], v[108:111], v[180:183], v[124:127]
	v_mfma_i32_16x16x64_i8 v[120:123], v[140:143], v[180:183], v[120:123]
	v_mfma_i32_16x16x64_i8 v[116:119], v[108:111], v[190:193], v[116:119]
	v_mfma_i32_16x16x64_i8 v[112:115], v[140:143], v[190:193], v[112:115]
	s_waitcnt lgkmcnt(0)
	v_mfma_i32_16x16x64_i8 v[104:107], v[108:111], v[198:201], v[104:107]
	v_mfma_i32_16x16x64_i8 v[96:99], v[140:143], v[198:201], v[96:99]
	v_mfma_i32_16x16x64_i8 v[60:63], v[144:147], v[164:167], 0
	v_mfma_i32_16x16x64_i8 v[56:59], v[152:155], v[164:167], 0
	v_mfma_i32_16x16x64_i8 v[52:55], v[144:147], v[172:175], 0
	v_mfma_i32_16x16x64_i8 v[48:51], v[152:155], v[172:175], 0
	v_mfma_i32_16x16x64_i8 v[44:47], v[144:147], v[186:189], 0
	v_mfma_i32_16x16x64_i8 v[40:43], v[152:155], v[186:189], 0
	v_mfma_i32_16x16x64_i8 v[36:39], v[144:147], v[194:197], 0
	v_mfma_i32_16x16x64_i8 v[32:35], v[152:155], v[194:197], 0
	v_mfma_i32_16x16x64_i8 v[60:63], v[148:151], v[168:171], v[60:63]
	v_mfma_i32_16x16x64_i8 v[56:59], v[156:159], v[168:171], v[56:59]
	v_mfma_i32_16x16x64_i8 v[52:55], v[148:151], v[180:183], v[52:55]
	v_mfma_i32_16x16x64_i8 v[48:51], v[156:159], v[180:183], v[48:51]
	v_mfma_i32_16x16x64_i8 v[44:47], v[148:151], v[190:193], v[44:47]
	v_mfma_i32_16x16x64_i8 v[40:43], v[156:159], v[190:193], v[40:43]
	v_mfma_i32_16x16x64_i8 v[36:39], v[148:151], v[198:201], v[36:39]
	v_mfma_i32_16x16x64_i8 v[32:35], v[156:159], v[198:201], v[32:35]
	s_barrier
	ds_read_b128 v[164:167], v185 offset:16384
	ds_read_b128 v[168:171], v185 offset:17408
	ds_read_b128 v[172:175], v185 offset:18432
	ds_read_b128 v[180:183], v185 offset:19456
	ds_read_b128 v[186:189], v185 offset:20480
	ds_read_b128 v[190:193], v185 offset:21504
	ds_read_b128 v[194:197], v185 offset:22528
	ds_read_b128 v[198:201], v185 offset:23552
	s_mov_b32 s5, m0
	s_mov_b32 m0, s41
	s_nop 0
	global_load_lds_dwordx4 v161, s[56:57]
	s_mov_b32 m0, s5
	s_add_u32 s6, s56, 0xb0000
	s_mov_b32 s5, m0
	s_mov_b32 m0, s62
	s_nop 0
	global_load_lds_dwordx4 v163, s[56:57]
	s_mov_b32 m0, s5
	s_addc_u32 s7, s57, 0
	s_mov_b32 s5, m0
	s_mov_b32 m0, s63
	s_nop 0
	global_load_lds_dwordx4 v161, s[6:7]
	s_mov_b32 m0, s5
	s_nop 0
	s_mov_b32 s5, m0
	s_mov_b32 m0, s64
	s_nop 0
	global_load_lds_dwordx4 v163, s[6:7]
	s_mov_b32 m0, s5
	s_nop 0
	s_mov_b32 s5, m0
	s_mov_b32 m0, s40
	s_nop 0
	global_load_lds_dwordx4 v160, s[60:61]
	s_mov_b32 m0, s5
	s_nop 0
	s_mov_b32 s5, m0
	s_mov_b32 m0, s68
	s_nop 0
	global_load_lds_dwordx4 v162, s[60:61]
	s_mov_b32 m0, s5
	s_waitcnt vmcnt(8)
	s_waitcnt lgkmcnt(0)
	s_barrier
	s_waitcnt lgkmcnt(7)
	v_mfma_i32_16x16x64_i8 v[92:95], v[100:103], v[164:167], 0
	v_mfma_i32_16x16x64_i8 v[88:91], v[136:139], v[164:167], 0
	s_waitcnt lgkmcnt(5)
	v_mfma_i32_16x16x64_i8 v[84:87], v[100:103], v[172:175], 0
	v_mfma_i32_16x16x64_i8 v[80:83], v[136:139], v[172:175], 0
	s_waitcnt lgkmcnt(3)
	v_mfma_i32_16x16x64_i8 v[76:79], v[100:103], v[186:189], 0
	v_mfma_i32_16x16x64_i8 v[72:75], v[136:139], v[186:189], 0
	s_waitcnt lgkmcnt(1)
	v_mfma_i32_16x16x64_i8 v[68:71], v[100:103], v[194:197], 0
	v_mfma_i32_16x16x64_i8 v[64:67], v[136:139], v[194:197], 0
	v_mfma_i32_16x16x64_i8 v[92:95], v[108:111], v[168:171], v[92:95]
	v_mfma_i32_16x16x64_i8 v[88:91], v[140:143], v[168:171], v[88:91]
	v_mfma_i32_16x16x64_i8 v[84:87], v[108:111], v[180:183], v[84:87]
	v_mfma_i32_16x16x64_i8 v[80:83], v[140:143], v[180:183], v[80:83]
	v_mfma_i32_16x16x64_i8 v[76:79], v[108:111], v[190:193], v[76:79]
	v_mfma_i32_16x16x64_i8 v[72:75], v[140:143], v[190:193], v[72:75]
	s_waitcnt lgkmcnt(0)
	v_mfma_i32_16x16x64_i8 v[68:71], v[108:111], v[198:201], v[68:71]
	v_mfma_i32_16x16x64_i8 v[64:67], v[140:143], v[198:201], v[64:67]
	v_mfma_i32_16x16x64_i8 v[28:31], v[144:147], v[164:167], 0
	v_mfma_i32_16x16x64_i8 v[24:27], v[152:155], v[164:167], 0
	v_mfma_i32_16x16x64_i8 v[20:23], v[144:147], v[172:175], 0
	v_mfma_i32_16x16x64_i8 v[16:19], v[152:155], v[172:175], 0
	v_mfma_i32_16x16x64_i8 v[12:15], v[144:147], v[186:189], 0
	v_mfma_i32_16x16x64_i8 v[8:11], v[152:155], v[186:189], 0
	v_mfma_i32_16x16x64_i8 v[4:7], v[144:147], v[194:197], 0
	v_mfma_i32_16x16x64_i8 v[0:3], v[152:155], v[194:197], 0
	v_mfma_i32_16x16x64_i8 v[28:31], v[148:151], v[168:171], v[28:31]
	v_mfma_i32_16x16x64_i8 v[24:27], v[156:159], v[168:171], v[24:27]
	v_mfma_i32_16x16x64_i8 v[20:23], v[148:151], v[180:183], v[20:23]
	v_mfma_i32_16x16x64_i8 v[16:19], v[156:159], v[180:183], v[16:19]
	v_mfma_i32_16x16x64_i8 v[12:15], v[148:151], v[190:193], v[12:15]
	v_mfma_i32_16x16x64_i8 v[8:11], v[156:159], v[190:193], v[8:11]
	v_mfma_i32_16x16x64_i8 v[4:7], v[148:151], v[198:201], v[4:7]
	v_mfma_i32_16x16x64_i8 v[0:3], v[156:159], v[198:201], v[0:3]
	s_barrier
; #define PG8_STAGE(bufoff, gbase, voff) do { _Pragma("unroll") for (int _i = 0; _i < 2; ++_i) glds16_s((gbase), (voff)[_i], ldsb + (unsigned)((bufoff) + _i * 8192)); } while (0)
; #define PG8_LDA(dst, b, h) do { _Pragma("unroll") for (int m = 0; m < 4; ++m) _Pragma("unroll") for (int k = 0; k < 2; ++k) dst[m][k] = *(const LAS h16x8*)(lds + PG8_SA(b, h) + aoff + m * 2048 + k * 1024); } while (0)
; #define PG8_LDB(dst, b, h) do { _Pragma("unroll") for (int n = 0; n < 2; ++n) _Pragma("unroll") for (int k = 0; k < 2; ++k) dst[n][k] = *(const LAS h16x8*)(lds + PG8_SB(b, h) + boff + n * 2048 + k * 1024); } while (0)
; #define PG8_MMA(ai, bj, At, Bt) do { __builtin_amdgcn_s_setprio(1); _Pragma("unroll") for (int m = 0; m < 4; ++m) _Pragma("unroll") for (int n = 0; n < 2; ++n) _Pragma("unroll") for (int k = 0; k < 2; ++k) \
;         acc[ai][bj][m][n] = mma_step<I8>(Bt[n][k], At[m][k], acc[ai][bj][m][n]); __builtin_amdgcn_s_setprio(0); } while (0)
; #define PG8_WAIT_V(n) asm volatile("s_waitcnt vmcnt(" #n ")" ::: "memory")
; #define PG8_WAIT_L(n) asm volatile("s_waitcnt lgkmcnt(" #n ")" ::: "memory")
; #define PG8_BAR __builtin_amdgcn_s_barrier()
; #define PG8_SCHED __builtin_amdgcn_sched_barrier(0)
; template <class Prob, class Epi, bool I8 = false, bool ALIGN_EPI = true, bool SP2 = true>
; __device__ __forceinline__ void gemm_phase(LAS unsigned char* lds, int wave, const Prob& P, const Epi& E) {
;     ...
;         for (int t = 0; t < nt; t += 2) {
;             const bool last = (t == nt - 2);
;             const char* a1 = cA + (size_t)(t + 1) * kstep;
;             const char* a2 = last ? nA : cA + (size_t)(t + 2) * kstep; const char* b2 = last ? nB : cB + (size_t)(t + 2) * kstep;
;             const char* a3 = a2 + kstep; const char* b3 = b2 + kstep;
;     ...
;             PG8_LDB(B0, 1, 0); PG8_LDB(B1, 1, 1); PG8_SCHED; PG8_LDA(At, 1, 0); PG8_STAGE(PG8_SA(0, 1), a2 + hstepA, voffA);
;             PG8_WAIT_V(8); PG8_WAIT_L(0); PG8_BAR; PG8_MMA(0, 0, At, B0); PG8_MMA(0, 1, At, B1); PG8_BAR; PG8_SCHED;
;             PG8_LDA(At, 1, 1); PG8_STAGE(PG8_SB(1, 0), b3, voffB); PG8_STAGE(PG8_SB(1, 1), b3 + hstepB, voffB); PG8_STAGE(PG8_SA(1, 0), a3, voffA);
;             PG8_WAIT_V(8); PG8_WAIT_L(0); PG8_BAR; PG8_MMA(1, 0, At, B0); PG8_MMA(1, 1, At, B1); PG8_BAR; PG8_SCHED;
	v_add_u32_e32 v140, 0x18000, v179
	v_add_u32_e32 v156, 0x1c000, v179
	ds_read_b128 v[100:103], v140
	ds_read_b128 v[108:111], v140 offset:1024
	ds_read_b128 v[136:139], v140 offset:2048
	ds_read_b128 v[140:143], v140 offset:3072
	ds_read_b128 v[144:147], v156
	ds_read_b128 v[148:151], v156 offset:1024
	ds_read_b128 v[152:155], v156 offset:2048
	ds_read_b128 v[156:159], v156 offset:3072
	ds_read_b128 v[164:167], v185 offset:32768
	ds_read_b128 v[168:171], v185 offset:33792
	ds_read_b128 v[172:175], v185 offset:34816
	ds_read_b128 v[180:183], v185 offset:35840
	ds_read_b128 v[186:189], v185 offset:36864
	ds_read_b128 v[190:193], v185 offset:37888
	ds_read_b128 v[194:197], v185 offset:38912
	ds_read_b128 v[198:201], v185 offset:39936
	s_add_u32 s6, s60, 0xb0000
	s_addc_u32 s7, s61, 0
	s_mov_b32 s5, m0
	s_mov_b32 m0, s69
	s_nop 0
	global_load_lds_dwordx4 v160, s[6:7]
	s_mov_b32 m0, s5
	s_nop 0
	s_mov_b32 s5, m0
	s_mov_b32 m0, s76
	s_nop 0
	global_load_lds_dwordx4 v162, s[6:7]
	s_mov_b32 m0, s5
	s_waitcnt vmcnt(8)
	s_waitcnt lgkmcnt(0)
	s_barrier
	s_waitcnt lgkmcnt(7)
	v_mfma_i32_16x16x64_i8 v[132:135], v[100:103], v[164:167], v[132:135]
	v_mfma_i32_16x16x64_i8 v[128:131], v[136:139], v[164:167], v[128:131]
	s_waitcnt lgkmcnt(5)
	v_mfma_i32_16x16x64_i8 v[124:127], v[100:103], v[172:175], v[124:127]
	v_mfma_i32_16x16x64_i8 v[120:123], v[136:139], v[172:175], v[120:123]
	s_waitcnt lgkmcnt(3)
	v_mfma_i32_16x16x64_i8 v[116:119], v[100:103], v[186:189], v[116:119]
	v_mfma_i32_16x16x64_i8 v[112:115], v[136:139], v[186:189], v[112:115]
	s_waitcnt lgkmcnt(1)
	v_mfma_i32_16x16x64_i8 v[104:107], v[100:103], v[194:197], v[104:107]
	v_mfma_i32_16x16x64_i8 v[96:99], v[136:139], v[194:197], v[96:99]
	v_mfma_i32_16x16x64_i8 v[132:135], v[108:111], v[168:171], v[132:135]
	v_mfma_i32_16x16x64_i8 v[128:131], v[140:143], v[168:171], v[128:131]
	v_mfma_i32_16x16x64_i8 v[124:127], v[108:111], v[180:183], v[124:127]
	v_mfma_i32_16x16x64_i8 v[120:123], v[140:143], v[180:183], v[120:123]
	v_mfma_i32_16x16x64_i8 v[116:119], v[108:111], v[190:193], v[116:119]
	v_mfma_i32_16x16x64_i8 v[112:115], v[140:143], v[190:193], v[112:115]
	s_waitcnt lgkmcnt(0)
	v_mfma_i32_16x16x64_i8 v[104:107], v[108:111], v[198:201], v[104:107]
	v_mfma_i32_16x16x64_i8 v[96:99], v[140:143], v[198:201], v[96:99]
	v_mfma_i32_16x16x64_i8 v[60:63], v[144:147], v[164:167], v[60:63]
	v_mfma_i32_16x16x64_i8 v[56:59], v[152:155], v[164:167], v[56:59]
	v_mfma_i32_16x16x64_i8 v[52:55], v[144:147], v[172:175], v[52:55]
	v_mfma_i32_16x16x64_i8 v[48:51], v[152:155], v[172:175], v[48:51]
	v_mfma_i32_16x16x64_i8 v[44:47], v[144:147], v[186:189], v[44:47]
	v_mfma_i32_16x16x64_i8 v[40:43], v[152:155], v[186:189], v[40:43]
	v_mfma_i32_16x16x64_i8 v[36:39], v[144:147], v[194:197], v[36:39]
	v_mfma_i32_16x16x64_i8 v[32:35], v[152:155], v[194:197], v[32:35]
	v_mfma_i32_16x16x64_i8 v[60:63], v[148:151], v[168:171], v[60:63]
	v_mfma_i32_16x16x64_i8 v[56:59], v[156:159], v[168:171], v[56:59]
	v_mfma_i32_16x16x64_i8 v[52:55], v[148:151], v[180:183], v[52:55]
	v_mfma_i32_16x16x64_i8 v[48:51], v[156:159], v[180:183], v[48:51]
	v_mfma_i32_16x16x64_i8 v[44:47], v[148:151], v[190:193], v[44:47]
	v_mfma_i32_16x16x64_i8 v[40:43], v[156:159], v[190:193], v[40:43]
	v_mfma_i32_16x16x64_i8 v[36:39], v[148:151], v[198:201], v[36:39]
	v_mfma_i32_16x16x64_i8 v[32:35], v[156:159], v[198:201], v[32:35]
	s_barrier
	ds_read_b128 v[164:167], v185 offset:49152
	ds_read_b128 v[168:171], v185 offset:50176
	ds_read_b128 v[172:175], v185 offset:51200
	ds_read_b128 v[180:183], v185 offset:52224
	ds_read_b128 v[186:189], v185 offset:53248
	ds_read_b128 v[190:193], v185 offset:54272
	ds_read_b128 v[194:197], v185 offset:55296
	ds_read_b128 v[198:201], v185 offset:56320
	s_add_u32 s6, s56, 0x80
	s_addc_u32 s7, s57, 0
	s_mov_b32 s5, m0
	s_mov_b32 m0, s80
	s_nop 0
	global_load_lds_dwordx4 v161, s[6:7]
	s_mov_b32 m0, s5
	s_nop 0
	s_mov_b32 s5, m0
	s_mov_b32 m0, s81
	s_nop 0
	global_load_lds_dwordx4 v163, s[6:7]
	s_mov_b32 m0, s5
	s_add_u32 s6, s56, 0xb0080
	s_addc_u32 s7, s57, 0
	s_mov_b32 s5, m0
	s_mov_b32 m0, s84
	s_nop 0
	global_load_lds_dwordx4 v161, s[6:7]
	s_mov_b32 m0, s5
	s_nop 0
	s_mov_b32 s5, m0
	s_mov_b32 m0, s85
	s_nop 0
	global_load_lds_dwordx4 v163, s[6:7]
	s_mov_b32 m0, s5
	s_nop 0
	s_mov_b32 s5, m0
	s_mov_b32 m0, s82
	s_nop 0
	global_load_lds_dwordx4 v160, s[44:45]
	s_mov_b32 m0, s5
	s_nop 0
	s_mov_b32 s5, m0
	s_mov_b32 m0, s83
	s_nop 0
	global_load_lds_dwordx4 v162, s[44:45]
	s_mov_b32 m0, s5
	s_waitcnt vmcnt(8)
	s_waitcnt lgkmcnt(0)
	s_barrier
	s_waitcnt lgkmcnt(7)
	v_mfma_i32_16x16x64_i8 v[92:95], v[100:103], v[164:167], v[92:95]
	v_mfma_i32_16x16x64_i8 v[88:91], v[136:139], v[164:167], v[88:91]
	s_waitcnt lgkmcnt(5)
	v_mfma_i32_16x16x64_i8 v[84:87], v[100:103], v[172:175], v[84:87]
	v_mfma_i32_16x16x64_i8 v[80:83], v[136:139], v[172:175], v[80:83]
	s_waitcnt lgkmcnt(3)
	v_mfma_i32_16x16x64_i8 v[76:79], v[100:103], v[186:189], v[76:79]
	v_mfma_i32_16x16x64_i8 v[72:75], v[136:139], v[186:189], v[72:75]
	s_waitcnt lgkmcnt(1)
	v_mfma_i32_16x16x64_i8 v[68:71], v[100:103], v[194:197], v[68:71]
	v_mfma_i32_16x16x64_i8 v[64:67], v[136:139], v[194:197], v[64:67]
	v_mfma_i32_16x16x64_i8 v[92:95], v[108:111], v[168:171], v[92:95]
	v_mfma_i32_16x16x64_i8 v[88:91], v[140:143], v[168:171], v[88:91]
	v_mfma_i32_16x16x64_i8 v[84:87], v[108:111], v[180:183], v[84:87]
	v_mfma_i32_16x16x64_i8 v[80:83], v[140:143], v[180:183], v[80:83]
	v_mfma_i32_16x16x64_i8 v[76:79], v[108:111], v[190:193], v[76:79]
	v_mfma_i32_16x16x64_i8 v[72:75], v[140:143], v[190:193], v[72:75]
	s_waitcnt lgkmcnt(0)
	v_mfma_i32_16x16x64_i8 v[68:71], v[108:111], v[198:201], v[68:71]
	v_mfma_i32_16x16x64_i8 v[64:67], v[140:143], v[198:201], v[64:67]
	v_mfma_i32_16x16x64_i8 v[28:31], v[144:147], v[164:167], v[28:31]
	v_mfma_i32_16x16x64_i8 v[24:27], v[152:155], v[164:167], v[24:27]
	v_mfma_i32_16x16x64_i8 v[20:23], v[144:147], v[172:175], v[20:23]
	v_mfma_i32_16x16x64_i8 v[16:19], v[152:155], v[172:175], v[16:19]
	v_mfma_i32_16x16x64_i8 v[12:15], v[144:147], v[186:189], v[12:15]
	v_mfma_i32_16x16x64_i8 v[8:11], v[152:155], v[186:189], v[8:11]
	v_mfma_i32_16x16x64_i8 v[4:7], v[144:147], v[194:197], v[4:7]
	v_mfma_i32_16x16x64_i8 v[0:3], v[152:155], v[194:197], v[0:3]
	v_mfma_i32_16x16x64_i8 v[28:31], v[148:151], v[168:171], v[28:31]
	v_mfma_i32_16x16x64_i8 v[24:27], v[156:159], v[168:171], v[24:27]
	v_mfma_i32_16x16x64_i8 v[20:23], v[148:151], v[180:183], v[20:23]
	v_mfma_i32_16x16x64_i8 v[16:19], v[156:159], v[180:183], v[16:19]
	v_mfma_i32_16x16x64_i8 v[12:15], v[148:151], v[190:193], v[12:15]
	v_mfma_i32_16x16x64_i8 v[8:11], v[156:159], v[190:193], v[8:11]
	v_mfma_i32_16x16x64_i8 v[4:7], v[148:151], v[198:201], v[4:7]
	v_mfma_i32_16x16x64_i8 v[0:3], v[156:159], v[198:201], v[0:3]
	s_barrier
	s_add_i32 s4, s4, 2
	s_add_u32 s74, s74, 0x100
	s_addc_u32 s75, s75, 0
	s_add_u32 s0, s0, 0x100
	s_addc_u32 s1, s1, 0
	s_add_u32 s14, s14, 0x100
	s_addc_u32 s15, s15, 0
	s_cmp_gt_u32 s4, 41
	.p2align 6
